# GEMM K-loops: barrier moved into middle of k-step 3, next K-tile first fragment reads hoisted behind it
# speedup vs baseline: 1.0028x; 1.0028x over previous
.LBB0_86:
	v_add_u32_e32 v0, v178, v179
	ds_read_b128 v[202:205], v0
	ds_read_b128 v[210:213], v0 offset:4608
	v_add_u32_e32 v0, v178, v180
	ds_read_b128 v[164:167], v0 offset:36864
	ds_read_b128 v[168:171], v0 offset:41472
	ds_read_b128 v[174:177], v0 offset:46080
	ds_read_b128 v[194:197], v0 offset:50688
	ds_read_b128 v[214:217], v184 offset:32
	ds_read_b128 v[218:221], v184 offset:4640
.Lkloop_top_0:
	s_add_i32 s35, s34, -3
	s_cmp_lt_u32 s35, 14
	s_cselect_b64 s[36:37], -1, 0
	s_and_b64 s[26:27], s[36:37], exec
	s_cselect_b32 s27, s11, s33
	s_cselect_b32 s26, s10, s31
	s_cselect_b32 s39, s9, s30
	s_cselect_b32 s38, s8, s29
	s_add_i32 s47, s34, -1
	s_waitcnt lgkmcnt(5)
	v_mfma_f32_32x32x16_bf16 v[114:129], v[164:167], v[202:205], v[114:129]
	v_mfma_f32_32x32x16_bf16 v[82:97], v[164:167], v[210:213], v[82:97]
	s_waitcnt lgkmcnt(4)
	v_mfma_f32_32x32x16_bf16 v[98:113], v[168:171], v[202:205], v[98:113]
	v_mfma_f32_32x32x16_bf16 v[66:81], v[168:171], v[210:213], v[66:81]
	s_waitcnt lgkmcnt(3)
	v_mfma_f32_32x32x16_bf16 v[50:65], v[174:177], v[202:205], v[50:65]
	s_and_b64 s[36:37], s[36:37], exec
	s_cselect_b32 s36, s47, s5
	v_mfma_f32_32x32x16_bf16 v[18:33], v[174:177], v[210:213], v[18:33]
	s_waitcnt lgkmcnt(2)
	v_mfma_f32_32x32x16_bf16 v[34:49], v[194:197], v[202:205], v[34:49]
	ds_read_b128 v[164:167], v185 offset:36896
	ds_read_b128 v[174:177], v185 offset:41504
	v_mfma_f32_32x32x16_bf16 v[2:17], v[194:197], v[210:213], v[2:17]
	s_lshl_b32 s96, s36, 7
	v_lshl_add_u64 v[168:169], s[38:39], 0, v[162:163]
	v_lshl_add_u64 v[168:169], v[168:169], 0, s[96:97]
	s_waitcnt vmcnt(6)
	ds_write_b128 v186, v[142:145] offset:9216
	v_add_co_u32_e32 v142, vcc, s91, v168
	ds_write_b128 v186, v[134:137]
	s_nop 0
	v_addc_co_u32_e32 v143, vcc, 0, v169, vcc
	global_load_dwordx4 v[134:137], v[168:169], off
	s_nop 0
	global_load_dwordx4 v[142:145], v[142:143], off
	s_waitcnt vmcnt(7)
	ds_write_b128 v186, v[130:133] offset:18432
	v_add_co_u32_e32 v130, vcc, s1, v168
	s_waitcnt vmcnt(6)
	ds_write_b128 v186, v[150:153] offset:27648
	v_addc_co_u32_e32 v131, vcc, 0, v169, vcc
	v_add_co_u32_e32 v150, vcc, s76, v168
	global_load_dwordx4 v[130:133], v[130:131], off
	s_nop 0
	v_addc_co_u32_e32 v151, vcc, 0, v169, vcc
	global_load_dwordx4 v[150:153], v[150:151], off
	ds_read_b128 v[168:171], v185 offset:46112
	ds_read_b128 v[194:197], v185 offset:50720
	ds_read_b128 v[202:205], v184 offset:64
	ds_read_b128 v[210:213], v184 offset:4672
	s_waitcnt lgkmcnt(9)
	v_mfma_f32_32x32x16_bf16 v[114:129], v[164:167], v[214:217], v[114:129]
	v_mfma_f32_32x32x16_bf16 v[82:97], v[164:167], v[218:221], v[82:97]
	s_waitcnt lgkmcnt(8)
	v_mfma_f32_32x32x16_bf16 v[98:113], v[174:177], v[214:217], v[98:113]
	v_mfma_f32_32x32x16_bf16 v[66:81], v[174:177], v[218:221], v[66:81]
	s_waitcnt lgkmcnt(3)
	v_mfma_f32_32x32x16_bf16 v[50:65], v[168:171], v[214:217], v[50:65]
	v_mfma_f32_32x32x16_bf16 v[18:33], v[168:171], v[218:221], v[18:33]
	ds_read_b128 v[164:167], v185 offset:36928
	ds_read_b128 v[168:171], v185 offset:41536
	s_waitcnt lgkmcnt(4)
	v_mfma_f32_32x32x16_bf16 v[34:49], v[194:197], v[214:217], v[34:49]
	v_mfma_f32_32x32x16_bf16 v[2:17], v[194:197], v[218:221], v[2:17]
	v_lshl_add_u64 v[174:175], s[26:27], 0, v[162:163]
	v_lshl_add_u64 v[198:199], v[174:175], 0, s[96:97]
	s_waitcnt vmcnt(6)
	ds_write_b128 v187, v[154:157] offset:9216
	v_add_co_u32_e32 v154, vcc, s91, v198
	ds_write_b128 v187, v[138:141]
	s_nop 0
	v_addc_co_u32_e32 v155, vcc, 0, v199, vcc
	global_load_dwordx4 v[138:141], v[198:199], off
	s_nop 0
	global_load_dwordx4 v[154:157], v[154:155], off
	ds_read_b128 v[174:177], v185 offset:46144
	ds_read_b128 v[194:197], v185 offset:50752
	ds_read_b128 v[214:217], v184 offset:96
	ds_read_b128 v[218:221], v184 offset:4704
	s_waitcnt lgkmcnt(7)
	v_mfma_f32_32x32x16_bf16 v[114:129], v[164:167], v[202:205], v[114:129]
	v_mfma_f32_32x32x16_bf16 v[82:97], v[164:167], v[210:213], v[82:97]
	s_waitcnt lgkmcnt(6)
	v_mfma_f32_32x32x16_bf16 v[98:113], v[168:171], v[202:205], v[98:113]
	v_mfma_f32_32x32x16_bf16 v[66:81], v[168:171], v[210:213], v[66:81]
	s_waitcnt lgkmcnt(3)
	v_mfma_f32_32x32x16_bf16 v[50:65], v[174:177], v[202:205], v[50:65]
	ds_read_b128 v[164:167], v185 offset:36960
	ds_read_b128 v[168:171], v185 offset:41568
	v_mfma_f32_32x32x16_bf16 v[18:33], v[174:177], v[210:213], v[18:33]
	s_waitcnt lgkmcnt(4)
	v_mfma_f32_32x32x16_bf16 v[34:49], v[194:197], v[202:205], v[34:49]
	v_mfma_f32_32x32x16_bf16 v[2:17], v[194:197], v[210:213], v[2:17]
	s_waitcnt vmcnt(7)
	ds_write_b128 v187, v[146:149] offset:18432
	v_add_co_u32_e32 v146, vcc, s1, v198
	s_waitcnt vmcnt(6)
	ds_write_b128 v187, v[158:161] offset:27648
	v_addc_co_u32_e32 v147, vcc, 0, v199, vcc
	v_add_co_u32_e32 v158, vcc, s76, v198
	global_load_dwordx4 v[146:149], v[146:147], off
	s_nop 0
	v_addc_co_u32_e32 v159, vcc, 0, v199, vcc
	global_load_dwordx4 v[158:161], v[158:159], off
	ds_read_b128 v[174:177], v185 offset:46176
	ds_read_b128 v[194:197], v185 offset:50784
	s_waitcnt lgkmcnt(5)
	v_mfma_f32_32x32x16_bf16 v[114:129], v[164:167], v[214:217], v[114:129]
	v_mfma_f32_32x32x16_bf16 v[82:97], v[164:167], v[218:221], v[82:97]
	s_waitcnt lgkmcnt(4)
	v_mfma_f32_32x32x16_bf16 v[98:113], v[168:171], v[214:217], v[98:113]
	v_mfma_f32_32x32x16_bf16 v[66:81], v[168:171], v[218:221], v[66:81]
	s_waitcnt lgkmcnt(0)
	s_barrier
	ds_read_b128 v[202:205], v188
	ds_read_b128 v[210:213], v188 offset:4608
	ds_read_b128 v[164:167], v189
	ds_read_b128 v[168:171], v189 offset:4608
	v_mfma_f32_32x32x16_bf16 v[50:65], v[174:177], v[214:217], v[50:65]
	v_mfma_f32_32x32x16_bf16 v[18:33], v[174:177], v[218:221], v[18:33]
	ds_read_b128 v[174:177], v189 offset:9216
	v_mfma_f32_32x32x16_bf16 v[34:49], v[194:197], v[214:217], v[34:49]
	v_mfma_f32_32x32x16_bf16 v[2:17], v[194:197], v[218:221], v[2:17]
	ds_read_b128 v[194:197], v189 offset:13824
	v_add_u32_e32 v0, v181, v173
	ds_read_b128 v[214:217], v0 offset:32
	ds_read_b128 v[218:221], v190 offset:32
	s_cmp_lt_u32 s35, 13
	s_cselect_b64 s[26:27], -1, 0
	s_and_b64 s[26:27], s[26:27], exec
	s_cselect_b32 s37, s9, s30
	s_cselect_b32 s36, s8, s29
	s_cselect_b32 s27, s11, s33
	s_cselect_b32 s26, s10, s31
	s_waitcnt lgkmcnt(5)
	v_mfma_f32_32x32x16_bf16 v[114:129], v[164:167], v[202:205], v[114:129]
	v_mfma_f32_32x32x16_bf16 v[82:97], v[164:167], v[210:213], v[82:97]
	s_waitcnt lgkmcnt(4)
	v_mfma_f32_32x32x16_bf16 v[98:113], v[168:171], v[202:205], v[98:113]
	v_mfma_f32_32x32x16_bf16 v[66:81], v[168:171], v[210:213], v[66:81]
	s_waitcnt lgkmcnt(3)
	v_mfma_f32_32x32x16_bf16 v[50:65], v[174:177], v[202:205], v[50:65]
	v_add_u32_e32 v172, v182, v173
	s_cselect_b32 s38, s34, s28
	v_mfma_f32_32x32x16_bf16 v[18:33], v[174:177], v[210:213], v[18:33]
	s_waitcnt lgkmcnt(2)
	v_mfma_f32_32x32x16_bf16 v[34:49], v[194:197], v[202:205], v[34:49]
	ds_read_b128 v[164:167], v172 offset:32
	ds_read_b128 v[174:177], v191 offset:32
	v_mfma_f32_32x32x16_bf16 v[2:17], v[194:197], v[210:213], v[2:17]
	s_lshl_b32 s96, s38, 7
	v_lshl_add_u64 v[168:169], s[36:37], 0, v[162:163]
	v_lshl_add_u64 v[168:169], v[168:169], 0, s[96:97]
	s_waitcnt vmcnt(6)
	ds_write_b128 v183, v[142:145] offset:9216
	v_add_co_u32_e32 v142, vcc, s91, v168
	ds_write_b128 v183, v[134:137]
	s_nop 0
	v_addc_co_u32_e32 v143, vcc, 0, v169, vcc
	global_load_dwordx4 v[134:137], v[168:169], off
	s_nop 0
	global_load_dwordx4 v[142:145], v[142:143], off
	s_waitcnt vmcnt(7)
	ds_write_b128 v183, v[130:133] offset:18432
	v_add_co_u32_e32 v130, vcc, s1, v168
	s_waitcnt vmcnt(6)
	ds_write_b128 v183, v[150:153] offset:27648
	v_addc_co_u32_e32 v131, vcc, 0, v169, vcc
	v_add_co_u32_e32 v150, vcc, s76, v168
	global_load_dwordx4 v[130:133], v[130:131], off
	s_nop 0
	v_addc_co_u32_e32 v151, vcc, 0, v169, vcc
	global_load_dwordx4 v[150:153], v[150:151], off
	ds_read_b128 v[168:171], v208 offset:32
	ds_read_b128 v[194:197], v209 offset:32
	ds_read_b128 v[202:205], v0 offset:64
	ds_read_b128 v[210:213], v190 offset:64
	s_waitcnt lgkmcnt(9)
	v_mfma_f32_32x32x16_bf16 v[114:129], v[164:167], v[214:217], v[114:129]
	v_mfma_f32_32x32x16_bf16 v[82:97], v[164:167], v[218:221], v[82:97]
	s_waitcnt lgkmcnt(8)
	v_mfma_f32_32x32x16_bf16 v[98:113], v[174:177], v[214:217], v[98:113]
	v_mfma_f32_32x32x16_bf16 v[66:81], v[174:177], v[218:221], v[66:81]
	s_waitcnt lgkmcnt(3)
	v_mfma_f32_32x32x16_bf16 v[50:65], v[168:171], v[214:217], v[50:65]
	v_mfma_f32_32x32x16_bf16 v[18:33], v[168:171], v[218:221], v[18:33]
	ds_read_b128 v[164:167], v172 offset:64
	ds_read_b128 v[168:171], v191 offset:64
	s_waitcnt lgkmcnt(4)
	v_mfma_f32_32x32x16_bf16 v[34:49], v[194:197], v[214:217], v[34:49]
	v_mfma_f32_32x32x16_bf16 v[2:17], v[194:197], v[218:221], v[2:17]
	v_lshl_add_u64 v[174:175], s[26:27], 0, v[162:163]
	v_lshl_add_u64 v[198:199], v[174:175], 0, s[96:97]
	s_waitcnt vmcnt(6)
	ds_write_b128 v183, v[154:157] offset:46080
	v_add_co_u32_e32 v154, vcc, s91, v198
	ds_write_b128 v183, v[138:141] offset:36864
	s_nop 0
	v_addc_co_u32_e32 v155, vcc, 0, v199, vcc
	global_load_dwordx4 v[138:141], v[198:199], off
	s_nop 0
	global_load_dwordx4 v[154:157], v[154:155], off
	ds_read_b128 v[174:177], v208 offset:64
	ds_read_b128 v[194:197], v209 offset:64
	ds_read_b128 v[214:217], v0 offset:96
	ds_read_b128 v[218:221], v190 offset:96
	s_waitcnt lgkmcnt(7)
	v_mfma_f32_32x32x16_bf16 v[114:129], v[164:167], v[202:205], v[114:129]
	v_mfma_f32_32x32x16_bf16 v[82:97], v[164:167], v[210:213], v[82:97]
	s_waitcnt lgkmcnt(6)
	v_mfma_f32_32x32x16_bf16 v[98:113], v[168:171], v[202:205], v[98:113]
	v_mfma_f32_32x32x16_bf16 v[66:81], v[168:171], v[210:213], v[66:81]
	s_waitcnt lgkmcnt(3)
	v_mfma_f32_32x32x16_bf16 v[50:65], v[174:177], v[202:205], v[50:65]
	ds_read_b128 v[164:167], v172 offset:96
	ds_read_b128 v[168:171], v191 offset:96
	v_mfma_f32_32x32x16_bf16 v[18:33], v[174:177], v[210:213], v[18:33]
	s_waitcnt lgkmcnt(4)
	v_mfma_f32_32x32x16_bf16 v[34:49], v[194:197], v[202:205], v[34:49]
	v_mfma_f32_32x32x16_bf16 v[2:17], v[194:197], v[210:213], v[2:17]
	s_waitcnt vmcnt(7)
	ds_write_b128 v183, v[146:149] offset:55296
	v_add_co_u32_e32 v146, vcc, s1, v198
	s_waitcnt vmcnt(6)
	ds_write_b128 v183, v[158:161] offset:64512
	v_addc_co_u32_e32 v147, vcc, 0, v199, vcc
	v_add_co_u32_e32 v158, vcc, s76, v198
	global_load_dwordx4 v[146:149], v[146:147], off
	s_nop 0
	v_addc_co_u32_e32 v159, vcc, 0, v199, vcc
	global_load_dwordx4 v[158:161], v[158:159], off
	ds_read_b128 v[174:177], v208 offset:96
	ds_read_b128 v[194:197], v209 offset:96
	s_waitcnt lgkmcnt(5)
	v_mfma_f32_32x32x16_bf16 v[114:129], v[164:167], v[214:217], v[114:129]
	v_mfma_f32_32x32x16_bf16 v[82:97], v[164:167], v[218:221], v[82:97]
	s_waitcnt lgkmcnt(4)
	v_mfma_f32_32x32x16_bf16 v[98:113], v[168:171], v[214:217], v[98:113]
	v_mfma_f32_32x32x16_bf16 v[66:81], v[168:171], v[218:221], v[66:81]
	s_waitcnt lgkmcnt(0)
	s_barrier
;   DI void operator()(int tok0, int feat0, f32x16 (&acc)[2][2], int r, int hh) const {
;     const int seg = feat0 >> 10, c0 = feat0 & 1023;
; #pragma unroll
;     for (int mt = 0; mt < 2; ++mt) {
;       const int tok = tok0 + mt * 32 + r, b = tok >> 14, s = tok & (SEQ - 1);
;       if (seg < 2) {
;         float ssq = 0.f;
; #pragma unroll
;         for (int nt = 0; nt < 2; ++nt)
; #pragma unroll
;           for (int i = 0; i < 16; ++i) ssq += acc[nt][mt][i] * acc[nt][mt][i];
;         ssq = xsum32(ssq);
;         float rs = rsqrtf(ssq * (1.f / 64.f) + 1e-6f);
;         if (seg == 0) rs *= 0.125f * LOG2E;
;         const float* gg = seg == 0 ? qg : kg;
;         bf16_t* dstb = (seg == 0 ? fq : fk) + (size_t)tok * 1024 + c0;
; #pragma unroll
;         for (int nt = 0; nt < 2; ++nt)
; #pragma unroll
;           for (int gp = 0; gp < 2; ++gp) {
;             const int d = nt * 32 + 16 * hh + 8 * gp;
;             f32x4 g0 = *(const f32x4*)(gg + d), g1 = *(const f32x4*)(gg + d + 4);
;             u32x4 o = {pk2(acc[nt][mt][8 * gp] * rs * g0[0], acc[nt][mt][8 * gp + 1] * rs * g0[1]), pk2(acc[nt][mt][8 * gp + 2] * rs * g0[2], acc[nt][mt][8 * gp + 3] * rs * g0[3]),
;                        pk2(acc[nt][mt][8 * gp + 4] * rs * g1[0], acc[nt][mt][8 * gp + 5] * rs * g1[1]), pk2(acc[nt][mt][8 * gp + 6] * rs * g1[2], acc[nt][mt][8 * gp + 7] * rs * g1[3])};
;             *(u32x4*)(dstb + d) = o;
;             __builtin_amdgcn_sched_barrier(0);
;           }
;       } else if (seg == 2) {
;         const int head = c0 >> 6;
; #pragma unroll
;         for (int nt = 0; nt < 2; ++nt)
; #pragma unroll
;           for (int i = 0; i < 16; ++i) {
;             const int d = nt * 32 + 16 * hh + i;
;             fvT[((size_t)((b * 16 + head) * 64 + d)) * SEQ + swz32(s)] = f2bf(acc[nt][mt][i]);
;           }
;       } else if (seg == 3) {
; #pragma unroll
;         for (int nt = 0; nt < 2; ++nt)
; #pragma unroll
;           for (int gp = 0; gp < 2; ++gp) {
;             const int c = c0 + nt * 32 + 16 * hh + 8 * gp;
;             u32x4 o = {pk2(sigmoidf_(acc[nt][mt][8 * gp]), sigmoidf_(acc[nt][mt][8 * gp + 1])), pk2(sigmoidf_(acc[nt][mt][8 * gp + 2]), sigmoidf_(acc[nt][mt][8 * gp + 3])),
;                        pk2(sigmoidf_(acc[nt][mt][8 * gp + 4]), sigmoidf_(acc[nt][mt][8 * gp + 5])), pk2(sigmoidf_(acc[nt][mt][8 * gp + 6]), sigmoidf_(acc[nt][mt][8 * gp + 7]))};
	v_add_u32_e32 v0, v178, v179
	ds_read_b128 v[202:205], v0
	ds_read_b128 v[210:213], v0 offset:4608
	v_add_u32_e32 v0, v178, v180
	ds_read_b128 v[164:167], v0 offset:36864
	ds_read_b128 v[168:171], v0 offset:41472
	v_mfma_f32_32x32x16_bf16 v[50:65], v[174:177], v[214:217], v[50:65]
	v_mfma_f32_32x32x16_bf16 v[18:33], v[174:177], v[218:221], v[18:33]
	ds_read_b128 v[174:177], v0 offset:46080
	v_mfma_f32_32x32x16_bf16 v[34:49], v[194:197], v[214:217], v[34:49]
	v_mfma_f32_32x32x16_bf16 v[2:17], v[194:197], v[218:221], v[2:17]
	ds_read_b128 v[194:197], v0 offset:50688
	ds_read_b128 v[214:217], v184 offset:32
	ds_read_b128 v[218:221], v184 offset:4640
	s_add_i32 s34, s34, 2
	s_cmp_gt_u32 s35, 13
	s_cbranch_scc0 .Lkloop_top_0
	s_waitcnt lgkmcnt(0)
	v_mov_b32_e32 v212, v192
	s_ashr_i32 s47, s2, 14
	v_ashrrev_i32_e32 v164, 1, v212
	v_and_b32_e32 v164, 0xffffff80, v164
	v_bfe_u32 v0, v212, 5, 1
	v_add_u32_e32 v165, s3, v164
	s_movk_i32 s3, 0x1000
	v_ashrrev_i32_e32 v213, 10, v165
	v_and_b32_e32 v210, 0x380, v165
	v_and_b32_e32 v166, 0xdf, v212
	v_lshlrev_b32_e32 v211, 4, v0
	v_cmp_eq_u32_e32 vcc, s3, v165
	v_cmp_eq_u32_e64 s[10:11], 0, v0
	s_movk_i32 s3, 0x400
	v_mov_b32_e32 v0, s4
	v_or_b32_e32 v164, s4, v166
	v_cmp_lt_i32_e64 s[8:9], 1, v213
	v_or_b32_e32 v215, v210, v211
	s_and_b64 s[26:27], s[10:11], vcc
	v_cmp_gt_u32_e32 vcc, s3, v165
	v_bitop3_b32 v214, v166, s53, v0 bitop3:0xc8
	s_and_saveexec_b64 s[2:3], s[8:9]
	s_xor_b64 s[28:29], exec, s[2:3]
	s_cbranch_execz .LBB0_99
	v_cmp_lt_i32_e64 s[10:11], 2, v213
	s_and_saveexec_b64 s[2:3], s[10:11]
	s_xor_b64 s[30:31], exec, s[2:3]
	s_cbranch_execz .LBB0_96
	v_cmp_ne_u32_e64 s[10:11], 3, v213
	s_and_saveexec_b64 s[2:3], s[10:11]
	s_xor_b64 s[34:35], exec, s[2:3]
	s_cbranch_execz .LBB0_93
	s_and_saveexec_b64 s[36:37], s[26:27]
	s_cbranch_execz .LBB0_92
	v_lshlrev_b32_e32 v0, 2, v214
	v_lshl_add_u64 v[166:167], s[16:17], 0, v[0:1]
	global_load_dword v0, v1, s[18:19]
	v_mov_b32_e32 v197, 0x7f800000
	v_mov_b32_e32 v196, 0x3ecc95a3
	s_lshl_b32 s38, s47, 4
	s_ashr_i32 s39, s38, 31
	s_lshl_b64 s[2:3], s[38:39], 16
	s_waitcnt vmcnt(0)
	v_add_f32_e32 v0, v114, v0
	v_mul_f32_e64 v168, |v0|, s54
	v_fma_f32 v169, |v0|, s54, -v168
	v_rndne_f32_e32 v170, v168
	v_fma_f32 v169, |v0|, s55, v169
	v_sub_f32_e32 v168, v168, v170
	v_add_f32_e32 v168, v168, v169
	v_exp_f32_e32 v168, v168
	v_cvt_i32_f32_e32 v169, v170
	v_cmp_ngt_f32_e64 s[10:11], |v0|, s56
	v_min_f32_e32 v165, 0, v0
	v_ldexp_f32 v168, v168, v169
	v_cndmask_b32_e64 v168, 0, v168, s[10:11]
	v_cmp_nlt_f32_e64 s[10:11], |v0|, s57
	s_nop 1
	v_cndmask_b32_e64 v0, v197, v168, s[10:11]
	v_add_f32_e32 v170, 1.0, v0
	v_add_f32_e32 v168, -1.0, v170
	v_sub_f32_e32 v169, v168, v170
	v_add_f32_e32 v169, 1.0, v169
	v_sub_f32_e32 v168, v0, v168
	v_add_f32_e32 v171, v168, v169
	v_frexp_mant_f32_e32 v168, v170
	v_cmp_gt_f32_e64 s[10:11], s59, v168
	v_cvt_f64_f32_e32 v[168:169], v170
	v_frexp_exp_i32_f64_e32 v168, v[168:169]
	v_subbrev_co_u32_e64 v168, s[10:11], 0, v168, s[10:11]
	v_sub_u32_e32 v169, 0, v168
	v_ldexp_f32 v170, v170, v169
	v_ldexp_f32 v169, v171, v169
	v_add_f32_e32 v171, -1.0, v170
	v_add_f32_e32 v172, 1.0, v171
	v_sub_f32_e32 v172, v170, v172
	v_add_f32_e32 v172, v169, v172
	v_add_f32_e32 v174, v171, v172
	v_sub_f32_e32 v171, v171, v174
	v_add_f32_e32 v171, v172, v171
	v_add_f32_e32 v172, 1.0, v170
	v_add_f32_e32 v175, -1.0, v172
	v_sub_f32_e32 v170, v170, v175
	v_add_f32_e32 v169, v169, v170
	v_add_f32_e32 v170, v172, v169
	v_sub_f32_e32 v172, v172, v170
	v_add_f32_e32 v169, v169, v172
	v_rcp_f32_e32 v172, v170
	v_cvt_f32_i32_e32 v168, v168
	v_cmp_neq_f32_e64 s[10:11], s58, v0
	v_mul_f32_e32 v175, v174, v172
	v_mul_f32_e32 v176, v170, v175
	v_fma_f32 v177, v175, v170, -v176
	v_fmac_f32_e32 v177, v175, v169
	v_add_f32_e32 v194, v176, v177
	v_sub_f32_e32 v195, v174, v194
	v_sub_f32_e32 v174, v174, v195
	v_sub_f32_e32 v176, v194, v176
	v_sub_f32_e32 v174, v174, v194
	v_add_f32_e32 v171, v171, v174
	v_sub_f32_e32 v174, v176, v177
	v_add_f32_e32 v171, v174, v171
	v_add_f32_e32 v174, v195, v171
	v_mul_f32_e32 v176, v172, v174
	v_mul_f32_e32 v177, v170, v176
	v_fma_f32 v170, v176, v170, -v177
	v_fmac_f32_e32 v170, v176, v169
	v_sub_f32_e32 v169, v195, v174
	v_add_f32_e32 v169, v171, v169
	v_add_f32_e32 v171, v177, v170
	v_sub_f32_e32 v194, v174, v171
	v_sub_f32_e32 v174, v174, v194
	v_sub_f32_e32 v177, v171, v177
	v_sub_f32_e32 v171, v174, v171
	v_add_f32_e32 v169, v169, v171
	v_sub_f32_e32 v170, v177, v170
	v_add_f32_e32 v169, v170, v169
	v_add_f32_e32 v170, v175, v176
	v_add_f32_e32 v169, v194, v169
	v_sub_f32_e32 v171, v170, v175
	v_mul_f32_e32 v169, v172, v169
	v_sub_f32_e32 v171, v176, v171
	v_add_f32_e32 v169, v171, v169
	v_mul_f32_e32 v175, 0x3f317218, v168
	v_add_f32_e32 v171, v170, v169
	v_fma_f32 v176, v168, s60, -v175
	v_mul_f32_e32 v172, v171, v171
	v_fmac_f32_e32 v176, 0xb102e308, v168
	v_sub_f32_e32 v168, v171, v170
	v_fmamk_f32 v174, v172, 0x3e9b6dac, v196
	v_sub_f32_e32 v168, v169, v168
	v_add_f32_e32 v169, v175, v176
	v_fmaak_f32 v174, v172, v174, 0x3f2aaada
	v_sub_f32_e32 v170, v169, v175
	v_ldexp_f32 v175, v171, 1
	v_mul_f32_e32 v171, v171, v172
	v_mul_f32_e32 v171, v171, v174
	v_add_f32_e32 v172, v175, v171
	v_sub_f32_e32 v174, v172, v175
	v_ldexp_f32 v168, v168, 1
	v_sub_f32_e32 v171, v171, v174
	v_add_f32_e32 v168, v168, v171
	v_add_f32_e32 v171, v172, v168
	v_sub_f32_e32 v172, v171, v172
	v_sub_f32_e32 v168, v168, v172
	v_add_f32_e32 v172, v169, v171
	v_sub_f32_e32 v174, v172, v169
	v_sub_f32_e32 v175, v172, v174
	v_sub_f32_e32 v170, v176, v170
	v_sub_f32_e32 v169, v169, v175
	v_sub_f32_e32 v171, v171, v174
	v_add_f32_e32 v169, v171, v169
	v_add_f32_e32 v171, v170, v168
	v_sub_f32_e32 v174, v171, v170
	v_sub_f32_e32 v175, v171, v174
	v_sub_f32_e32 v170, v170, v175
	v_sub_f32_e32 v168, v168, v174
	v_add_f32_e32 v169, v171, v169
	v_add_f32_e32 v168, v168, v170
	v_add_f32_e32 v170, v172, v169
	v_sub_f32_e32 v171, v170, v172
	v_sub_f32_e32 v169, v169, v171
	v_add_f32_e32 v168, v168, v169
	v_add_f32_e32 v168, v170, v168
	v_cndmask_b32_e64 v168, v197, v168, s[10:11]
	v_cmp_lt_f32_e64 s[10:11], |v0|, s61
	s_nop 1
	v_cndmask_b32_e64 v0, v168, v0, s[10:11]
	v_sub_f32_e32 v0, v165, v0
	v_lshl_add_u64 v[168:169], v[166:167], 0, s[2:3]
	global_store_dword v[168:169], v0, off
	global_load_dword v0, v1, s[18:19] offset:4
	s_or_b32 s2, s38, 1
	s_ashr_i32 s3, s2, 31
	s_lshl_b64 s[2:3], s[2:3], 16
	s_waitcnt vmcnt(0)
;   DI void operator()(int tok0, int feat0, f32x16 (&acc)[2][2], int r, int hh) const {
;     ...
;           for (int i = 0; i < 16; ++i) {
;             const float xv = acc[0][mt][i] + bf[i];
;             const float ls = fminf(xv, 0.f) - log1pf(expf(-fabsf(xv)));
;             lf[((size_t)(b * 16 + i)) * SEQ + s] = ls;
;           }
	v_add_f32_e32 v0, v115, v0
	v_mul_f32_e64 v168, |v0|, s54
	v_fma_f32 v169, |v0|, s54, -v168
	v_rndne_f32_e32 v170, v168
	v_fma_f32 v169, |v0|, s55, v169
	v_sub_f32_e32 v168, v168, v170
	v_add_f32_e32 v168, v168, v169
	v_exp_f32_e32 v168, v168
	v_cvt_i32_f32_e32 v169, v170
	v_cmp_ngt_f32_e64 s[10:11], |v0|, s56
	v_min_f32_e32 v165, 0, v0
	v_ldexp_f32 v168, v168, v169
	v_cndmask_b32_e64 v168, 0, v168, s[10:11]
	v_cmp_nlt_f32_e64 s[10:11], |v0|, s57
	s_nop 1
	v_cndmask_b32_e64 v0, v197, v168, s[10:11]
	v_add_f32_e32 v170, 1.0, v0
	v_add_f32_e32 v168, -1.0, v170
	v_sub_f32_e32 v169, v168, v170
	v_add_f32_e32 v169, 1.0, v169
	v_sub_f32_e32 v168, v0, v168
	v_add_f32_e32 v171, v168, v169
	v_frexp_mant_f32_e32 v168, v170
	v_cmp_gt_f32_e64 s[10:11], s59, v168
	v_cvt_f64_f32_e32 v[168:169], v170
	v_frexp_exp_i32_f64_e32 v168, v[168:169]
	v_subbrev_co_u32_e64 v168, s[10:11], 0, v168, s[10:11]
	v_sub_u32_e32 v169, 0, v168
	v_ldexp_f32 v170, v170, v169
	v_ldexp_f32 v169, v171, v169
	v_add_f32_e32 v171, -1.0, v170
	v_add_f32_e32 v172, 1.0, v171
	v_sub_f32_e32 v172, v170, v172
	v_add_f32_e32 v172, v169, v172
	v_add_f32_e32 v174, v171, v172
	v_sub_f32_e32 v171, v171, v174
	v_add_f32_e32 v171, v172, v171
	v_add_f32_e32 v172, 1.0, v170
	v_add_f32_e32 v175, -1.0, v172
	v_sub_f32_e32 v170, v170, v175
	v_add_f32_e32 v169, v169, v170
	v_add_f32_e32 v170, v172, v169
	v_sub_f32_e32 v172, v172, v170
	v_add_f32_e32 v169, v169, v172
	v_rcp_f32_e32 v172, v170
	v_cvt_f32_i32_e32 v168, v168
	v_cmp_neq_f32_e64 s[10:11], s58, v0
	v_mul_f32_e32 v175, v174, v172
	v_mul_f32_e32 v176, v170, v175
	v_fma_f32 v177, v175, v170, -v176
	v_fmac_f32_e32 v177, v175, v169
	v_add_f32_e32 v194, v176, v177
	v_sub_f32_e32 v195, v174, v194
	v_sub_f32_e32 v174, v174, v195
	v_sub_f32_e32 v176, v194, v176
	v_sub_f32_e32 v174, v174, v194
	v_add_f32_e32 v171, v171, v174
	v_sub_f32_e32 v174, v176, v177
	v_add_f32_e32 v171, v174, v171
	v_add_f32_e32 v174, v195, v171
	v_mul_f32_e32 v176, v172, v174
	v_mul_f32_e32 v177, v170, v176
	v_fma_f32 v170, v176, v170, -v177
	v_fmac_f32_e32 v170, v176, v169
	v_sub_f32_e32 v169, v195, v174
	v_add_f32_e32 v169, v171, v169
	v_add_f32_e32 v171, v177, v170
	v_sub_f32_e32 v194, v174, v171
	v_sub_f32_e32 v174, v174, v194
	v_sub_f32_e32 v177, v171, v177
	v_sub_f32_e32 v171, v174, v171
	v_add_f32_e32 v169, v169, v171
	v_sub_f32_e32 v170, v177, v170
	v_add_f32_e32 v169, v170, v169
	v_add_f32_e32 v170, v175, v176
	v_add_f32_e32 v169, v194, v169
	v_sub_f32_e32 v171, v170, v175
	v_mul_f32_e32 v169, v172, v169
	v_sub_f32_e32 v171, v176, v171
	v_add_f32_e32 v169, v171, v169
	v_mul_f32_e32 v175, 0x3f317218, v168
	v_add_f32_e32 v171, v170, v169
	v_fma_f32 v176, v168, s60, -v175
	v_mul_f32_e32 v172, v171, v171
	v_fmac_f32_e32 v176, 0xb102e308, v168
	v_sub_f32_e32 v168, v171, v170
	v_fmamk_f32 v174, v172, 0x3e9b6dac, v196
	v_sub_f32_e32 v168, v169, v168
	v_add_f32_e32 v169, v175, v176
	v_fmaak_f32 v174, v172, v174, 0x3f2aaada
	v_sub_f32_e32 v170, v169, v175
	v_ldexp_f32 v175, v171, 1
	v_mul_f32_e32 v171, v171, v172
	v_mul_f32_e32 v171, v171, v174
	v_add_f32_e32 v172, v175, v171
	v_sub_f32_e32 v174, v172, v175
	v_ldexp_f32 v168, v168, 1
	v_sub_f32_e32 v171, v171, v174
	v_add_f32_e32 v168, v168, v171
	v_add_f32_e32 v171, v172, v168
	v_sub_f32_e32 v172, v171, v172
	v_sub_f32_e32 v168, v168, v172
	v_add_f32_e32 v172, v169, v171
	v_sub_f32_e32 v174, v172, v169
	v_sub_f32_e32 v175, v172, v174
	v_sub_f32_e32 v170, v176, v170
	v_sub_f32_e32 v169, v169, v175
	v_sub_f32_e32 v171, v171, v174
	v_add_f32_e32 v169, v171, v169
	v_add_f32_e32 v171, v170, v168
	v_sub_f32_e32 v174, v171, v170
	v_sub_f32_e32 v175, v171, v174
	v_sub_f32_e32 v170, v170, v175
	v_sub_f32_e32 v168, v168, v174
	v_add_f32_e32 v169, v171, v169
	v_add_f32_e32 v168, v168, v170
	v_add_f32_e32 v170, v172, v169
	v_sub_f32_e32 v171, v170, v172
	v_sub_f32_e32 v169, v169, v171
	v_add_f32_e32 v168, v168, v169
	v_add_f32_e32 v168, v170, v168
	v_cndmask_b32_e64 v168, v197, v168, s[10:11]
	v_cmp_lt_f32_e64 s[10:11], |v0|, s61
	s_nop 1
	v_cndmask_b32_e64 v0, v168, v0, s[10:11]
	v_sub_f32_e32 v0, v165, v0
	v_lshl_add_u64 v[168:169], v[166:167], 0, s[2:3]
	global_store_dword v[168:169], v0, off
	global_load_dword v0, v1, s[18:19] offset:8
	s_or_b32 s2, s38, 2
	s_ashr_i32 s3, s2, 31
	s_lshl_b64 s[2:3], s[2:3], 16
	s_waitcnt vmcnt(0)
;   DI void operator()(int tok0, int feat0, f32x16 (&acc)[2][2], int r, int hh) const {
;     ...
;           for (int i = 0; i < 16; ++i) {
;             const float xv = acc[0][mt][i] + bf[i];
;             const float ls = fminf(xv, 0.f) - log1pf(expf(-fabsf(xv)));
;             lf[((size_t)(b * 16 + i)) * SEQ + s] = ls;
;           }
	v_add_f32_e32 v0, v116, v0
	v_mul_f32_e64 v168, |v0|, s54
	v_fma_f32 v169, |v0|, s54, -v168
	v_rndne_f32_e32 v170, v168
	v_fma_f32 v169, |v0|, s55, v169
	v_sub_f32_e32 v168, v168, v170
	v_add_f32_e32 v168, v168, v169
	v_exp_f32_e32 v168, v168
	v_cvt_i32_f32_e32 v169, v170
	v_cmp_ngt_f32_e64 s[10:11], |v0|, s56
	v_min_f32_e32 v165, 0, v0
	v_ldexp_f32 v168, v168, v169
	v_cndmask_b32_e64 v168, 0, v168, s[10:11]
	v_cmp_nlt_f32_e64 s[10:11], |v0|, s57
	s_nop 1
	v_cndmask_b32_e64 v0, v197, v168, s[10:11]
	v_add_f32_e32 v170, 1.0, v0
	v_add_f32_e32 v168, -1.0, v170
	v_sub_f32_e32 v169, v168, v170
	v_add_f32_e32 v169, 1.0, v169
	v_sub_f32_e32 v168, v0, v168
	v_add_f32_e32 v171, v168, v169
	v_frexp_mant_f32_e32 v168, v170
	v_cmp_gt_f32_e64 s[10:11], s59, v168
	v_cvt_f64_f32_e32 v[168:169], v170
	v_frexp_exp_i32_f64_e32 v168, v[168:169]
	v_subbrev_co_u32_e64 v168, s[10:11], 0, v168, s[10:11]
	v_sub_u32_e32 v169, 0, v168
	v_ldexp_f32 v170, v170, v169
	v_ldexp_f32 v169, v171, v169
	v_add_f32_e32 v171, -1.0, v170
	v_add_f32_e32 v172, 1.0, v171
	v_sub_f32_e32 v172, v170, v172
	v_add_f32_e32 v172, v169, v172
	v_add_f32_e32 v174, v171, v172
	v_sub_f32_e32 v171, v171, v174
	v_add_f32_e32 v171, v172, v171
	v_add_f32_e32 v172, 1.0, v170
	v_add_f32_e32 v175, -1.0, v172
	v_sub_f32_e32 v170, v170, v175
	v_add_f32_e32 v169, v169, v170
	v_add_f32_e32 v170, v172, v169
	v_sub_f32_e32 v172, v172, v170
	v_add_f32_e32 v169, v169, v172
	v_rcp_f32_e32 v172, v170
	v_cvt_f32_i32_e32 v168, v168
	v_cmp_neq_f32_e64 s[10:11], s58, v0
	v_mul_f32_e32 v175, v174, v172
	v_mul_f32_e32 v176, v170, v175
	v_fma_f32 v177, v175, v170, -v176
	v_fmac_f32_e32 v177, v175, v169
	v_add_f32_e32 v194, v176, v177
	v_sub_f32_e32 v195, v174, v194
	v_sub_f32_e32 v174, v174, v195
	v_sub_f32_e32 v176, v194, v176
	v_sub_f32_e32 v174, v174, v194
	v_add_f32_e32 v171, v171, v174
	v_sub_f32_e32 v174, v176, v177
	v_add_f32_e32 v171, v174, v171
	v_add_f32_e32 v174, v195, v171
	v_mul_f32_e32 v176, v172, v174
	v_mul_f32_e32 v177, v170, v176
	v_fma_f32 v170, v176, v170, -v177
	v_fmac_f32_e32 v170, v176, v169
	v_sub_f32_e32 v169, v195, v174
	v_add_f32_e32 v169, v171, v169
	v_add_f32_e32 v171, v177, v170
	v_sub_f32_e32 v194, v174, v171
	v_sub_f32_e32 v174, v174, v194
	v_sub_f32_e32 v177, v171, v177
	v_sub_f32_e32 v171, v174, v171
	v_add_f32_e32 v169, v169, v171
	v_sub_f32_e32 v170, v177, v170
	v_add_f32_e32 v169, v170, v169
	v_add_f32_e32 v170, v175, v176
	v_add_f32_e32 v169, v194, v169
	v_sub_f32_e32 v171, v170, v175
	v_mul_f32_e32 v169, v172, v169
	v_sub_f32_e32 v171, v176, v171
	v_add_f32_e32 v169, v171, v169
	v_mul_f32_e32 v175, 0x3f317218, v168
	v_add_f32_e32 v171, v170, v169
	v_fma_f32 v176, v168, s60, -v175
	v_mul_f32_e32 v172, v171, v171
	v_fmac_f32_e32 v176, 0xb102e308, v168
	v_sub_f32_e32 v168, v171, v170
	v_fmamk_f32 v174, v172, 0x3e9b6dac, v196
	v_sub_f32_e32 v168, v169, v168
	v_add_f32_e32 v169, v175, v176
	v_fmaak_f32 v174, v172, v174, 0x3f2aaada
	v_sub_f32_e32 v170, v169, v175
	v_ldexp_f32 v175, v171, 1
	v_mul_f32_e32 v171, v171, v172
	v_mul_f32_e32 v171, v171, v174
	v_add_f32_e32 v172, v175, v171
	v_sub_f32_e32 v174, v172, v175
	v_ldexp_f32 v168, v168, 1
	v_sub_f32_e32 v171, v171, v174
	v_add_f32_e32 v168, v168, v171
	v_add_f32_e32 v171, v172, v168
	v_sub_f32_e32 v172, v171, v172
	v_sub_f32_e32 v168, v168, v172
	v_add_f32_e32 v172, v169, v171
	v_sub_f32_e32 v174, v172, v169
	v_sub_f32_e32 v175, v172, v174
	v_sub_f32_e32 v170, v176, v170
	v_sub_f32_e32 v169, v169, v175
	v_sub_f32_e32 v171, v171, v174
	v_add_f32_e32 v169, v171, v169
	v_add_f32_e32 v171, v170, v168
	v_sub_f32_e32 v174, v171, v170
	v_sub_f32_e32 v175, v171, v174
	v_sub_f32_e32 v170, v170, v175
	v_sub_f32_e32 v168, v168, v174
	v_add_f32_e32 v169, v171, v169
	v_add_f32_e32 v168, v168, v170
	v_add_f32_e32 v170, v172, v169
	v_sub_f32_e32 v171, v170, v172
	v_sub_f32_e32 v169, v169, v171
	v_add_f32_e32 v168, v168, v169
	v_add_f32_e32 v168, v170, v168
	v_cndmask_b32_e64 v168, v197, v168, s[10:11]
	v_cmp_lt_f32_e64 s[10:11], |v0|, s61
	s_nop 1
	v_cndmask_b32_e64 v0, v168, v0, s[10:11]
	v_sub_f32_e32 v0, v165, v0
	v_lshl_add_u64 v[168:169], v[166:167], 0, s[2:3]
	global_store_dword v[168:169], v0, off
	global_load_dword v0, v1, s[18:19] offset:12
	s_or_b32 s2, s38, 3
	s_ashr_i32 s3, s2, 31
	s_lshl_b64 s[2:3], s[2:3], 16
	s_waitcnt vmcnt(0)
;   DI void operator()(int tok0, int feat0, f32x16 (&acc)[2][2], int r, int hh) const {
;     ...
;           for (int i = 0; i < 16; ++i) {
;             const float xv = acc[0][mt][i] + bf[i];
;             const float ls = fminf(xv, 0.f) - log1pf(expf(-fabsf(xv)));
;             lf[((size_t)(b * 16 + i)) * SEQ + s] = ls;
;           }
	v_add_f32_e32 v0, v117, v0
	v_mul_f32_e64 v168, |v0|, s54
	v_fma_f32 v169, |v0|, s54, -v168
	v_rndne_f32_e32 v170, v168
	v_fma_f32 v169, |v0|, s55, v169
	v_sub_f32_e32 v168, v168, v170
	v_add_f32_e32 v168, v168, v169
	v_exp_f32_e32 v168, v168
	v_cvt_i32_f32_e32 v169, v170
	v_cmp_ngt_f32_e64 s[10:11], |v0|, s56
	v_min_f32_e32 v165, 0, v0
	v_ldexp_f32 v168, v168, v169
	v_cndmask_b32_e64 v168, 0, v168, s[10:11]
	v_cmp_nlt_f32_e64 s[10:11], |v0|, s57
	s_nop 1
	v_cndmask_b32_e64 v0, v197, v168, s[10:11]
	v_add_f32_e32 v170, 1.0, v0
	v_add_f32_e32 v168, -1.0, v170
	v_sub_f32_e32 v169, v168, v170
	v_add_f32_e32 v169, 1.0, v169
	v_sub_f32_e32 v168, v0, v168
	v_add_f32_e32 v171, v168, v169
	v_frexp_mant_f32_e32 v168, v170
	v_cmp_gt_f32_e64 s[10:11], s59, v168
	v_cvt_f64_f32_e32 v[168:169], v170
	v_frexp_exp_i32_f64_e32 v168, v[168:169]
	v_subbrev_co_u32_e64 v168, s[10:11], 0, v168, s[10:11]
	v_sub_u32_e32 v169, 0, v168
	v_ldexp_f32 v170, v170, v169
	v_ldexp_f32 v169, v171, v169
	v_add_f32_e32 v171, -1.0, v170
	v_add_f32_e32 v172, 1.0, v171
	v_sub_f32_e32 v172, v170, v172
	v_add_f32_e32 v172, v169, v172
	v_add_f32_e32 v174, v171, v172
	v_sub_f32_e32 v171, v171, v174
	v_add_f32_e32 v171, v172, v171
	v_add_f32_e32 v172, 1.0, v170
	v_add_f32_e32 v175, -1.0, v172
	v_sub_f32_e32 v170, v170, v175
	v_add_f32_e32 v169, v169, v170
	v_add_f32_e32 v170, v172, v169
	v_sub_f32_e32 v172, v172, v170
	v_add_f32_e32 v169, v169, v172
	v_rcp_f32_e32 v172, v170
	v_cvt_f32_i32_e32 v168, v168
	v_cmp_neq_f32_e64 s[10:11], s58, v0
	v_mul_f32_e32 v175, v174, v172
	v_mul_f32_e32 v176, v170, v175
	v_fma_f32 v177, v175, v170, -v176
	v_fmac_f32_e32 v177, v175, v169
	v_add_f32_e32 v194, v176, v177
	v_sub_f32_e32 v195, v174, v194
	v_sub_f32_e32 v174, v174, v195
	v_sub_f32_e32 v176, v194, v176
	v_sub_f32_e32 v174, v174, v194
	v_add_f32_e32 v171, v171, v174
	v_sub_f32_e32 v174, v176, v177
	v_add_f32_e32 v171, v174, v171
	v_add_f32_e32 v174, v195, v171
	v_mul_f32_e32 v176, v172, v174
	v_mul_f32_e32 v177, v170, v176
	v_fma_f32 v170, v176, v170, -v177
	v_fmac_f32_e32 v170, v176, v169
	v_sub_f32_e32 v169, v195, v174
	v_add_f32_e32 v169, v171, v169
	v_add_f32_e32 v171, v177, v170
	v_sub_f32_e32 v194, v174, v171
	v_sub_f32_e32 v174, v174, v194
	v_sub_f32_e32 v177, v171, v177
	v_sub_f32_e32 v171, v174, v171
	v_add_f32_e32 v169, v169, v171
	v_sub_f32_e32 v170, v177, v170
	v_add_f32_e32 v169, v170, v169
	v_add_f32_e32 v170, v175, v176
	v_add_f32_e32 v169, v194, v169
	v_sub_f32_e32 v171, v170, v175
	v_mul_f32_e32 v169, v172, v169
	v_sub_f32_e32 v171, v176, v171
	v_add_f32_e32 v169, v171, v169
	v_mul_f32_e32 v175, 0x3f317218, v168
	v_add_f32_e32 v171, v170, v169
	v_fma_f32 v176, v168, s60, -v175
	v_mul_f32_e32 v172, v171, v171
	v_fmac_f32_e32 v176, 0xb102e308, v168
	v_sub_f32_e32 v168, v171, v170
	v_fmamk_f32 v174, v172, 0x3e9b6dac, v196
	v_sub_f32_e32 v168, v169, v168
	v_add_f32_e32 v169, v175, v176
	v_fmaak_f32 v174, v172, v174, 0x3f2aaada
	v_sub_f32_e32 v170, v169, v175
	v_ldexp_f32 v175, v171, 1
	v_mul_f32_e32 v171, v171, v172
	v_mul_f32_e32 v171, v171, v174
	v_add_f32_e32 v172, v175, v171
	v_sub_f32_e32 v174, v172, v175
	v_ldexp_f32 v168, v168, 1
	v_sub_f32_e32 v171, v171, v174
	v_add_f32_e32 v168, v168, v171
	v_add_f32_e32 v171, v172, v168
	v_sub_f32_e32 v172, v171, v172
	v_sub_f32_e32 v168, v168, v172
	v_add_f32_e32 v172, v169, v171
	v_sub_f32_e32 v174, v172, v169
	v_sub_f32_e32 v175, v172, v174
	v_sub_f32_e32 v170, v176, v170
	v_sub_f32_e32 v169, v169, v175
	v_sub_f32_e32 v171, v171, v174
	v_add_f32_e32 v169, v171, v169
	v_add_f32_e32 v171, v170, v168
	v_sub_f32_e32 v174, v171, v170
	v_sub_f32_e32 v175, v171, v174
	v_sub_f32_e32 v170, v170, v175
	v_sub_f32_e32 v168, v168, v174
	v_add_f32_e32 v169, v171, v169
	v_add_f32_e32 v168, v168, v170
	v_add_f32_e32 v170, v172, v169
	v_sub_f32_e32 v171, v170, v172
	v_sub_f32_e32 v169, v169, v171
	v_add_f32_e32 v168, v168, v169
	v_add_f32_e32 v168, v170, v168
	v_cndmask_b32_e64 v168, v197, v168, s[10:11]
	v_cmp_lt_f32_e64 s[10:11], |v0|, s61
	s_nop 1
	v_cndmask_b32_e64 v0, v168, v0, s[10:11]
	v_sub_f32_e32 v0, v165, v0
	v_lshl_add_u64 v[168:169], v[166:167], 0, s[2:3]
	global_store_dword v[168:169], v0, off
	global_load_dword v0, v1, s[18:19] offset:16
	s_or_b32 s2, s38, 4
	s_ashr_i32 s3, s2, 31
	s_lshl_b64 s[2:3], s[2:3], 16
	s_waitcnt vmcnt(0)
;   DI void operator()(int tok0, int feat0, f32x16 (&acc)[2][2], int r, int hh) const {
;     ...
;           for (int i = 0; i < 16; ++i) {
;             const float xv = acc[0][mt][i] + bf[i];
;             const float ls = fminf(xv, 0.f) - log1pf(expf(-fabsf(xv)));
;             lf[((size_t)(b * 16 + i)) * SEQ + s] = ls;
;           }
	v_add_f32_e32 v0, v118, v0
	v_mul_f32_e64 v168, |v0|, s54
	v_fma_f32 v169, |v0|, s54, -v168
	v_rndne_f32_e32 v170, v168
	v_fma_f32 v169, |v0|, s55, v169
	v_sub_f32_e32 v168, v168, v170
	v_add_f32_e32 v168, v168, v169
	v_exp_f32_e32 v168, v168
	v_cvt_i32_f32_e32 v169, v170
	v_cmp_ngt_f32_e64 s[10:11], |v0|, s56
	v_min_f32_e32 v165, 0, v0
	v_ldexp_f32 v168, v168, v169
	v_cndmask_b32_e64 v168, 0, v168, s[10:11]
	v_cmp_nlt_f32_e64 s[10:11], |v0|, s57
	s_nop 1
	v_cndmask_b32_e64 v0, v197, v168, s[10:11]
	v_add_f32_e32 v170, 1.0, v0
	v_add_f32_e32 v168, -1.0, v170
	v_sub_f32_e32 v169, v168, v170
	v_add_f32_e32 v169, 1.0, v169
	v_sub_f32_e32 v168, v0, v168
	v_add_f32_e32 v171, v168, v169
	v_frexp_mant_f32_e32 v168, v170
	v_cmp_gt_f32_e64 s[10:11], s59, v168
	v_cvt_f64_f32_e32 v[168:169], v170
	v_frexp_exp_i32_f64_e32 v168, v[168:169]
	v_subbrev_co_u32_e64 v168, s[10:11], 0, v168, s[10:11]
	v_sub_u32_e32 v169, 0, v168
	v_ldexp_f32 v170, v170, v169
	v_ldexp_f32 v169, v171, v169
	v_add_f32_e32 v171, -1.0, v170
	v_add_f32_e32 v172, 1.0, v171
	v_sub_f32_e32 v172, v170, v172
	v_add_f32_e32 v172, v169, v172
	v_add_f32_e32 v174, v171, v172
	v_sub_f32_e32 v171, v171, v174
	v_add_f32_e32 v171, v172, v171
	v_add_f32_e32 v172, 1.0, v170
	v_add_f32_e32 v175, -1.0, v172
	v_sub_f32_e32 v170, v170, v175
	v_add_f32_e32 v169, v169, v170
	v_add_f32_e32 v170, v172, v169
	v_sub_f32_e32 v172, v172, v170
	v_add_f32_e32 v169, v169, v172
	v_rcp_f32_e32 v172, v170
	v_cvt_f32_i32_e32 v168, v168
	v_cmp_neq_f32_e64 s[10:11], s58, v0
	v_mul_f32_e32 v175, v174, v172
	v_mul_f32_e32 v176, v170, v175
	v_fma_f32 v177, v175, v170, -v176
	v_fmac_f32_e32 v177, v175, v169
	v_add_f32_e32 v194, v176, v177
	v_sub_f32_e32 v195, v174, v194
	v_sub_f32_e32 v174, v174, v195
	v_sub_f32_e32 v176, v194, v176
	v_sub_f32_e32 v174, v174, v194
	v_add_f32_e32 v171, v171, v174
	v_sub_f32_e32 v174, v176, v177
	v_add_f32_e32 v171, v174, v171
	v_add_f32_e32 v174, v195, v171
	v_mul_f32_e32 v176, v172, v174
	v_mul_f32_e32 v177, v170, v176
	v_fma_f32 v170, v176, v170, -v177
	v_fmac_f32_e32 v170, v176, v169
	v_sub_f32_e32 v169, v195, v174
	v_add_f32_e32 v169, v171, v169
	v_add_f32_e32 v171, v177, v170
	v_sub_f32_e32 v194, v174, v171
	v_sub_f32_e32 v174, v174, v194
	v_sub_f32_e32 v177, v171, v177
	v_sub_f32_e32 v171, v174, v171
	v_add_f32_e32 v169, v169, v171
	v_sub_f32_e32 v170, v177, v170
	v_add_f32_e32 v169, v170, v169
	v_add_f32_e32 v170, v175, v176
	v_add_f32_e32 v169, v194, v169
	v_sub_f32_e32 v171, v170, v175
	v_mul_f32_e32 v169, v172, v169
	v_sub_f32_e32 v171, v176, v171
	v_add_f32_e32 v169, v171, v169
	v_mul_f32_e32 v175, 0x3f317218, v168
	v_add_f32_e32 v171, v170, v169
	v_fma_f32 v176, v168, s60, -v175
	v_mul_f32_e32 v172, v171, v171
	v_fmac_f32_e32 v176, 0xb102e308, v168
	v_sub_f32_e32 v168, v171, v170
	v_fmamk_f32 v174, v172, 0x3e9b6dac, v196
	v_sub_f32_e32 v168, v169, v168
	v_add_f32_e32 v169, v175, v176
	v_fmaak_f32 v174, v172, v174, 0x3f2aaada
	v_sub_f32_e32 v170, v169, v175
	v_ldexp_f32 v175, v171, 1
	v_mul_f32_e32 v171, v171, v172
	v_mul_f32_e32 v171, v171, v174
	v_add_f32_e32 v172, v175, v171
	v_sub_f32_e32 v174, v172, v175
	v_ldexp_f32 v168, v168, 1
	v_sub_f32_e32 v171, v171, v174
	v_add_f32_e32 v168, v168, v171
	v_add_f32_e32 v171, v172, v168
	v_sub_f32_e32 v172, v171, v172
	v_sub_f32_e32 v168, v168, v172
	v_add_f32_e32 v172, v169, v171
	v_sub_f32_e32 v174, v172, v169
	v_sub_f32_e32 v175, v172, v174
	v_sub_f32_e32 v170, v176, v170
	v_sub_f32_e32 v169, v169, v175
	v_sub_f32_e32 v171, v171, v174
	v_add_f32_e32 v169, v171, v169
	v_add_f32_e32 v171, v170, v168
	v_sub_f32_e32 v174, v171, v170
	v_sub_f32_e32 v175, v171, v174
	v_sub_f32_e32 v170, v170, v175
	v_sub_f32_e32 v168, v168, v174
	v_add_f32_e32 v169, v171, v169
	v_add_f32_e32 v168, v168, v170
	v_add_f32_e32 v170, v172, v169
	v_sub_f32_e32 v171, v170, v172
	v_sub_f32_e32 v169, v169, v171
	v_add_f32_e32 v168, v168, v169
	v_add_f32_e32 v168, v170, v168
	v_cndmask_b32_e64 v168, v197, v168, s[10:11]
	v_cmp_lt_f32_e64 s[10:11], |v0|, s61
	s_nop 1
	v_cndmask_b32_e64 v0, v168, v0, s[10:11]
	v_sub_f32_e32 v0, v165, v0
	v_lshl_add_u64 v[168:169], v[166:167], 0, s[2:3]
	global_store_dword v[168:169], v0, off
	global_load_dword v0, v1, s[18:19] offset:20
	s_or_b32 s2, s38, 5
	s_ashr_i32 s3, s2, 31
	s_lshl_b64 s[2:3], s[2:3], 16
	s_waitcnt vmcnt(0)
;   DI void operator()(int tok0, int feat0, f32x16 (&acc)[2][2], int r, int hh) const {
;     ...
;           for (int i = 0; i < 16; ++i) {
;             const float xv = acc[0][mt][i] + bf[i];
;             const float ls = fminf(xv, 0.f) - log1pf(expf(-fabsf(xv)));
;             lf[((size_t)(b * 16 + i)) * SEQ + s] = ls;
;           }
	v_add_f32_e32 v0, v119, v0
	v_mul_f32_e64 v168, |v0|, s54
	v_fma_f32 v169, |v0|, s54, -v168
	v_rndne_f32_e32 v170, v168
	v_fma_f32 v169, |v0|, s55, v169
	v_sub_f32_e32 v168, v168, v170
	v_add_f32_e32 v168, v168, v169
	v_exp_f32_e32 v168, v168
	v_cvt_i32_f32_e32 v169, v170
	v_cmp_ngt_f32_e64 s[10:11], |v0|, s56
	v_min_f32_e32 v165, 0, v0
	v_ldexp_f32 v168, v168, v169
	v_cndmask_b32_e64 v168, 0, v168, s[10:11]
	v_cmp_nlt_f32_e64 s[10:11], |v0|, s57
	s_nop 1
	v_cndmask_b32_e64 v0, v197, v168, s[10:11]
	v_add_f32_e32 v170, 1.0, v0
	v_add_f32_e32 v168, -1.0, v170
	v_sub_f32_e32 v169, v168, v170
	v_add_f32_e32 v169, 1.0, v169
	v_sub_f32_e32 v168, v0, v168
	v_add_f32_e32 v171, v168, v169
	v_frexp_mant_f32_e32 v168, v170
	v_cmp_gt_f32_e64 s[10:11], s59, v168
	v_cvt_f64_f32_e32 v[168:169], v170
	v_frexp_exp_i32_f64_e32 v168, v[168:169]
	v_subbrev_co_u32_e64 v168, s[10:11], 0, v168, s[10:11]
	v_sub_u32_e32 v169, 0, v168
	v_ldexp_f32 v170, v170, v169
	v_ldexp_f32 v169, v171, v169
	v_add_f32_e32 v171, -1.0, v170
	v_add_f32_e32 v172, 1.0, v171
	v_sub_f32_e32 v172, v170, v172
	v_add_f32_e32 v172, v169, v172
	v_add_f32_e32 v174, v171, v172
	v_sub_f32_e32 v171, v171, v174
	v_add_f32_e32 v171, v172, v171
	v_add_f32_e32 v172, 1.0, v170
	v_add_f32_e32 v175, -1.0, v172
	v_sub_f32_e32 v170, v170, v175
	v_add_f32_e32 v169, v169, v170
	v_add_f32_e32 v170, v172, v169
	v_sub_f32_e32 v172, v172, v170
	v_add_f32_e32 v169, v169, v172
	v_rcp_f32_e32 v172, v170
	v_cvt_f32_i32_e32 v168, v168
	v_cmp_neq_f32_e64 s[10:11], s58, v0
	v_mul_f32_e32 v175, v174, v172
	v_mul_f32_e32 v176, v170, v175
	v_fma_f32 v177, v175, v170, -v176
	v_fmac_f32_e32 v177, v175, v169
	v_add_f32_e32 v194, v176, v177
	v_sub_f32_e32 v195, v174, v194
	v_sub_f32_e32 v174, v174, v195
	v_sub_f32_e32 v176, v194, v176
	v_sub_f32_e32 v174, v174, v194
	v_add_f32_e32 v171, v171, v174
	v_sub_f32_e32 v174, v176, v177
	v_add_f32_e32 v171, v174, v171
	v_add_f32_e32 v174, v195, v171
	v_mul_f32_e32 v176, v172, v174
	v_mul_f32_e32 v177, v170, v176
	v_fma_f32 v170, v176, v170, -v177
	v_fmac_f32_e32 v170, v176, v169
	v_sub_f32_e32 v169, v195, v174
	v_add_f32_e32 v169, v171, v169
	v_add_f32_e32 v171, v177, v170
	v_sub_f32_e32 v194, v174, v171
	v_sub_f32_e32 v174, v174, v194
	v_sub_f32_e32 v177, v171, v177
	v_sub_f32_e32 v171, v174, v171
	v_add_f32_e32 v169, v169, v171
	v_sub_f32_e32 v170, v177, v170
	v_add_f32_e32 v169, v170, v169
	v_add_f32_e32 v170, v175, v176
	v_add_f32_e32 v169, v194, v169
	v_sub_f32_e32 v171, v170, v175
	v_mul_f32_e32 v169, v172, v169
	v_sub_f32_e32 v171, v176, v171
	v_add_f32_e32 v169, v171, v169
	v_mul_f32_e32 v175, 0x3f317218, v168
	v_add_f32_e32 v171, v170, v169
	v_fma_f32 v176, v168, s60, -v175
	v_mul_f32_e32 v172, v171, v171
	v_fmac_f32_e32 v176, 0xb102e308, v168
	v_sub_f32_e32 v168, v171, v170
	v_fmamk_f32 v174, v172, 0x3e9b6dac, v196
	v_sub_f32_e32 v168, v169, v168
	v_add_f32_e32 v169, v175, v176
	v_fmaak_f32 v174, v172, v174, 0x3f2aaada
	v_sub_f32_e32 v170, v169, v175
	v_ldexp_f32 v175, v171, 1
	v_mul_f32_e32 v171, v171, v172
	v_mul_f32_e32 v171, v171, v174
	v_add_f32_e32 v172, v175, v171
	v_sub_f32_e32 v174, v172, v175
	v_ldexp_f32 v168, v168, 1
	v_sub_f32_e32 v171, v171, v174
	v_add_f32_e32 v168, v168, v171
	v_add_f32_e32 v171, v172, v168
	v_sub_f32_e32 v172, v171, v172
	v_sub_f32_e32 v168, v168, v172
	v_add_f32_e32 v172, v169, v171
	v_sub_f32_e32 v174, v172, v169
	v_sub_f32_e32 v175, v172, v174
	v_sub_f32_e32 v170, v176, v170
	v_sub_f32_e32 v169, v169, v175
	v_sub_f32_e32 v171, v171, v174
	v_add_f32_e32 v169, v171, v169
	v_add_f32_e32 v171, v170, v168
	v_sub_f32_e32 v174, v171, v170
	v_sub_f32_e32 v175, v171, v174
	v_sub_f32_e32 v170, v170, v175
	v_sub_f32_e32 v168, v168, v174
	v_add_f32_e32 v169, v171, v169
	v_add_f32_e32 v168, v168, v170
	v_add_f32_e32 v170, v172, v169
	v_sub_f32_e32 v171, v170, v172
	v_sub_f32_e32 v169, v169, v171
	v_add_f32_e32 v168, v168, v169
	v_add_f32_e32 v168, v170, v168
	v_cndmask_b32_e64 v168, v197, v168, s[10:11]
	v_cmp_lt_f32_e64 s[10:11], |v0|, s61
	s_nop 1
	v_cndmask_b32_e64 v0, v168, v0, s[10:11]
	v_sub_f32_e32 v0, v165, v0
	v_lshl_add_u64 v[168:169], v[166:167], 0, s[2:3]
	global_store_dword v[168:169], v0, off
	global_load_dword v0, v1, s[18:19] offset:24
	s_or_b32 s2, s38, 6
	s_ashr_i32 s3, s2, 31
	s_lshl_b64 s[2:3], s[2:3], 16
	s_waitcnt vmcnt(0)
;   DI void operator()(int tok0, int feat0, f32x16 (&acc)[2][2], int r, int hh) const {
;     ...
;           for (int i = 0; i < 16; ++i) {
;             const float xv = acc[0][mt][i] + bf[i];
;             const float ls = fminf(xv, 0.f) - log1pf(expf(-fabsf(xv)));
;             lf[((size_t)(b * 16 + i)) * SEQ + s] = ls;
;           }
	v_add_f32_e32 v0, v120, v0
	v_mul_f32_e64 v168, |v0|, s54
	v_fma_f32 v169, |v0|, s54, -v168
	v_rndne_f32_e32 v170, v168
	v_fma_f32 v169, |v0|, s55, v169
	v_sub_f32_e32 v168, v168, v170
	v_add_f32_e32 v168, v168, v169
	v_exp_f32_e32 v168, v168
	v_cvt_i32_f32_e32 v169, v170
	v_cmp_ngt_f32_e64 s[10:11], |v0|, s56
	v_min_f32_e32 v165, 0, v0
	v_ldexp_f32 v168, v168, v169
	v_cndmask_b32_e64 v168, 0, v168, s[10:11]
	v_cmp_nlt_f32_e64 s[10:11], |v0|, s57
	s_nop 1
	v_cndmask_b32_e64 v0, v197, v168, s[10:11]
	v_add_f32_e32 v170, 1.0, v0
	v_add_f32_e32 v168, -1.0, v170
	v_sub_f32_e32 v169, v168, v170
	v_add_f32_e32 v169, 1.0, v169
	v_sub_f32_e32 v168, v0, v168
	v_add_f32_e32 v171, v168, v169
	v_frexp_mant_f32_e32 v168, v170
	v_cmp_gt_f32_e64 s[10:11], s59, v168
	v_cvt_f64_f32_e32 v[168:169], v170
	v_frexp_exp_i32_f64_e32 v168, v[168:169]
	v_subbrev_co_u32_e64 v168, s[10:11], 0, v168, s[10:11]
	v_sub_u32_e32 v169, 0, v168
	v_ldexp_f32 v170, v170, v169
	v_ldexp_f32 v169, v171, v169
	v_add_f32_e32 v171, -1.0, v170
	v_add_f32_e32 v172, 1.0, v171
	v_sub_f32_e32 v172, v170, v172
	v_add_f32_e32 v172, v169, v172
	v_add_f32_e32 v174, v171, v172
	v_sub_f32_e32 v171, v171, v174
	v_add_f32_e32 v171, v172, v171
	v_add_f32_e32 v172, 1.0, v170
	v_add_f32_e32 v175, -1.0, v172
	v_sub_f32_e32 v170, v170, v175
	v_add_f32_e32 v169, v169, v170
	v_add_f32_e32 v170, v172, v169
	v_sub_f32_e32 v172, v172, v170
	v_add_f32_e32 v169, v169, v172
	v_rcp_f32_e32 v172, v170
	v_cvt_f32_i32_e32 v168, v168
	v_cmp_neq_f32_e64 s[10:11], s58, v0
	v_mul_f32_e32 v175, v174, v172
	v_mul_f32_e32 v176, v170, v175
	v_fma_f32 v177, v175, v170, -v176
	v_fmac_f32_e32 v177, v175, v169
	v_add_f32_e32 v194, v176, v177
	v_sub_f32_e32 v195, v174, v194
	v_sub_f32_e32 v174, v174, v195
	v_sub_f32_e32 v176, v194, v176
	v_sub_f32_e32 v174, v174, v194
	v_add_f32_e32 v171, v171, v174
	v_sub_f32_e32 v174, v176, v177
	v_add_f32_e32 v171, v174, v171
	v_add_f32_e32 v174, v195, v171
	v_mul_f32_e32 v176, v172, v174
	v_mul_f32_e32 v177, v170, v176
	v_fma_f32 v170, v176, v170, -v177
	v_fmac_f32_e32 v170, v176, v169
	v_sub_f32_e32 v169, v195, v174
	v_add_f32_e32 v169, v171, v169
	v_add_f32_e32 v171, v177, v170
	v_sub_f32_e32 v194, v174, v171
	v_sub_f32_e32 v174, v174, v194
	v_sub_f32_e32 v177, v171, v177
	v_sub_f32_e32 v171, v174, v171
	v_add_f32_e32 v169, v169, v171
	v_sub_f32_e32 v170, v177, v170
	v_add_f32_e32 v169, v170, v169
	v_add_f32_e32 v170, v175, v176
	v_add_f32_e32 v169, v194, v169
	v_sub_f32_e32 v171, v170, v175
	v_mul_f32_e32 v169, v172, v169
	v_sub_f32_e32 v171, v176, v171
	v_add_f32_e32 v169, v171, v169
	v_mul_f32_e32 v175, 0x3f317218, v168
	v_add_f32_e32 v171, v170, v169
	v_fma_f32 v176, v168, s60, -v175
	v_mul_f32_e32 v172, v171, v171
	v_fmac_f32_e32 v176, 0xb102e308, v168
	v_sub_f32_e32 v168, v171, v170
	v_fmamk_f32 v174, v172, 0x3e9b6dac, v196
	v_sub_f32_e32 v168, v169, v168
	v_add_f32_e32 v169, v175, v176
	v_fmaak_f32 v174, v172, v174, 0x3f2aaada
	v_sub_f32_e32 v170, v169, v175
	v_ldexp_f32 v175, v171, 1
	v_mul_f32_e32 v171, v171, v172
	v_mul_f32_e32 v171, v171, v174
	v_add_f32_e32 v172, v175, v171
	v_sub_f32_e32 v174, v172, v175
	v_ldexp_f32 v168, v168, 1
	v_sub_f32_e32 v171, v171, v174
	v_add_f32_e32 v168, v168, v171
	v_add_f32_e32 v171, v172, v168
	v_sub_f32_e32 v172, v171, v172
	v_sub_f32_e32 v168, v168, v172
	v_add_f32_e32 v172, v169, v171
	v_sub_f32_e32 v174, v172, v169
	v_sub_f32_e32 v175, v172, v174
	v_sub_f32_e32 v170, v176, v170
	v_sub_f32_e32 v169, v169, v175
	v_sub_f32_e32 v171, v171, v174
	v_add_f32_e32 v169, v171, v169
	v_add_f32_e32 v171, v170, v168
	v_sub_f32_e32 v174, v171, v170
	v_sub_f32_e32 v175, v171, v174
	v_sub_f32_e32 v170, v170, v175
	v_sub_f32_e32 v168, v168, v174
	v_add_f32_e32 v169, v171, v169
	v_add_f32_e32 v168, v168, v170
	v_add_f32_e32 v170, v172, v169
	v_sub_f32_e32 v171, v170, v172
	v_sub_f32_e32 v169, v169, v171
	v_add_f32_e32 v168, v168, v169
	v_add_f32_e32 v168, v170, v168
	v_cndmask_b32_e64 v168, v197, v168, s[10:11]
	v_cmp_lt_f32_e64 s[10:11], |v0|, s61
	s_nop 1
	v_cndmask_b32_e64 v0, v168, v0, s[10:11]
	v_sub_f32_e32 v0, v165, v0
	v_lshl_add_u64 v[168:169], v[166:167], 0, s[2:3]
	global_store_dword v[168:169], v0, off
	global_load_dword v0, v1, s[18:19] offset:28
	s_or_b32 s2, s38, 7
	s_ashr_i32 s3, s2, 31
	s_lshl_b64 s[2:3], s[2:3], 16
	s_waitcnt vmcnt(0)
;   DI void operator()(int tok0, int feat0, f32x16 (&acc)[2][2], int r, int hh) const {
;     ...
;           for (int i = 0; i < 16; ++i) {
;             const float xv = acc[0][mt][i] + bf[i];
;             const float ls = fminf(xv, 0.f) - log1pf(expf(-fabsf(xv)));
;             lf[((size_t)(b * 16 + i)) * SEQ + s] = ls;
;           }
	v_add_f32_e32 v0, v121, v0
	v_mul_f32_e64 v168, |v0|, s54
	v_fma_f32 v169, |v0|, s54, -v168
	v_rndne_f32_e32 v170, v168
	v_fma_f32 v169, |v0|, s55, v169
	v_sub_f32_e32 v168, v168, v170
	v_add_f32_e32 v168, v168, v169
	v_exp_f32_e32 v168, v168
	v_cvt_i32_f32_e32 v169, v170
	v_cmp_ngt_f32_e64 s[10:11], |v0|, s56
	v_min_f32_e32 v165, 0, v0
	v_ldexp_f32 v168, v168, v169
	v_cndmask_b32_e64 v168, 0, v168, s[10:11]
	v_cmp_nlt_f32_e64 s[10:11], |v0|, s57
	s_nop 1
	v_cndmask_b32_e64 v0, v197, v168, s[10:11]
	v_add_f32_e32 v170, 1.0, v0
	v_add_f32_e32 v168, -1.0, v170
	v_sub_f32_e32 v169, v168, v170
	v_add_f32_e32 v169, 1.0, v169
	v_sub_f32_e32 v168, v0, v168
	v_add_f32_e32 v171, v168, v169
	v_frexp_mant_f32_e32 v168, v170
	v_cmp_gt_f32_e64 s[10:11], s59, v168
	v_cvt_f64_f32_e32 v[168:169], v170
	v_frexp_exp_i32_f64_e32 v168, v[168:169]
	v_subbrev_co_u32_e64 v168, s[10:11], 0, v168, s[10:11]
	v_sub_u32_e32 v169, 0, v168
	v_ldexp_f32 v170, v170, v169
	v_ldexp_f32 v169, v171, v169
	v_add_f32_e32 v171, -1.0, v170
	v_add_f32_e32 v172, 1.0, v171
	v_sub_f32_e32 v172, v170, v172
	v_add_f32_e32 v172, v169, v172
	v_add_f32_e32 v174, v171, v172
	v_sub_f32_e32 v171, v171, v174
	v_add_f32_e32 v171, v172, v171
	v_add_f32_e32 v172, 1.0, v170
	v_add_f32_e32 v175, -1.0, v172
	v_sub_f32_e32 v170, v170, v175
	v_add_f32_e32 v169, v169, v170
	v_add_f32_e32 v170, v172, v169
	v_sub_f32_e32 v172, v172, v170
	v_add_f32_e32 v169, v169, v172
	v_rcp_f32_e32 v172, v170
	v_cvt_f32_i32_e32 v168, v168
	v_cmp_neq_f32_e64 s[10:11], s58, v0
	v_mul_f32_e32 v175, v174, v172
	v_mul_f32_e32 v176, v170, v175
	v_fma_f32 v177, v175, v170, -v176
	v_fmac_f32_e32 v177, v175, v169
	v_add_f32_e32 v194, v176, v177
	v_sub_f32_e32 v195, v174, v194
	v_sub_f32_e32 v174, v174, v195
	v_sub_f32_e32 v176, v194, v176
	v_sub_f32_e32 v174, v174, v194
	v_add_f32_e32 v171, v171, v174
	v_sub_f32_e32 v174, v176, v177
	v_add_f32_e32 v171, v174, v171
	v_add_f32_e32 v174, v195, v171
	v_mul_f32_e32 v176, v172, v174
	v_mul_f32_e32 v177, v170, v176
	v_fma_f32 v170, v176, v170, -v177
	v_fmac_f32_e32 v170, v176, v169
	v_sub_f32_e32 v169, v195, v174
	v_add_f32_e32 v169, v171, v169
	v_add_f32_e32 v171, v177, v170
	v_sub_f32_e32 v194, v174, v171
	v_sub_f32_e32 v174, v174, v194
	v_sub_f32_e32 v177, v171, v177
	v_sub_f32_e32 v171, v174, v171
	v_add_f32_e32 v169, v169, v171
	v_sub_f32_e32 v170, v177, v170
	v_add_f32_e32 v169, v170, v169
	v_add_f32_e32 v170, v175, v176
	v_add_f32_e32 v169, v194, v169
	v_sub_f32_e32 v171, v170, v175
	v_mul_f32_e32 v169, v172, v169
	v_sub_f32_e32 v171, v176, v171
	v_add_f32_e32 v169, v171, v169
	v_mul_f32_e32 v175, 0x3f317218, v168
	v_add_f32_e32 v171, v170, v169
	v_fma_f32 v176, v168, s60, -v175
	v_mul_f32_e32 v172, v171, v171
	v_fmac_f32_e32 v176, 0xb102e308, v168
	v_sub_f32_e32 v168, v171, v170
	v_fmamk_f32 v174, v172, 0x3e9b6dac, v196
	v_sub_f32_e32 v168, v169, v168
	v_add_f32_e32 v169, v175, v176
	v_fmaak_f32 v174, v172, v174, 0x3f2aaada
	v_sub_f32_e32 v170, v169, v175
	v_ldexp_f32 v175, v171, 1
	v_mul_f32_e32 v171, v171, v172
	v_mul_f32_e32 v171, v171, v174
	v_add_f32_e32 v172, v175, v171
	v_sub_f32_e32 v174, v172, v175
	v_ldexp_f32 v168, v168, 1
	v_sub_f32_e32 v171, v171, v174
	v_add_f32_e32 v168, v168, v171
	v_add_f32_e32 v171, v172, v168
	v_sub_f32_e32 v172, v171, v172
	v_sub_f32_e32 v168, v168, v172
	v_add_f32_e32 v172, v169, v171
	v_sub_f32_e32 v174, v172, v169
	v_sub_f32_e32 v175, v172, v174
	v_sub_f32_e32 v170, v176, v170
	v_sub_f32_e32 v169, v169, v175
	v_sub_f32_e32 v171, v171, v174
	v_add_f32_e32 v169, v171, v169
	v_add_f32_e32 v171, v170, v168
	v_sub_f32_e32 v174, v171, v170
	v_sub_f32_e32 v175, v171, v174
	v_sub_f32_e32 v170, v170, v175
	v_sub_f32_e32 v168, v168, v174
	v_add_f32_e32 v169, v171, v169
	v_add_f32_e32 v168, v168, v170
	v_add_f32_e32 v170, v172, v169
	v_sub_f32_e32 v171, v170, v172
	v_sub_f32_e32 v169, v169, v171
	v_add_f32_e32 v168, v168, v169
	v_add_f32_e32 v168, v170, v168
	v_cndmask_b32_e64 v168, v197, v168, s[10:11]
	v_cmp_lt_f32_e64 s[10:11], |v0|, s61
	s_nop 1
	v_cndmask_b32_e64 v0, v168, v0, s[10:11]
	v_sub_f32_e32 v0, v165, v0
	v_lshl_add_u64 v[168:169], v[166:167], 0, s[2:3]
	global_store_dword v[168:169], v0, off
	global_load_dword v0, v1, s[18:19] offset:32
	s_or_b32 s2, s38, 8
	s_ashr_i32 s3, s2, 31
	s_lshl_b64 s[2:3], s[2:3], 16
	s_waitcnt vmcnt(0)
;   DI void operator()(int tok0, int feat0, f32x16 (&acc)[2][2], int r, int hh) const {
;     ...
;           for (int i = 0; i < 16; ++i) {
;             const float xv = acc[0][mt][i] + bf[i];
;             const float ls = fminf(xv, 0.f) - log1pf(expf(-fabsf(xv)));
;             lf[((size_t)(b * 16 + i)) * SEQ + s] = ls;
;           }
	v_add_f32_e32 v0, v122, v0
	v_mul_f32_e64 v168, |v0|, s54
	v_fma_f32 v169, |v0|, s54, -v168
	v_rndne_f32_e32 v170, v168
	v_fma_f32 v169, |v0|, s55, v169
	v_sub_f32_e32 v168, v168, v170
	v_add_f32_e32 v168, v168, v169
	v_exp_f32_e32 v168, v168
	v_cvt_i32_f32_e32 v169, v170
	v_cmp_ngt_f32_e64 s[10:11], |v0|, s56
	v_min_f32_e32 v165, 0, v0
	v_ldexp_f32 v168, v168, v169
	v_cndmask_b32_e64 v168, 0, v168, s[10:11]
	v_cmp_nlt_f32_e64 s[10:11], |v0|, s57
	s_nop 1
	v_cndmask_b32_e64 v0, v197, v168, s[10:11]
	v_add_f32_e32 v170, 1.0, v0
	v_add_f32_e32 v168, -1.0, v170
	v_sub_f32_e32 v169, v168, v170
	v_add_f32_e32 v169, 1.0, v169
	v_sub_f32_e32 v168, v0, v168
	v_add_f32_e32 v171, v168, v169
	v_frexp_mant_f32_e32 v168, v170
	v_cmp_gt_f32_e64 s[10:11], s59, v168
	v_cvt_f64_f32_e32 v[168:169], v170
	v_frexp_exp_i32_f64_e32 v168, v[168:169]
	v_subbrev_co_u32_e64 v168, s[10:11], 0, v168, s[10:11]
	v_sub_u32_e32 v169, 0, v168
	v_ldexp_f32 v170, v170, v169
	v_ldexp_f32 v169, v171, v169
	v_add_f32_e32 v171, -1.0, v170
	v_add_f32_e32 v172, 1.0, v171
	v_sub_f32_e32 v172, v170, v172
	v_add_f32_e32 v172, v169, v172
	v_add_f32_e32 v174, v171, v172
	v_sub_f32_e32 v171, v171, v174
	v_add_f32_e32 v171, v172, v171
	v_add_f32_e32 v172, 1.0, v170
	v_add_f32_e32 v175, -1.0, v172
	v_sub_f32_e32 v170, v170, v175
	v_add_f32_e32 v169, v169, v170
	v_add_f32_e32 v170, v172, v169
	v_sub_f32_e32 v172, v172, v170
	v_add_f32_e32 v169, v169, v172
	v_rcp_f32_e32 v172, v170
	v_cvt_f32_i32_e32 v168, v168
	v_cmp_neq_f32_e64 s[10:11], s58, v0
	v_mul_f32_e32 v175, v174, v172
	v_mul_f32_e32 v176, v170, v175
	v_fma_f32 v177, v175, v170, -v176
	v_fmac_f32_e32 v177, v175, v169
	v_add_f32_e32 v194, v176, v177
	v_sub_f32_e32 v195, v174, v194
	v_sub_f32_e32 v174, v174, v195
	v_sub_f32_e32 v176, v194, v176
	v_sub_f32_e32 v174, v174, v194
	v_add_f32_e32 v171, v171, v174
	v_sub_f32_e32 v174, v176, v177
	v_add_f32_e32 v171, v174, v171
	v_add_f32_e32 v174, v195, v171
	v_mul_f32_e32 v176, v172, v174
	v_mul_f32_e32 v177, v170, v176
	v_fma_f32 v170, v176, v170, -v177
	v_fmac_f32_e32 v170, v176, v169
	v_sub_f32_e32 v169, v195, v174
	v_add_f32_e32 v169, v171, v169
	v_add_f32_e32 v171, v177, v170
	v_sub_f32_e32 v194, v174, v171
	v_sub_f32_e32 v174, v174, v194
	v_sub_f32_e32 v177, v171, v177
	v_sub_f32_e32 v171, v174, v171
	v_add_f32_e32 v169, v169, v171
	v_sub_f32_e32 v170, v177, v170
	v_add_f32_e32 v169, v170, v169
	v_add_f32_e32 v170, v175, v176
	v_add_f32_e32 v169, v194, v169
	v_sub_f32_e32 v171, v170, v175
	v_mul_f32_e32 v169, v172, v169
	v_sub_f32_e32 v171, v176, v171
	v_add_f32_e32 v169, v171, v169
	v_mul_f32_e32 v175, 0x3f317218, v168
	v_add_f32_e32 v171, v170, v169
	v_fma_f32 v176, v168, s60, -v175
	v_mul_f32_e32 v172, v171, v171
	v_fmac_f32_e32 v176, 0xb102e308, v168
	v_sub_f32_e32 v168, v171, v170
	v_fmamk_f32 v174, v172, 0x3e9b6dac, v196
	v_sub_f32_e32 v168, v169, v168
	v_add_f32_e32 v169, v175, v176
	v_fmaak_f32 v174, v172, v174, 0x3f2aaada
	v_sub_f32_e32 v170, v169, v175
	v_ldexp_f32 v175, v171, 1
	v_mul_f32_e32 v171, v171, v172
	v_mul_f32_e32 v171, v171, v174
	v_add_f32_e32 v172, v175, v171
	v_sub_f32_e32 v174, v172, v175
	v_ldexp_f32 v168, v168, 1
	v_sub_f32_e32 v171, v171, v174
	v_add_f32_e32 v168, v168, v171
	v_add_f32_e32 v171, v172, v168
	v_sub_f32_e32 v172, v171, v172
	v_sub_f32_e32 v168, v168, v172
	v_add_f32_e32 v172, v169, v171
	v_sub_f32_e32 v174, v172, v169
	v_sub_f32_e32 v175, v172, v174
	v_sub_f32_e32 v170, v176, v170
	v_sub_f32_e32 v169, v169, v175
	v_sub_f32_e32 v171, v171, v174
	v_add_f32_e32 v169, v171, v169
	v_add_f32_e32 v171, v170, v168
	v_sub_f32_e32 v174, v171, v170
	v_sub_f32_e32 v175, v171, v174
	v_sub_f32_e32 v170, v170, v175
	v_sub_f32_e32 v168, v168, v174
	v_add_f32_e32 v169, v171, v169
	v_add_f32_e32 v168, v168, v170
	v_add_f32_e32 v170, v172, v169
	v_sub_f32_e32 v171, v170, v172
	v_sub_f32_e32 v169, v169, v171
	v_add_f32_e32 v168, v168, v169
	v_add_f32_e32 v168, v170, v168
	v_cndmask_b32_e64 v168, v197, v168, s[10:11]
	v_cmp_lt_f32_e64 s[10:11], |v0|, s61
	s_nop 1
	v_cndmask_b32_e64 v0, v168, v0, s[10:11]
	v_sub_f32_e32 v0, v165, v0
	v_lshl_add_u64 v[168:169], v[166:167], 0, s[2:3]
	global_store_dword v[168:169], v0, off
	global_load_dword v0, v1, s[18:19] offset:36
	s_or_b32 s2, s38, 9
	s_ashr_i32 s3, s2, 31
	s_lshl_b64 s[2:3], s[2:3], 16
	s_waitcnt vmcnt(0)
;   DI void operator()(int tok0, int feat0, f32x16 (&acc)[2][2], int r, int hh) const {
;     ...
;           for (int i = 0; i < 16; ++i) {
;             const float xv = acc[0][mt][i] + bf[i];
;             const float ls = fminf(xv, 0.f) - log1pf(expf(-fabsf(xv)));
;             lf[((size_t)(b * 16 + i)) * SEQ + s] = ls;
;           }
	v_add_f32_e32 v0, v123, v0
	v_mul_f32_e64 v168, |v0|, s54
	v_fma_f32 v169, |v0|, s54, -v168
	v_rndne_f32_e32 v170, v168
	v_fma_f32 v169, |v0|, s55, v169
	v_sub_f32_e32 v168, v168, v170
	v_add_f32_e32 v168, v168, v169
	v_exp_f32_e32 v168, v168
	v_cvt_i32_f32_e32 v169, v170
	v_cmp_ngt_f32_e64 s[10:11], |v0|, s56
	v_min_f32_e32 v165, 0, v0
	v_ldexp_f32 v168, v168, v169
	v_cndmask_b32_e64 v168, 0, v168, s[10:11]
	v_cmp_nlt_f32_e64 s[10:11], |v0|, s57
	s_nop 1
	v_cndmask_b32_e64 v0, v197, v168, s[10:11]
	v_add_f32_e32 v170, 1.0, v0
	v_add_f32_e32 v168, -1.0, v170
	v_sub_f32_e32 v169, v168, v170
	v_add_f32_e32 v169, 1.0, v169
	v_sub_f32_e32 v168, v0, v168
	v_add_f32_e32 v171, v168, v169
	v_frexp_mant_f32_e32 v168, v170
	v_cmp_gt_f32_e64 s[10:11], s59, v168
	v_cvt_f64_f32_e32 v[168:169], v170
	v_frexp_exp_i32_f64_e32 v168, v[168:169]
	v_subbrev_co_u32_e64 v168, s[10:11], 0, v168, s[10:11]
	v_sub_u32_e32 v169, 0, v168
	v_ldexp_f32 v170, v170, v169
	v_ldexp_f32 v169, v171, v169
	v_add_f32_e32 v171, -1.0, v170
	v_add_f32_e32 v172, 1.0, v171
	v_sub_f32_e32 v172, v170, v172
	v_add_f32_e32 v172, v169, v172
	v_add_f32_e32 v174, v171, v172
	v_sub_f32_e32 v171, v171, v174
	v_add_f32_e32 v171, v172, v171
	v_add_f32_e32 v172, 1.0, v170
	v_add_f32_e32 v175, -1.0, v172
	v_sub_f32_e32 v170, v170, v175
	v_add_f32_e32 v169, v169, v170
	v_add_f32_e32 v170, v172, v169
	v_sub_f32_e32 v172, v172, v170
	v_add_f32_e32 v169, v169, v172
	v_rcp_f32_e32 v172, v170
	v_cvt_f32_i32_e32 v168, v168
	v_cmp_neq_f32_e64 s[10:11], s58, v0
	v_mul_f32_e32 v175, v174, v172
	v_mul_f32_e32 v176, v170, v175
	v_fma_f32 v177, v175, v170, -v176
	v_fmac_f32_e32 v177, v175, v169
	v_add_f32_e32 v194, v176, v177
	v_sub_f32_e32 v195, v174, v194
	v_sub_f32_e32 v174, v174, v195
	v_sub_f32_e32 v176, v194, v176
	v_sub_f32_e32 v174, v174, v194
	v_add_f32_e32 v171, v171, v174
	v_sub_f32_e32 v174, v176, v177
	v_add_f32_e32 v171, v174, v171
	v_add_f32_e32 v174, v195, v171
	v_mul_f32_e32 v176, v172, v174
	v_mul_f32_e32 v177, v170, v176
	v_fma_f32 v170, v176, v170, -v177
	v_fmac_f32_e32 v170, v176, v169
	v_sub_f32_e32 v169, v195, v174
	v_add_f32_e32 v169, v171, v169
	v_add_f32_e32 v171, v177, v170
	v_sub_f32_e32 v194, v174, v171
	v_sub_f32_e32 v174, v174, v194
	v_sub_f32_e32 v177, v171, v177
	v_sub_f32_e32 v171, v174, v171
	v_add_f32_e32 v169, v169, v171
	v_sub_f32_e32 v170, v177, v170
	v_add_f32_e32 v169, v170, v169
	v_add_f32_e32 v170, v175, v176
	v_add_f32_e32 v169, v194, v169
	v_sub_f32_e32 v171, v170, v175
	v_mul_f32_e32 v169, v172, v169
	v_sub_f32_e32 v171, v176, v171
	v_add_f32_e32 v169, v171, v169
	v_mul_f32_e32 v175, 0x3f317218, v168
	v_add_f32_e32 v171, v170, v169
	v_fma_f32 v176, v168, s60, -v175
	v_mul_f32_e32 v172, v171, v171
	v_fmac_f32_e32 v176, 0xb102e308, v168
	v_sub_f32_e32 v168, v171, v170
	v_fmamk_f32 v174, v172, 0x3e9b6dac, v196
	v_sub_f32_e32 v168, v169, v168
	v_add_f32_e32 v169, v175, v176
	v_fmaak_f32 v174, v172, v174, 0x3f2aaada
	v_sub_f32_e32 v170, v169, v175
	v_ldexp_f32 v175, v171, 1
	v_mul_f32_e32 v171, v171, v172
	v_mul_f32_e32 v171, v171, v174
	v_add_f32_e32 v172, v175, v171
	v_sub_f32_e32 v174, v172, v175
	v_ldexp_f32 v168, v168, 1
	v_sub_f32_e32 v171, v171, v174
	v_add_f32_e32 v168, v168, v171
	v_add_f32_e32 v171, v172, v168
	v_sub_f32_e32 v172, v171, v172
	v_sub_f32_e32 v168, v168, v172
	v_add_f32_e32 v172, v169, v171
	v_sub_f32_e32 v174, v172, v169
	v_sub_f32_e32 v175, v172, v174
	v_sub_f32_e32 v170, v176, v170
	v_sub_f32_e32 v169, v169, v175
	v_sub_f32_e32 v171, v171, v174
	v_add_f32_e32 v169, v171, v169
	v_add_f32_e32 v171, v170, v168
	v_sub_f32_e32 v174, v171, v170
	v_sub_f32_e32 v175, v171, v174
	v_sub_f32_e32 v170, v170, v175
	v_sub_f32_e32 v168, v168, v174
	v_add_f32_e32 v169, v171, v169
	v_add_f32_e32 v168, v168, v170
	v_add_f32_e32 v170, v172, v169
	v_sub_f32_e32 v171, v170, v172
	v_sub_f32_e32 v169, v169, v171
	v_add_f32_e32 v168, v168, v169
	v_add_f32_e32 v168, v170, v168
	v_cndmask_b32_e64 v168, v197, v168, s[10:11]
	v_cmp_lt_f32_e64 s[10:11], |v0|, s61
	s_nop 1
	v_cndmask_b32_e64 v0, v168, v0, s[10:11]
	v_sub_f32_e32 v0, v165, v0
	v_lshl_add_u64 v[168:169], v[166:167], 0, s[2:3]
	global_store_dword v[168:169], v0, off
	global_load_dword v0, v1, s[18:19] offset:40
	s_or_b32 s2, s38, 10
	s_ashr_i32 s3, s2, 31
	s_lshl_b64 s[2:3], s[2:3], 16
	s_waitcnt vmcnt(0)
;   DI void operator()(int tok0, int feat0, f32x16 (&acc)[2][2], int r, int hh) const {
;     ...
;           for (int i = 0; i < 16; ++i) {
;             const float xv = acc[0][mt][i] + bf[i];
;             const float ls = fminf(xv, 0.f) - log1pf(expf(-fabsf(xv)));
;             lf[((size_t)(b * 16 + i)) * SEQ + s] = ls;
;           }
	v_add_f32_e32 v0, v124, v0
	v_mul_f32_e64 v168, |v0|, s54
	v_fma_f32 v169, |v0|, s54, -v168
	v_rndne_f32_e32 v170, v168
	v_fma_f32 v169, |v0|, s55, v169
	v_sub_f32_e32 v168, v168, v170
	v_add_f32_e32 v168, v168, v169
	v_exp_f32_e32 v168, v168
	v_cvt_i32_f32_e32 v169, v170
	v_cmp_ngt_f32_e64 s[10:11], |v0|, s56
	v_min_f32_e32 v165, 0, v0
	v_ldexp_f32 v168, v168, v169
	v_cndmask_b32_e64 v168, 0, v168, s[10:11]
	v_cmp_nlt_f32_e64 s[10:11], |v0|, s57
	s_nop 1
	v_cndmask_b32_e64 v0, v197, v168, s[10:11]
	v_add_f32_e32 v170, 1.0, v0
	v_add_f32_e32 v168, -1.0, v170
	v_sub_f32_e32 v169, v168, v170
	v_add_f32_e32 v169, 1.0, v169
	v_sub_f32_e32 v168, v0, v168
	v_add_f32_e32 v171, v168, v169
	v_frexp_mant_f32_e32 v168, v170
	v_cmp_gt_f32_e64 s[10:11], s59, v168
	v_cvt_f64_f32_e32 v[168:169], v170
	v_frexp_exp_i32_f64_e32 v168, v[168:169]
	v_subbrev_co_u32_e64 v168, s[10:11], 0, v168, s[10:11]
	v_sub_u32_e32 v169, 0, v168
	v_ldexp_f32 v170, v170, v169
	v_ldexp_f32 v169, v171, v169
	v_add_f32_e32 v171, -1.0, v170
	v_add_f32_e32 v172, 1.0, v171
	v_sub_f32_e32 v172, v170, v172
	v_add_f32_e32 v172, v169, v172
	v_add_f32_e32 v174, v171, v172
	v_sub_f32_e32 v171, v171, v174
	v_add_f32_e32 v171, v172, v171
	v_add_f32_e32 v172, 1.0, v170
	v_add_f32_e32 v175, -1.0, v172
	v_sub_f32_e32 v170, v170, v175
	v_add_f32_e32 v169, v169, v170
	v_add_f32_e32 v170, v172, v169
	v_sub_f32_e32 v172, v172, v170
	v_add_f32_e32 v169, v169, v172
	v_rcp_f32_e32 v172, v170
	v_cvt_f32_i32_e32 v168, v168
	v_cmp_neq_f32_e64 s[10:11], s58, v0
	v_mul_f32_e32 v175, v174, v172
	v_mul_f32_e32 v176, v170, v175
	v_fma_f32 v177, v175, v170, -v176
	v_fmac_f32_e32 v177, v175, v169
	v_add_f32_e32 v194, v176, v177
	v_sub_f32_e32 v195, v174, v194
	v_sub_f32_e32 v174, v174, v195
	v_sub_f32_e32 v176, v194, v176
	v_sub_f32_e32 v174, v174, v194
	v_add_f32_e32 v171, v171, v174
	v_sub_f32_e32 v174, v176, v177
	v_add_f32_e32 v171, v174, v171
	v_add_f32_e32 v174, v195, v171
	v_mul_f32_e32 v176, v172, v174
	v_mul_f32_e32 v177, v170, v176
	v_fma_f32 v170, v176, v170, -v177
	v_fmac_f32_e32 v170, v176, v169
	v_sub_f32_e32 v169, v195, v174
	v_add_f32_e32 v169, v171, v169
	v_add_f32_e32 v171, v177, v170
	v_sub_f32_e32 v194, v174, v171
	v_sub_f32_e32 v174, v174, v194
	v_sub_f32_e32 v177, v171, v177
	v_sub_f32_e32 v171, v174, v171
	v_add_f32_e32 v169, v169, v171
	v_sub_f32_e32 v170, v177, v170
	v_add_f32_e32 v169, v170, v169
	v_add_f32_e32 v170, v175, v176
	v_add_f32_e32 v169, v194, v169
	v_sub_f32_e32 v171, v170, v175
	v_mul_f32_e32 v169, v172, v169
	v_sub_f32_e32 v171, v176, v171
	v_add_f32_e32 v169, v171, v169
	v_mul_f32_e32 v175, 0x3f317218, v168
	v_add_f32_e32 v171, v170, v169
	v_fma_f32 v176, v168, s60, -v175
	v_mul_f32_e32 v172, v171, v171
	v_fmac_f32_e32 v176, 0xb102e308, v168
	v_sub_f32_e32 v168, v171, v170
	v_fmamk_f32 v174, v172, 0x3e9b6dac, v196
	v_sub_f32_e32 v168, v169, v168
	v_add_f32_e32 v169, v175, v176
	v_fmaak_f32 v174, v172, v174, 0x3f2aaada
	v_sub_f32_e32 v170, v169, v175
	v_ldexp_f32 v175, v171, 1
	v_mul_f32_e32 v171, v171, v172
	v_mul_f32_e32 v171, v171, v174
	v_add_f32_e32 v172, v175, v171
	v_sub_f32_e32 v174, v172, v175
	v_ldexp_f32 v168, v168, 1
	v_sub_f32_e32 v171, v171, v174
	v_add_f32_e32 v168, v168, v171
	v_add_f32_e32 v171, v172, v168
	v_sub_f32_e32 v172, v171, v172
	v_sub_f32_e32 v168, v168, v172
	v_add_f32_e32 v172, v169, v171
	v_sub_f32_e32 v174, v172, v169
	v_sub_f32_e32 v175, v172, v174
	v_sub_f32_e32 v170, v176, v170
	v_sub_f32_e32 v169, v169, v175
	v_sub_f32_e32 v171, v171, v174
	v_add_f32_e32 v169, v171, v169
	v_add_f32_e32 v171, v170, v168
	v_sub_f32_e32 v174, v171, v170
	v_sub_f32_e32 v175, v171, v174
	v_sub_f32_e32 v170, v170, v175
	v_sub_f32_e32 v168, v168, v174
	v_add_f32_e32 v169, v171, v169
	v_add_f32_e32 v168, v168, v170
	v_add_f32_e32 v170, v172, v169
	v_sub_f32_e32 v171, v170, v172
	v_sub_f32_e32 v169, v169, v171
	v_add_f32_e32 v168, v168, v169
	v_add_f32_e32 v168, v170, v168
	v_cndmask_b32_e64 v168, v197, v168, s[10:11]
	v_cmp_lt_f32_e64 s[10:11], |v0|, s61
	s_nop 1
	v_cndmask_b32_e64 v0, v168, v0, s[10:11]
	v_sub_f32_e32 v0, v165, v0
	v_lshl_add_u64 v[168:169], v[166:167], 0, s[2:3]
	global_store_dword v[168:169], v0, off
	global_load_dword v0, v1, s[18:19] offset:44
	s_or_b32 s2, s38, 11
	s_ashr_i32 s3, s2, 31
	s_lshl_b64 s[2:3], s[2:3], 16
	s_waitcnt vmcnt(0)
;   DI void operator()(int tok0, int feat0, f32x16 (&acc)[2][2], int r, int hh) const {
;     ...
;           for (int i = 0; i < 16; ++i) {
;             const float xv = acc[0][mt][i] + bf[i];
;             const float ls = fminf(xv, 0.f) - log1pf(expf(-fabsf(xv)));
;             lf[((size_t)(b * 16 + i)) * SEQ + s] = ls;
;           }
	v_add_f32_e32 v0, v125, v0
	v_mul_f32_e64 v168, |v0|, s54
	v_fma_f32 v169, |v0|, s54, -v168
	v_rndne_f32_e32 v170, v168
	v_fma_f32 v169, |v0|, s55, v169
	v_sub_f32_e32 v168, v168, v170
	v_add_f32_e32 v168, v168, v169
	v_exp_f32_e32 v168, v168
	v_cvt_i32_f32_e32 v169, v170
	v_cmp_ngt_f32_e64 s[10:11], |v0|, s56
	v_min_f32_e32 v165, 0, v0
	v_ldexp_f32 v168, v168, v169
	v_cndmask_b32_e64 v168, 0, v168, s[10:11]
	v_cmp_nlt_f32_e64 s[10:11], |v0|, s57
	s_nop 1
	v_cndmask_b32_e64 v0, v197, v168, s[10:11]
	v_add_f32_e32 v170, 1.0, v0
	v_add_f32_e32 v168, -1.0, v170
	v_sub_f32_e32 v169, v168, v170
	v_add_f32_e32 v169, 1.0, v169
	v_sub_f32_e32 v168, v0, v168
	v_add_f32_e32 v171, v168, v169
	v_frexp_mant_f32_e32 v168, v170
	v_cmp_gt_f32_e64 s[10:11], s59, v168
	v_cvt_f64_f32_e32 v[168:169], v170
	v_frexp_exp_i32_f64_e32 v168, v[168:169]
	v_subbrev_co_u32_e64 v168, s[10:11], 0, v168, s[10:11]
	v_sub_u32_e32 v169, 0, v168
	v_ldexp_f32 v170, v170, v169
	v_ldexp_f32 v169, v171, v169
	v_add_f32_e32 v171, -1.0, v170
	v_add_f32_e32 v172, 1.0, v171
	v_sub_f32_e32 v172, v170, v172
	v_add_f32_e32 v172, v169, v172
	v_add_f32_e32 v174, v171, v172
	v_sub_f32_e32 v171, v171, v174
	v_add_f32_e32 v171, v172, v171
	v_add_f32_e32 v172, 1.0, v170
	v_add_f32_e32 v175, -1.0, v172
	v_sub_f32_e32 v170, v170, v175
	v_add_f32_e32 v169, v169, v170
	v_add_f32_e32 v170, v172, v169
	v_sub_f32_e32 v172, v172, v170
	v_add_f32_e32 v169, v169, v172
	v_rcp_f32_e32 v172, v170
	v_cvt_f32_i32_e32 v168, v168
	v_cmp_neq_f32_e64 s[10:11], s58, v0
	v_mul_f32_e32 v175, v174, v172
	v_mul_f32_e32 v176, v170, v175
	v_fma_f32 v177, v175, v170, -v176
	v_fmac_f32_e32 v177, v175, v169
	v_add_f32_e32 v194, v176, v177
	v_sub_f32_e32 v195, v174, v194
	v_sub_f32_e32 v174, v174, v195
	v_sub_f32_e32 v176, v194, v176
	v_sub_f32_e32 v174, v174, v194
	v_add_f32_e32 v171, v171, v174
	v_sub_f32_e32 v174, v176, v177
	v_add_f32_e32 v171, v174, v171
	v_add_f32_e32 v174, v195, v171
	v_mul_f32_e32 v176, v172, v174
	v_mul_f32_e32 v177, v170, v176
	v_fma_f32 v170, v176, v170, -v177
	v_fmac_f32_e32 v170, v176, v169
	v_sub_f32_e32 v169, v195, v174
	v_add_f32_e32 v169, v171, v169
	v_add_f32_e32 v171, v177, v170
	v_sub_f32_e32 v194, v174, v171
	v_sub_f32_e32 v174, v174, v194
	v_sub_f32_e32 v177, v171, v177
	v_sub_f32_e32 v171, v174, v171
	v_add_f32_e32 v169, v169, v171
	v_sub_f32_e32 v170, v177, v170
	v_add_f32_e32 v169, v170, v169
	v_add_f32_e32 v170, v175, v176
	v_add_f32_e32 v169, v194, v169
	v_sub_f32_e32 v171, v170, v175
	v_mul_f32_e32 v169, v172, v169
	v_sub_f32_e32 v171, v176, v171
	v_add_f32_e32 v169, v171, v169
	v_mul_f32_e32 v175, 0x3f317218, v168
	v_add_f32_e32 v171, v170, v169
	v_fma_f32 v176, v168, s60, -v175
	v_mul_f32_e32 v172, v171, v171
	v_fmac_f32_e32 v176, 0xb102e308, v168
	v_sub_f32_e32 v168, v171, v170
	v_fmamk_f32 v174, v172, 0x3e9b6dac, v196
	v_sub_f32_e32 v168, v169, v168
	v_add_f32_e32 v169, v175, v176
	v_fmaak_f32 v174, v172, v174, 0x3f2aaada
	v_sub_f32_e32 v170, v169, v175
	v_ldexp_f32 v175, v171, 1
	v_mul_f32_e32 v171, v171, v172
	v_mul_f32_e32 v171, v171, v174
	v_add_f32_e32 v172, v175, v171
	v_sub_f32_e32 v174, v172, v175
	v_ldexp_f32 v168, v168, 1
	v_sub_f32_e32 v171, v171, v174
	v_add_f32_e32 v168, v168, v171
	v_add_f32_e32 v171, v172, v168
	v_sub_f32_e32 v172, v171, v172
	v_sub_f32_e32 v168, v168, v172
	v_add_f32_e32 v172, v169, v171
	v_sub_f32_e32 v174, v172, v169
	v_sub_f32_e32 v175, v172, v174
	v_sub_f32_e32 v170, v176, v170
	v_sub_f32_e32 v169, v169, v175
	v_sub_f32_e32 v171, v171, v174
	v_add_f32_e32 v169, v171, v169
	v_add_f32_e32 v171, v170, v168
	v_sub_f32_e32 v174, v171, v170
	v_sub_f32_e32 v175, v171, v174
	v_sub_f32_e32 v170, v170, v175
	v_sub_f32_e32 v168, v168, v174
	v_add_f32_e32 v169, v171, v169
	v_add_f32_e32 v168, v168, v170
	v_add_f32_e32 v170, v172, v169
	v_sub_f32_e32 v171, v170, v172
	v_sub_f32_e32 v169, v169, v171
	v_add_f32_e32 v168, v168, v169
	v_add_f32_e32 v168, v170, v168
	v_cndmask_b32_e64 v168, v197, v168, s[10:11]
	v_cmp_lt_f32_e64 s[10:11], |v0|, s61
	s_nop 1
	v_cndmask_b32_e64 v0, v168, v0, s[10:11]
	v_sub_f32_e32 v0, v165, v0
	v_lshl_add_u64 v[168:169], v[166:167], 0, s[2:3]
	global_store_dword v[168:169], v0, off
	global_load_dword v0, v1, s[18:19] offset:48
	s_or_b32 s2, s38, 12
	s_ashr_i32 s3, s2, 31
	s_lshl_b64 s[2:3], s[2:3], 16
	s_waitcnt vmcnt(0)
;   DI void operator()(int tok0, int feat0, f32x16 (&acc)[2][2], int r, int hh) const {
;     ...
;           for (int i = 0; i < 16; ++i) {
;             const float xv = acc[0][mt][i] + bf[i];
;             const float ls = fminf(xv, 0.f) - log1pf(expf(-fabsf(xv)));
;             lf[((size_t)(b * 16 + i)) * SEQ + s] = ls;
;           }
	v_add_f32_e32 v0, v126, v0
	v_mul_f32_e64 v168, |v0|, s54
	v_fma_f32 v169, |v0|, s54, -v168
	v_rndne_f32_e32 v170, v168
	v_fma_f32 v169, |v0|, s55, v169
	v_sub_f32_e32 v168, v168, v170
	v_add_f32_e32 v168, v168, v169
	v_exp_f32_e32 v168, v168
	v_cvt_i32_f32_e32 v169, v170
	v_cmp_ngt_f32_e64 s[10:11], |v0|, s56
	v_min_f32_e32 v165, 0, v0
	v_ldexp_f32 v168, v168, v169
	v_cndmask_b32_e64 v168, 0, v168, s[10:11]
	v_cmp_nlt_f32_e64 s[10:11], |v0|, s57
	s_nop 1
	v_cndmask_b32_e64 v0, v197, v168, s[10:11]
	v_add_f32_e32 v170, 1.0, v0
	v_add_f32_e32 v168, -1.0, v170
	v_sub_f32_e32 v169, v168, v170
	v_add_f32_e32 v169, 1.0, v169
	v_sub_f32_e32 v168, v0, v168
	v_add_f32_e32 v171, v168, v169
	v_frexp_mant_f32_e32 v168, v170
	v_cmp_gt_f32_e64 s[10:11], s59, v168
	v_cvt_f64_f32_e32 v[168:169], v170
	v_frexp_exp_i32_f64_e32 v168, v[168:169]
	v_subbrev_co_u32_e64 v168, s[10:11], 0, v168, s[10:11]
	v_sub_u32_e32 v169, 0, v168
	v_ldexp_f32 v170, v170, v169
	v_ldexp_f32 v169, v171, v169
	v_add_f32_e32 v171, -1.0, v170
	v_add_f32_e32 v172, 1.0, v171
	v_sub_f32_e32 v172, v170, v172
	v_add_f32_e32 v172, v169, v172
	v_add_f32_e32 v174, v171, v172
	v_sub_f32_e32 v171, v171, v174
	v_add_f32_e32 v171, v172, v171
	v_add_f32_e32 v172, 1.0, v170
	v_add_f32_e32 v175, -1.0, v172
	v_sub_f32_e32 v170, v170, v175
	v_add_f32_e32 v169, v169, v170
	v_add_f32_e32 v170, v172, v169
	v_sub_f32_e32 v172, v172, v170
	v_add_f32_e32 v169, v169, v172
	v_rcp_f32_e32 v172, v170
	v_cvt_f32_i32_e32 v168, v168
	v_cmp_neq_f32_e64 s[10:11], s58, v0
	v_mul_f32_e32 v175, v174, v172
	v_mul_f32_e32 v176, v170, v175
	v_fma_f32 v177, v175, v170, -v176
	v_fmac_f32_e32 v177, v175, v169
	v_add_f32_e32 v194, v176, v177
	v_sub_f32_e32 v195, v174, v194
	v_sub_f32_e32 v174, v174, v195
	v_sub_f32_e32 v176, v194, v176
	v_sub_f32_e32 v174, v174, v194
	v_add_f32_e32 v171, v171, v174
	v_sub_f32_e32 v174, v176, v177
	v_add_f32_e32 v171, v174, v171
	v_add_f32_e32 v174, v195, v171
	v_mul_f32_e32 v176, v172, v174
	v_mul_f32_e32 v177, v170, v176
	v_fma_f32 v170, v176, v170, -v177
	v_fmac_f32_e32 v170, v176, v169
	v_sub_f32_e32 v169, v195, v174
	v_add_f32_e32 v169, v171, v169
	v_add_f32_e32 v171, v177, v170
	v_sub_f32_e32 v194, v174, v171
	v_sub_f32_e32 v174, v174, v194
	v_sub_f32_e32 v177, v171, v177
	v_sub_f32_e32 v171, v174, v171
	v_add_f32_e32 v169, v169, v171
	v_sub_f32_e32 v170, v177, v170
	v_add_f32_e32 v169, v170, v169
	v_add_f32_e32 v170, v175, v176
	v_add_f32_e32 v169, v194, v169
	v_sub_f32_e32 v171, v170, v175
	v_mul_f32_e32 v169, v172, v169
	v_sub_f32_e32 v171, v176, v171
	v_add_f32_e32 v169, v171, v169
	v_mul_f32_e32 v175, 0x3f317218, v168
	v_add_f32_e32 v171, v170, v169
	v_fma_f32 v176, v168, s60, -v175
	v_mul_f32_e32 v172, v171, v171
	v_fmac_f32_e32 v176, 0xb102e308, v168
	v_sub_f32_e32 v168, v171, v170
	v_fmamk_f32 v174, v172, 0x3e9b6dac, v196
	v_sub_f32_e32 v168, v169, v168
	v_add_f32_e32 v169, v175, v176
	v_fmaak_f32 v174, v172, v174, 0x3f2aaada
	v_sub_f32_e32 v170, v169, v175
	v_ldexp_f32 v175, v171, 1
	v_mul_f32_e32 v171, v171, v172
	v_mul_f32_e32 v171, v171, v174
	v_add_f32_e32 v172, v175, v171
	v_sub_f32_e32 v174, v172, v175
	v_ldexp_f32 v168, v168, 1
	v_sub_f32_e32 v171, v171, v174
	v_add_f32_e32 v168, v168, v171
	v_add_f32_e32 v171, v172, v168
	v_sub_f32_e32 v172, v171, v172
	v_sub_f32_e32 v168, v168, v172
	v_add_f32_e32 v172, v169, v171
	v_sub_f32_e32 v174, v172, v169
	v_sub_f32_e32 v175, v172, v174
	v_sub_f32_e32 v170, v176, v170
	v_sub_f32_e32 v169, v169, v175
	v_sub_f32_e32 v171, v171, v174
	v_add_f32_e32 v169, v171, v169
	v_add_f32_e32 v171, v170, v168
	v_sub_f32_e32 v174, v171, v170
	v_sub_f32_e32 v175, v171, v174
	v_sub_f32_e32 v170, v170, v175
	v_sub_f32_e32 v168, v168, v174
	v_add_f32_e32 v169, v171, v169
	v_add_f32_e32 v168, v168, v170
	v_add_f32_e32 v170, v172, v169
	v_sub_f32_e32 v171, v170, v172
	v_sub_f32_e32 v169, v169, v171
	v_add_f32_e32 v168, v168, v169
	v_add_f32_e32 v168, v170, v168
	v_cndmask_b32_e64 v168, v197, v168, s[10:11]
	v_cmp_lt_f32_e64 s[10:11], |v0|, s61
	s_nop 1
	v_cndmask_b32_e64 v0, v168, v0, s[10:11]
	v_sub_f32_e32 v0, v165, v0
	v_lshl_add_u64 v[168:169], v[166:167], 0, s[2:3]
	global_store_dword v[168:169], v0, off
	global_load_dword v0, v1, s[18:19] offset:52
	s_or_b32 s2, s38, 13
	s_ashr_i32 s3, s2, 31
	s_lshl_b64 s[2:3], s[2:3], 16
	s_waitcnt vmcnt(0)
;   DI void operator()(int tok0, int feat0, f32x16 (&acc)[2][2], int r, int hh) const {
;     ...
;           for (int i = 0; i < 16; ++i) {
;             const float xv = acc[0][mt][i] + bf[i];
;             const float ls = fminf(xv, 0.f) - log1pf(expf(-fabsf(xv)));
;             lf[((size_t)(b * 16 + i)) * SEQ + s] = ls;
;           }
	v_add_f32_e32 v0, v127, v0
	v_mul_f32_e64 v168, |v0|, s54
	v_fma_f32 v169, |v0|, s54, -v168
	v_rndne_f32_e32 v170, v168
	v_fma_f32 v169, |v0|, s55, v169
	v_sub_f32_e32 v168, v168, v170
	v_add_f32_e32 v168, v168, v169
	v_exp_f32_e32 v168, v168
	v_cvt_i32_f32_e32 v169, v170
	v_cmp_ngt_f32_e64 s[10:11], |v0|, s56
	v_min_f32_e32 v165, 0, v0
	v_ldexp_f32 v168, v168, v169
	v_cndmask_b32_e64 v168, 0, v168, s[10:11]
	v_cmp_nlt_f32_e64 s[10:11], |v0|, s57
	s_nop 1
	v_cndmask_b32_e64 v0, v197, v168, s[10:11]
	v_add_f32_e32 v170, 1.0, v0
	v_add_f32_e32 v168, -1.0, v170
	v_sub_f32_e32 v169, v168, v170
	v_add_f32_e32 v169, 1.0, v169
	v_sub_f32_e32 v168, v0, v168
	v_add_f32_e32 v171, v168, v169
	v_frexp_mant_f32_e32 v168, v170
	v_cmp_gt_f32_e64 s[10:11], s59, v168
	v_cvt_f64_f32_e32 v[168:169], v170
	v_frexp_exp_i32_f64_e32 v168, v[168:169]
	v_subbrev_co_u32_e64 v168, s[10:11], 0, v168, s[10:11]
	v_sub_u32_e32 v169, 0, v168
	v_ldexp_f32 v170, v170, v169
	v_ldexp_f32 v169, v171, v169
	v_add_f32_e32 v171, -1.0, v170
	v_add_f32_e32 v172, 1.0, v171
	v_sub_f32_e32 v172, v170, v172
	v_add_f32_e32 v172, v169, v172
	v_add_f32_e32 v174, v171, v172
	v_sub_f32_e32 v171, v171, v174
	v_add_f32_e32 v171, v172, v171
	v_add_f32_e32 v172, 1.0, v170
	v_add_f32_e32 v175, -1.0, v172
	v_sub_f32_e32 v170, v170, v175
	v_add_f32_e32 v169, v169, v170
	v_add_f32_e32 v170, v172, v169
	v_sub_f32_e32 v172, v172, v170
	v_add_f32_e32 v169, v169, v172
	v_rcp_f32_e32 v172, v170
	v_cvt_f32_i32_e32 v168, v168
	v_cmp_neq_f32_e64 s[10:11], s58, v0
	v_mul_f32_e32 v175, v174, v172
	v_mul_f32_e32 v176, v170, v175
	v_fma_f32 v177, v175, v170, -v176
	v_fmac_f32_e32 v177, v175, v169
	v_add_f32_e32 v194, v176, v177
	v_sub_f32_e32 v195, v174, v194
	v_sub_f32_e32 v174, v174, v195
	v_sub_f32_e32 v176, v194, v176
	v_sub_f32_e32 v174, v174, v194
	v_add_f32_e32 v171, v171, v174
	v_sub_f32_e32 v174, v176, v177
	v_add_f32_e32 v171, v174, v171
	v_add_f32_e32 v174, v195, v171
	v_mul_f32_e32 v176, v172, v174
	v_mul_f32_e32 v177, v170, v176
	v_fma_f32 v170, v176, v170, -v177
	v_fmac_f32_e32 v170, v176, v169
	v_sub_f32_e32 v169, v195, v174
	v_add_f32_e32 v169, v171, v169
	v_add_f32_e32 v171, v177, v170
	v_sub_f32_e32 v194, v174, v171
	v_sub_f32_e32 v174, v174, v194
	v_sub_f32_e32 v177, v171, v177
	v_sub_f32_e32 v171, v174, v171
	v_add_f32_e32 v169, v169, v171
	v_sub_f32_e32 v170, v177, v170
	v_add_f32_e32 v169, v170, v169
	v_add_f32_e32 v170, v175, v176
	v_add_f32_e32 v169, v194, v169
	v_sub_f32_e32 v171, v170, v175
	v_mul_f32_e32 v169, v172, v169
	v_sub_f32_e32 v171, v176, v171
	v_add_f32_e32 v169, v171, v169
	v_mul_f32_e32 v175, 0x3f317218, v168
	v_add_f32_e32 v171, v170, v169
	v_fma_f32 v176, v168, s60, -v175
	v_mul_f32_e32 v172, v171, v171
	v_fmac_f32_e32 v176, 0xb102e308, v168
	v_sub_f32_e32 v168, v171, v170
	v_fmamk_f32 v174, v172, 0x3e9b6dac, v196
	v_sub_f32_e32 v168, v169, v168
	v_add_f32_e32 v169, v175, v176
	v_fmaak_f32 v174, v172, v174, 0x3f2aaada
	v_sub_f32_e32 v170, v169, v175
	v_ldexp_f32 v175, v171, 1
	v_mul_f32_e32 v171, v171, v172
	v_mul_f32_e32 v171, v171, v174
	v_add_f32_e32 v172, v175, v171
	v_sub_f32_e32 v174, v172, v175
	v_ldexp_f32 v168, v168, 1
	v_sub_f32_e32 v171, v171, v174
	v_add_f32_e32 v168, v168, v171
	v_add_f32_e32 v171, v172, v168
	v_sub_f32_e32 v172, v171, v172
	v_sub_f32_e32 v168, v168, v172
	v_add_f32_e32 v172, v169, v171
	v_sub_f32_e32 v174, v172, v169
	v_sub_f32_e32 v175, v172, v174
	v_sub_f32_e32 v170, v176, v170
	v_sub_f32_e32 v169, v169, v175
	v_sub_f32_e32 v171, v171, v174
	v_add_f32_e32 v169, v171, v169
	v_add_f32_e32 v171, v170, v168
	v_sub_f32_e32 v174, v171, v170
	v_sub_f32_e32 v175, v171, v174
	v_sub_f32_e32 v170, v170, v175
	v_sub_f32_e32 v168, v168, v174
	v_add_f32_e32 v169, v171, v169
	v_add_f32_e32 v168, v168, v170
	v_add_f32_e32 v170, v172, v169
	v_sub_f32_e32 v171, v170, v172
	v_sub_f32_e32 v169, v169, v171
	v_add_f32_e32 v168, v168, v169
	v_add_f32_e32 v168, v170, v168
	v_cndmask_b32_e64 v168, v197, v168, s[10:11]
	v_cmp_lt_f32_e64 s[10:11], |v0|, s61
	s_nop 1
	v_cndmask_b32_e64 v0, v168, v0, s[10:11]
	v_sub_f32_e32 v0, v165, v0
	v_lshl_add_u64 v[168:169], v[166:167], 0, s[2:3]
	global_store_dword v[168:169], v0, off
	global_load_dword v0, v1, s[18:19] offset:56
	s_or_b32 s2, s38, 14
	s_ashr_i32 s3, s2, 31
	s_lshl_b64 s[2:3], s[2:3], 16
	s_waitcnt vmcnt(0)
;   DI void operator()(int tok0, int feat0, f32x16 (&acc)[2][2], int r, int hh) const {
;     ...
;           for (int i = 0; i < 16; ++i) {
;             const float xv = acc[0][mt][i] + bf[i];
;             const float ls = fminf(xv, 0.f) - log1pf(expf(-fabsf(xv)));
;             lf[((size_t)(b * 16 + i)) * SEQ + s] = ls;
;           }
	v_add_f32_e32 v0, v128, v0
	v_mul_f32_e64 v168, |v0|, s54
	v_fma_f32 v169, |v0|, s54, -v168
	v_rndne_f32_e32 v170, v168
	v_fma_f32 v169, |v0|, s55, v169
	v_sub_f32_e32 v168, v168, v170
	v_add_f32_e32 v168, v168, v169
	v_exp_f32_e32 v168, v168
	v_cvt_i32_f32_e32 v169, v170
	v_cmp_ngt_f32_e64 s[10:11], |v0|, s56
	v_min_f32_e32 v165, 0, v0
	v_ldexp_f32 v168, v168, v169
	v_cndmask_b32_e64 v168, 0, v168, s[10:11]
	v_cmp_nlt_f32_e64 s[10:11], |v0|, s57
	s_nop 1
	v_cndmask_b32_e64 v0, v197, v168, s[10:11]
	v_add_f32_e32 v170, 1.0, v0
	v_add_f32_e32 v168, -1.0, v170
	v_sub_f32_e32 v169, v168, v170
	v_add_f32_e32 v169, 1.0, v169
	v_sub_f32_e32 v168, v0, v168
	v_add_f32_e32 v171, v168, v169
	v_frexp_mant_f32_e32 v168, v170
	v_cmp_gt_f32_e64 s[10:11], s59, v168
	v_cvt_f64_f32_e32 v[168:169], v170
	v_frexp_exp_i32_f64_e32 v168, v[168:169]
	v_subbrev_co_u32_e64 v168, s[10:11], 0, v168, s[10:11]
	v_sub_u32_e32 v169, 0, v168
	v_ldexp_f32 v170, v170, v169
	v_ldexp_f32 v169, v171, v169
	v_add_f32_e32 v171, -1.0, v170
	v_add_f32_e32 v172, 1.0, v171
	v_sub_f32_e32 v172, v170, v172
	v_add_f32_e32 v172, v169, v172
	v_add_f32_e32 v174, v171, v172
	v_sub_f32_e32 v171, v171, v174
	v_add_f32_e32 v171, v172, v171
	v_add_f32_e32 v172, 1.0, v170
	v_add_f32_e32 v175, -1.0, v172
	v_sub_f32_e32 v170, v170, v175
	v_add_f32_e32 v169, v169, v170
	v_add_f32_e32 v170, v172, v169
	v_sub_f32_e32 v172, v172, v170
	v_add_f32_e32 v169, v169, v172
	v_rcp_f32_e32 v172, v170
	v_cvt_f32_i32_e32 v168, v168
	v_cmp_neq_f32_e64 s[10:11], s58, v0
	v_mul_f32_e32 v175, v174, v172
	v_mul_f32_e32 v176, v170, v175
	v_fma_f32 v177, v175, v170, -v176
	v_fmac_f32_e32 v177, v175, v169
	v_add_f32_e32 v194, v176, v177
	v_sub_f32_e32 v195, v174, v194
	v_sub_f32_e32 v174, v174, v195
	v_sub_f32_e32 v176, v194, v176
	v_sub_f32_e32 v174, v174, v194
	v_add_f32_e32 v171, v171, v174
	v_sub_f32_e32 v174, v176, v177
	v_add_f32_e32 v171, v174, v171
	v_add_f32_e32 v174, v195, v171
	v_mul_f32_e32 v176, v172, v174
	v_mul_f32_e32 v177, v170, v176
	v_fma_f32 v170, v176, v170, -v177
	v_fmac_f32_e32 v170, v176, v169
	v_sub_f32_e32 v169, v195, v174
	v_add_f32_e32 v169, v171, v169
	v_add_f32_e32 v171, v177, v170
	v_sub_f32_e32 v194, v174, v171
	v_sub_f32_e32 v174, v174, v194
	v_sub_f32_e32 v177, v171, v177
	v_sub_f32_e32 v171, v174, v171
	v_add_f32_e32 v169, v169, v171
	v_sub_f32_e32 v170, v177, v170
	v_add_f32_e32 v169, v170, v169
	v_add_f32_e32 v170, v175, v176
	v_add_f32_e32 v169, v194, v169
	v_sub_f32_e32 v171, v170, v175
	v_mul_f32_e32 v169, v172, v169
	v_sub_f32_e32 v171, v176, v171
	v_add_f32_e32 v169, v171, v169
	v_mul_f32_e32 v175, 0x3f317218, v168
	v_add_f32_e32 v171, v170, v169
	v_fma_f32 v176, v168, s60, -v175
	v_mul_f32_e32 v172, v171, v171
	v_fmac_f32_e32 v176, 0xb102e308, v168
	v_sub_f32_e32 v168, v171, v170
	v_fmamk_f32 v174, v172, 0x3e9b6dac, v196
	v_sub_f32_e32 v168, v169, v168
	v_add_f32_e32 v169, v175, v176
	v_fmaak_f32 v174, v172, v174, 0x3f2aaada
	v_sub_f32_e32 v170, v169, v175
	v_ldexp_f32 v175, v171, 1
	v_mul_f32_e32 v171, v171, v172
	v_mul_f32_e32 v171, v171, v174
	v_add_f32_e32 v172, v175, v171
	v_sub_f32_e32 v174, v172, v175
	v_ldexp_f32 v168, v168, 1
	v_sub_f32_e32 v171, v171, v174
	v_add_f32_e32 v168, v168, v171
	v_add_f32_e32 v171, v172, v168
	v_sub_f32_e32 v172, v171, v172
	v_sub_f32_e32 v168, v168, v172
	v_add_f32_e32 v172, v169, v171
	v_sub_f32_e32 v174, v172, v169
	v_sub_f32_e32 v175, v172, v174
	v_sub_f32_e32 v170, v176, v170
	v_sub_f32_e32 v169, v169, v175
	v_sub_f32_e32 v171, v171, v174
	v_add_f32_e32 v169, v171, v169
	v_add_f32_e32 v171, v170, v168
	v_sub_f32_e32 v174, v171, v170
	v_sub_f32_e32 v175, v171, v174
	v_sub_f32_e32 v170, v170, v175
	v_sub_f32_e32 v168, v168, v174
	v_add_f32_e32 v169, v171, v169
	v_add_f32_e32 v168, v168, v170
	v_add_f32_e32 v170, v172, v169
	v_sub_f32_e32 v171, v170, v172
	v_sub_f32_e32 v169, v169, v171
	v_add_f32_e32 v168, v168, v169
	v_add_f32_e32 v168, v170, v168
	v_cndmask_b32_e64 v168, v197, v168, s[10:11]
	v_cmp_lt_f32_e64 s[10:11], |v0|, s61
	s_nop 1
	v_cndmask_b32_e64 v0, v168, v0, s[10:11]
	v_sub_f32_e32 v0, v165, v0
	v_lshl_add_u64 v[168:169], v[166:167], 0, s[2:3]
	global_store_dword v[168:169], v0, off
	global_load_dword v0, v1, s[18:19] offset:60
	s_or_b32 s2, s38, 15
	s_ashr_i32 s3, s2, 31
	s_lshl_b64 s[4:5], s[2:3], 16
	v_lshl_add_u64 v[166:167], v[166:167], 0, s[4:5]
	s_waitcnt vmcnt(0)
;   DI void operator()(int tok0, int feat0, f32x16 (&acc)[2][2], int r, int hh) const {
;     ...
;           for (int i = 0; i < 16; ++i) {
;             const float xv = acc[0][mt][i] + bf[i];
;             const float ls = fminf(xv, 0.f) - log1pf(expf(-fabsf(xv)));
;             lf[((size_t)(b * 16 + i)) * SEQ + s] = ls;
;           }
	v_add_f32_e32 v0, v129, v0
	v_mul_f32_e64 v168, |v0|, s54
	v_fma_f32 v169, |v0|, s54, -v168
	v_rndne_f32_e32 v170, v168
	v_fma_f32 v169, |v0|, s55, v169
	v_sub_f32_e32 v168, v168, v170
	v_add_f32_e32 v168, v168, v169
	v_exp_f32_e32 v168, v168
	v_cvt_i32_f32_e32 v169, v170
	v_cmp_ngt_f32_e64 s[10:11], |v0|, s56
	v_min_f32_e32 v165, 0, v0
	v_ldexp_f32 v168, v168, v169
	v_cndmask_b32_e64 v168, 0, v168, s[10:11]
	v_cmp_nlt_f32_e64 s[10:11], |v0|, s57
	s_nop 1
	v_cndmask_b32_e64 v0, v197, v168, s[10:11]
	v_add_f32_e32 v170, 1.0, v0
	v_add_f32_e32 v168, -1.0, v170
	v_sub_f32_e32 v169, v168, v170
	v_add_f32_e32 v169, 1.0, v169
	v_sub_f32_e32 v168, v0, v168
	v_add_f32_e32 v171, v168, v169
	v_frexp_mant_f32_e32 v168, v170
	v_cmp_gt_f32_e64 s[10:11], s59, v168
	v_cvt_f64_f32_e32 v[168:169], v170
	v_frexp_exp_i32_f64_e32 v168, v[168:169]
	v_subbrev_co_u32_e64 v168, s[10:11], 0, v168, s[10:11]
	v_sub_u32_e32 v169, 0, v168
	v_ldexp_f32 v170, v170, v169
	v_ldexp_f32 v169, v171, v169
	v_add_f32_e32 v171, -1.0, v170
	v_add_f32_e32 v172, 1.0, v171
	v_sub_f32_e32 v172, v170, v172
	v_add_f32_e32 v172, v169, v172
	v_add_f32_e32 v174, v171, v172
	v_sub_f32_e32 v171, v171, v174
	v_add_f32_e32 v171, v172, v171
	v_add_f32_e32 v172, 1.0, v170
	v_add_f32_e32 v175, -1.0, v172
	v_sub_f32_e32 v170, v170, v175
	v_add_f32_e32 v169, v169, v170
	v_add_f32_e32 v170, v172, v169
	v_sub_f32_e32 v172, v172, v170
	v_add_f32_e32 v169, v169, v172
	v_rcp_f32_e32 v172, v170
	v_cvt_f32_i32_e32 v168, v168
	v_cmp_neq_f32_e64 s[10:11], s58, v0
	v_mul_f32_e32 v175, v174, v172
	v_mul_f32_e32 v176, v170, v175
	v_fma_f32 v177, v175, v170, -v176
	v_fmac_f32_e32 v177, v175, v169
	v_add_f32_e32 v194, v176, v177
	v_sub_f32_e32 v195, v174, v194
	v_sub_f32_e32 v174, v174, v195
	v_sub_f32_e32 v176, v194, v176
	v_sub_f32_e32 v174, v174, v194
	v_add_f32_e32 v171, v171, v174
	v_sub_f32_e32 v174, v176, v177
	v_add_f32_e32 v171, v174, v171
	v_add_f32_e32 v174, v195, v171
	v_mul_f32_e32 v176, v172, v174
	v_mul_f32_e32 v177, v170, v176
	v_fma_f32 v170, v176, v170, -v177
	v_fmac_f32_e32 v170, v176, v169
	v_sub_f32_e32 v169, v195, v174
	v_add_f32_e32 v169, v171, v169
	v_add_f32_e32 v171, v177, v170
	v_sub_f32_e32 v194, v174, v171
	v_sub_f32_e32 v174, v174, v194
	v_sub_f32_e32 v177, v171, v177
	v_sub_f32_e32 v171, v174, v171
	v_add_f32_e32 v169, v169, v171
	v_sub_f32_e32 v170, v177, v170
	v_add_f32_e32 v169, v170, v169
	v_add_f32_e32 v170, v175, v176
	v_add_f32_e32 v169, v194, v169
	v_sub_f32_e32 v171, v170, v175
	v_mul_f32_e32 v169, v172, v169
	v_sub_f32_e32 v171, v176, v171
	v_add_f32_e32 v169, v171, v169
	v_mul_f32_e32 v175, 0x3f317218, v168
	v_add_f32_e32 v171, v170, v169
	v_fma_f32 v176, v168, s60, -v175
	v_mul_f32_e32 v172, v171, v171
	v_fmac_f32_e32 v176, 0xb102e308, v168
	v_sub_f32_e32 v168, v171, v170
	v_fmamk_f32 v174, v172, 0x3e9b6dac, v196
	v_sub_f32_e32 v168, v169, v168
	v_add_f32_e32 v169, v175, v176
	v_fmaak_f32 v174, v172, v174, 0x3f2aaada
	v_sub_f32_e32 v170, v169, v175
	v_ldexp_f32 v175, v171, 1
	v_mul_f32_e32 v171, v171, v172
	v_mul_f32_e32 v171, v171, v174
	v_add_f32_e32 v172, v175, v171
	v_sub_f32_e32 v174, v172, v175
	v_ldexp_f32 v168, v168, 1
	v_sub_f32_e32 v171, v171, v174
	v_add_f32_e32 v168, v168, v171
	v_add_f32_e32 v171, v172, v168
	v_sub_f32_e32 v172, v171, v172
	v_sub_f32_e32 v168, v168, v172
	v_add_f32_e32 v172, v169, v171
	v_sub_f32_e32 v174, v172, v169
	v_sub_f32_e32 v175, v172, v174
	v_sub_f32_e32 v170, v176, v170
	v_sub_f32_e32 v169, v169, v175
	v_sub_f32_e32 v171, v171, v174
	v_add_f32_e32 v169, v171, v169
	v_add_f32_e32 v171, v170, v168
	v_sub_f32_e32 v174, v171, v170
	v_sub_f32_e32 v175, v171, v174
	v_sub_f32_e32 v170, v170, v175
	v_sub_f32_e32 v168, v168, v174
	v_add_f32_e32 v169, v171, v169
	v_add_f32_e32 v168, v168, v170
	v_add_f32_e32 v170, v172, v169
	v_sub_f32_e32 v171, v170, v172
	v_sub_f32_e32 v169, v169, v171
	v_add_f32_e32 v168, v168, v169
	v_add_f32_e32 v168, v170, v168
	v_cndmask_b32_e64 v168, v197, v168, s[10:11]
	v_cmp_lt_f32_e64 s[10:11], |v0|, s61
	s_nop 1
	v_cndmask_b32_e64 v0, v168, v0, s[10:11]
	v_sub_f32_e32 v0, v165, v0
	global_store_dword v[166:167], v0, off

.LBB0_269:
	v_add_u32_e32 v0, v191, v208
	ds_read_b128 v[224:227], v0
	ds_read_b128 v[228:231], v0 offset:4608
	v_add_u32_e32 v0, v191, v209
	ds_read_b128 v[166:169], v0 offset:36864
	ds_read_b128 v[184:187], v0 offset:41472
	ds_read_b128 v[194:197], v0 offset:46080
	ds_read_b128 v[202:205], v0 offset:50688
	ds_read_b128 v[232:235], v212 offset:32
	ds_read_b128 v[236:239], v212 offset:4640
.Lkloop_top_1:
	s_add_i32 s5, s21, 2
	s_cmp_lt_u32 s21, 14
	s_cselect_b32 s96, s3, 0x780
	s_min_u32 s20, s21, 12
	s_lshl_b32 s20, s20, 7
	s_addk_i32 s3, 0x100
	s_cmp_gt_u32 s21, 13
	s_waitcnt lgkmcnt(5)
	v_mfma_f32_32x32x16_bf16 v[114:129], v[166:169], v[224:227], v[114:129]
	v_mfma_f32_32x32x16_bf16 v[66:81], v[166:169], v[228:231], v[66:81]
	s_waitcnt lgkmcnt(4)
	v_mfma_f32_32x32x16_bf16 v[98:113], v[184:187], v[224:227], v[98:113]
	v_mfma_f32_32x32x16_bf16 v[34:49], v[184:187], v[228:231], v[34:49]
	s_waitcnt lgkmcnt(3)
	v_mfma_f32_32x32x16_bf16 v[82:97], v[194:197], v[224:227], v[82:97]
	v_mfma_f32_32x32x16_bf16 v[18:33], v[194:197], v[228:231], v[18:33]
	s_waitcnt lgkmcnt(2)
	v_mfma_f32_32x32x16_bf16 v[50:65], v[202:205], v[224:227], v[50:65]
	ds_read_b128 v[166:169], v213 offset:36896
	ds_read_b128 v[194:197], v213 offset:41504
	v_mfma_f32_32x32x16_bf16 v[2:17], v[202:205], v[228:231], v[2:17]
	v_lshl_add_u64 v[184:185], v[178:179], 0, s[96:97]
	s_waitcnt vmcnt(1)
	ds_write_b128 v214, v[154:157] offset:9216
	v_add_co_u32_e32 v154, vcc, s91, v184
	s_waitcnt vmcnt(0)
	ds_write_b128 v214, v[142:145]
	v_addc_co_u32_e32 v155, vcc, 0, v185, vcc
	global_load_dwordx4 v[142:145], v[184:185], off
	s_nop 0
	global_load_dwordx4 v[154:157], v[154:155], off
	ds_write_b128 v214, v[134:137] offset:18432
	v_lshl_add_u64 v[134:135], v[180:181], 0, s[96:97]
	ds_write_b128 v214, v[146:149] offset:27648
	v_lshl_add_u64 v[146:147], v[182:183], 0, s[96:97]
	global_load_dwordx4 v[134:137], v[134:135], off
	s_nop 0
	global_load_dwordx4 v[146:149], v[146:147], off
	ds_read_b128 v[184:187], v213 offset:46112
	ds_read_b128 v[202:205], v213 offset:50720
	ds_read_b128 v[224:227], v212 offset:64
	ds_read_b128 v[228:231], v212 offset:4672
	s_waitcnt lgkmcnt(9)
	v_mfma_f32_32x32x16_bf16 v[114:129], v[166:169], v[232:235], v[114:129]
	v_mfma_f32_32x32x16_bf16 v[66:81], v[166:169], v[236:239], v[66:81]
	s_waitcnt lgkmcnt(8)
	v_mfma_f32_32x32x16_bf16 v[98:113], v[194:197], v[232:235], v[98:113]
	v_mfma_f32_32x32x16_bf16 v[34:49], v[194:197], v[236:239], v[34:49]
	s_waitcnt lgkmcnt(3)
	v_mfma_f32_32x32x16_bf16 v[82:97], v[184:187], v[232:235], v[82:97]
	v_mfma_f32_32x32x16_bf16 v[18:33], v[184:187], v[236:239], v[18:33]
	ds_read_b128 v[166:169], v213 offset:36928
	ds_read_b128 v[184:187], v213 offset:41536
	s_waitcnt lgkmcnt(4)
	v_mfma_f32_32x32x16_bf16 v[50:65], v[202:205], v[232:235], v[50:65]
	v_mfma_f32_32x32x16_bf16 v[2:17], v[202:205], v[236:239], v[2:17]
	v_lshl_add_u64 v[188:189], v[164:165], 0, s[96:97]
	ds_write_b128 v215, v[150:153] offset:9216
	v_add_co_u32_e32 v150, vcc, s91, v188
	ds_write_b128 v215, v[138:141]
	s_nop 0
	v_addc_co_u32_e32 v151, vcc, 0, v189, vcc
	global_load_dwordx4 v[138:141], v[188:189], off
	s_nop 0
	global_load_dwordx4 v[150:153], v[150:151], off
	ds_read_b128 v[194:197], v213 offset:46144
	ds_read_b128 v[202:205], v213 offset:50752
	ds_read_b128 v[232:235], v212 offset:96
	ds_read_b128 v[236:239], v212 offset:4704
	s_waitcnt lgkmcnt(7)
	v_mfma_f32_32x32x16_bf16 v[114:129], v[166:169], v[224:227], v[114:129]
	v_mfma_f32_32x32x16_bf16 v[66:81], v[166:169], v[228:231], v[66:81]
	s_waitcnt lgkmcnt(6)
	v_mfma_f32_32x32x16_bf16 v[98:113], v[184:187], v[224:227], v[98:113]
	v_mfma_f32_32x32x16_bf16 v[34:49], v[184:187], v[228:231], v[34:49]
	s_waitcnt lgkmcnt(3)
	v_mfma_f32_32x32x16_bf16 v[82:97], v[194:197], v[224:227], v[82:97]
	ds_read_b128 v[166:169], v213 offset:36960
	ds_read_b128 v[184:187], v213 offset:41568
	v_mfma_f32_32x32x16_bf16 v[18:33], v[194:197], v[228:231], v[18:33]
	s_waitcnt lgkmcnt(4)
	v_mfma_f32_32x32x16_bf16 v[50:65], v[202:205], v[224:227], v[50:65]
	v_mfma_f32_32x32x16_bf16 v[2:17], v[202:205], v[228:231], v[2:17]
	ds_write_b128 v215, v[130:133] offset:18432
	v_add_co_u32_e32 v130, vcc, s1, v188
	ds_write_b128 v215, v[158:161] offset:27648
	s_nop 0
	v_addc_co_u32_e32 v131, vcc, 0, v189, vcc
	v_add_co_u32_e32 v158, vcc, s76, v188
	global_load_dwordx4 v[130:133], v[130:131], off
	s_nop 0
	v_addc_co_u32_e32 v159, vcc, 0, v189, vcc
	global_load_dwordx4 v[158:161], v[158:159], off
	ds_read_b128 v[194:197], v213 offset:46176
	ds_read_b128 v[202:205], v213 offset:50784
	s_waitcnt lgkmcnt(5)
	v_mfma_f32_32x32x16_bf16 v[114:129], v[166:169], v[232:235], v[114:129]
	v_mfma_f32_32x32x16_bf16 v[66:81], v[166:169], v[236:239], v[66:81]
	s_waitcnt lgkmcnt(4)
	v_mfma_f32_32x32x16_bf16 v[98:113], v[184:187], v[232:235], v[98:113]
	v_mfma_f32_32x32x16_bf16 v[34:49], v[184:187], v[236:239], v[34:49]
	s_waitcnt lgkmcnt(0)
	s_barrier
	ds_read_b128 v[224:227], v216
	ds_read_b128 v[228:231], v216 offset:4608
	ds_read_b128 v[166:169], v217
	ds_read_b128 v[184:187], v217 offset:4608
	v_mfma_f32_32x32x16_bf16 v[82:97], v[194:197], v[232:235], v[82:97]
	v_mfma_f32_32x32x16_bf16 v[18:33], v[194:197], v[236:239], v[18:33]
	ds_read_b128 v[194:197], v217 offset:9216
	v_mfma_f32_32x32x16_bf16 v[50:65], v[202:205], v[232:235], v[50:65]
	v_mfma_f32_32x32x16_bf16 v[2:17], v[202:205], v[236:239], v[2:17]
	ds_read_b128 v[202:205], v217 offset:13824
	v_add_u32_e32 v0, v210, v190
	ds_read_b128 v[232:235], v0 offset:32
	ds_read_b128 v[236:239], v218 offset:32
	s_waitcnt lgkmcnt(5)
	v_mfma_f32_32x32x16_bf16 v[114:129], v[166:169], v[224:227], v[114:129]
	v_mfma_f32_32x32x16_bf16 v[66:81], v[166:169], v[228:231], v[66:81]
	s_waitcnt lgkmcnt(4)
	v_mfma_f32_32x32x16_bf16 v[98:113], v[184:187], v[224:227], v[98:113]
	v_mfma_f32_32x32x16_bf16 v[34:49], v[184:187], v[228:231], v[34:49]
	s_waitcnt lgkmcnt(3)
	v_mfma_f32_32x32x16_bf16 v[82:97], v[194:197], v[224:227], v[82:97]
	v_add_u32_e32 v223, v211, v190
	v_mfma_f32_32x32x16_bf16 v[18:33], v[194:197], v[228:231], v[18:33]
	s_waitcnt lgkmcnt(2)
	v_mfma_f32_32x32x16_bf16 v[50:65], v[202:205], v[224:227], v[50:65]
	ds_read_b128 v[166:169], v223 offset:32
	ds_read_b128 v[194:197], v219 offset:32
	v_mfma_f32_32x32x16_bf16 v[2:17], v[202:205], v[228:231], v[2:17]
	s_mov_b32 s21, s97
	v_lshl_add_u64 v[184:185], v[178:179], 0, s[20:21]
	s_waitcnt vmcnt(6)
	ds_write_b128 v222, v[154:157] offset:9216
	v_add_co_u32_e32 v154, vcc, s91, v184
	ds_write_b128 v222, v[142:145]
	s_nop 0
	v_addc_co_u32_e32 v155, vcc, 0, v185, vcc
	global_load_dwordx4 v[142:145], v[184:185], off offset:384
	s_nop 0
	global_load_dwordx4 v[154:157], v[154:155], off offset:384
	s_waitcnt vmcnt(7)
	ds_write_b128 v222, v[134:137] offset:18432
	v_add_co_u32_e32 v134, vcc, s1, v184
	s_waitcnt vmcnt(6)
	ds_write_b128 v222, v[146:149] offset:27648
	v_addc_co_u32_e32 v135, vcc, 0, v185, vcc
	v_lshl_add_u64 v[146:147], v[182:183], 0, s[20:21]
	global_load_dwordx4 v[134:137], v[134:135], off offset:384
	s_nop 0
	global_load_dwordx4 v[146:149], v[146:147], off offset:384
	ds_read_b128 v[184:187], v220 offset:32
	ds_read_b128 v[202:205], v221 offset:32
	ds_read_b128 v[224:227], v0 offset:64
	ds_read_b128 v[228:231], v218 offset:64
	s_waitcnt lgkmcnt(9)
	v_mfma_f32_32x32x16_bf16 v[114:129], v[166:169], v[232:235], v[114:129]
	v_mfma_f32_32x32x16_bf16 v[66:81], v[166:169], v[236:239], v[66:81]
	s_waitcnt lgkmcnt(8)
	v_mfma_f32_32x32x16_bf16 v[98:113], v[194:197], v[232:235], v[98:113]
	v_mfma_f32_32x32x16_bf16 v[34:49], v[194:197], v[236:239], v[34:49]
	s_waitcnt lgkmcnt(3)
	v_mfma_f32_32x32x16_bf16 v[82:97], v[184:187], v[232:235], v[82:97]
	v_mfma_f32_32x32x16_bf16 v[18:33], v[184:187], v[236:239], v[18:33]
	ds_read_b128 v[166:169], v223 offset:64
	ds_read_b128 v[184:187], v219 offset:64
	s_waitcnt lgkmcnt(4)
	v_mfma_f32_32x32x16_bf16 v[50:65], v[202:205], v[232:235], v[50:65]
	v_mfma_f32_32x32x16_bf16 v[2:17], v[202:205], v[236:239], v[2:17]
	v_lshl_add_u64 v[188:189], v[164:165], 0, s[20:21]
	s_waitcnt vmcnt(6)
	ds_write_b128 v222, v[150:153] offset:46080
	v_add_co_u32_e32 v150, vcc, s91, v188
	ds_write_b128 v222, v[138:141] offset:36864
	s_nop 0
	v_addc_co_u32_e32 v151, vcc, 0, v189, vcc
	global_load_dwordx4 v[138:141], v[188:189], off offset:384
	s_nop 0
	global_load_dwordx4 v[150:153], v[150:151], off offset:384
	ds_read_b128 v[194:197], v220 offset:64
	ds_read_b128 v[202:205], v221 offset:64
	ds_read_b128 v[232:235], v0 offset:96
	ds_read_b128 v[236:239], v218 offset:96
	s_waitcnt lgkmcnt(7)
	v_mfma_f32_32x32x16_bf16 v[114:129], v[166:169], v[224:227], v[114:129]
	v_mfma_f32_32x32x16_bf16 v[66:81], v[166:169], v[228:231], v[66:81]
	s_waitcnt lgkmcnt(6)
	v_mfma_f32_32x32x16_bf16 v[98:113], v[184:187], v[224:227], v[98:113]
	v_mfma_f32_32x32x16_bf16 v[34:49], v[184:187], v[228:231], v[34:49]
	s_waitcnt lgkmcnt(3)
	v_mfma_f32_32x32x16_bf16 v[82:97], v[194:197], v[224:227], v[82:97]
	ds_read_b128 v[166:169], v223 offset:96
	ds_read_b128 v[184:187], v219 offset:96
	v_mfma_f32_32x32x16_bf16 v[18:33], v[194:197], v[228:231], v[18:33]
	s_waitcnt lgkmcnt(4)
	v_mfma_f32_32x32x16_bf16 v[50:65], v[202:205], v[224:227], v[50:65]
	v_mfma_f32_32x32x16_bf16 v[2:17], v[202:205], v[228:231], v[2:17]
	s_waitcnt vmcnt(7)
	ds_write_b128 v222, v[130:133] offset:55296
	v_add_co_u32_e32 v130, vcc, s1, v188
	s_waitcnt vmcnt(6)
	ds_write_b128 v222, v[158:161] offset:64512
	v_addc_co_u32_e32 v131, vcc, 0, v189, vcc
	v_add_co_u32_e32 v158, vcc, s76, v188
	global_load_dwordx4 v[130:133], v[130:131], off offset:384
	s_nop 0
	v_addc_co_u32_e32 v159, vcc, 0, v189, vcc
	global_load_dwordx4 v[158:161], v[158:159], off offset:384
	ds_read_b128 v[194:197], v220 offset:96
	ds_read_b128 v[202:205], v221 offset:96
	s_waitcnt lgkmcnt(5)
	v_mfma_f32_32x32x16_bf16 v[114:129], v[166:169], v[232:235], v[114:129]
	v_mfma_f32_32x32x16_bf16 v[66:81], v[166:169], v[236:239], v[66:81]
	s_waitcnt lgkmcnt(4)
	v_mfma_f32_32x32x16_bf16 v[98:113], v[184:187], v[232:235], v[98:113]
	v_mfma_f32_32x32x16_bf16 v[34:49], v[184:187], v[236:239], v[34:49]
	s_waitcnt lgkmcnt(0)
	s_barrier
	v_add_u32_e32 v0, v191, v208
	ds_read_b128 v[224:227], v0
	ds_read_b128 v[228:231], v0 offset:4608
	v_add_u32_e32 v0, v191, v209
	ds_read_b128 v[166:169], v0 offset:36864
	ds_read_b128 v[184:187], v0 offset:41472
	v_mfma_f32_32x32x16_bf16 v[82:97], v[194:197], v[232:235], v[82:97]
	v_mfma_f32_32x32x16_bf16 v[18:33], v[194:197], v[236:239], v[18:33]
	ds_read_b128 v[194:197], v0 offset:46080
	v_mfma_f32_32x32x16_bf16 v[50:65], v[202:205], v[232:235], v[50:65]
	v_mfma_f32_32x32x16_bf16 v[2:17], v[202:205], v[236:239], v[2:17]
	ds_read_b128 v[202:205], v0 offset:50688
	ds_read_b128 v[232:235], v212 offset:32
	ds_read_b128 v[236:239], v212 offset:4640
	s_mov_b32 s21, s5
	s_cbranch_scc0 .Lkloop_top_1
; #define RL_LOAD(XV, G) { constexpr int mt__ = (G) >> 2, half__ = ((G) >> 1) & 1, nt__ = (G) & 1; \
;     _Pragma("unroll") for (int gq = 0; gq < 4; ++gq) XV[gq] = *(const f32x4*)(xin + rbase + (size_t)mt__ * 32 * 1024 + half__ * 64 + nt__ * 32 + 4 * gq); }
; #define RL_FOLD(XV, G, SM, SQ) { constexpr int mt__ = (G) >> 2, half__ = ((G) >> 1) & 1, nt__ = (G) & 1; \
;     _Pragma("unroll") for (int gq = 0; gq < 4; ++gq) _Pragma("unroll") for (int jj = 0; jj < 4; ++jj) { \
;       const float y = ALPHA * XV[gq][jj] + acc[half__][nt__][mt__][4 * gq + jj]; acc[half__][nt__][mt__][4 * gq + jj] = y; SM += y; SQ += y * y; } }
; #define SB __builtin_amdgcn_sched_barrier(0)
;   DI void full(const int mt_, const int nt_, f32x16 (&acc)[2][2][2], const int tw, const int fw, const int r, const int hh, char* lds, const int tid) const {
;     ...
;     const size_t rbase = (size_t)(mt_ * 256 + tw * 64 + r) * 1024 + nt_ * 256 + fw * 128 + 16 * hh;
;     f32x4 xa[4], xc[4], xe[4];
;     ...
;     float sm0 = 0.f, sq0 = 0.f, sm1 = 0.f, sq1 = 0.f;
;     RL_LOAD(xa, 0); RL_LOAD(xc, 1); RL_LOAD(xe, 2); SB;
;     RL_FOLD(xa, 0, sm0, sq0); SB; RL_LOAD(xa, 3); SB;
;     RL_FOLD(xc, 1, sm0, sq0); SB; RL_LOAD(xc, 4); SB;
;     RL_FOLD(xe, 2, sm0, sq0); SB; RL_LOAD(xe, 5); SB;
;     RL_FOLD(xa, 3, sm0, sq0); SB; RL_LOAD(xa, 6); SB;
;     RL_FOLD(xc, 4, sm1, sq1); SB; RL_LOAD(xc, 7); SB;
	s_waitcnt lgkmcnt(0)
	v_mov_b32_e32 v184, v192
	s_waitcnt vmcnt(1)
	v_ashrrev_i32_e32 v130, 1, v184
	v_and_b32_e32 v223, 0xdf, v184
	v_and_b32_e32 v182, 0xffffff80, v130
	v_or_b32_e32 v0, s4, v223
	v_ashrrev_i32_e32 v183, 31, v182
	v_bfe_u32 v224, v184, 5, 1
	v_lshl_add_u64 v[130:131], v[182:183], 2, s[18:19]
	v_lshlrev_b64 v[132:133], 12, v[0:1]
	v_lshl_add_u64 v[130:131], v[130:131], 0, v[132:133]
	v_lshlrev_b32_e32 v132, 6, v224
	v_mov_b32_e32 v133, v1
	v_lshl_add_u64 v[186:187], v[130:131], 0, v[132:133]
	global_load_dwordx4 v[130:133], v[186:187], off offset:48
	global_load_dwordx4 v[134:137], v[186:187], off offset:32
	global_load_dwordx4 v[138:141], v[186:187], off offset:16
	global_load_dwordx4 v[142:145], v[186:187], off
	global_load_dwordx4 v[194:197], v[186:187], off offset:176
	global_load_dwordx4 v[202:205], v[186:187], off offset:160
	global_load_dwordx4 v[226:229], v[186:187], off offset:144
	global_load_dwordx4 v[146:149], v[186:187], off offset:128
	global_load_dwordx4 v[230:233], v[186:187], off offset:304
	global_load_dwordx4 v[234:237], v[186:187], off offset:288
	global_load_dwordx4 v[238:241], v[186:187], off offset:272
	global_load_dwordx4 v[242:245], v[186:187], off offset:256
	s_waitcnt vmcnt(8)
	v_pk_fma_f32 v[178:179], v[142:143], s[0:1], v[114:115] op_sel_hi:[1,0,1]
	v_pk_fma_f32 v[180:181], v[144:145], s[0:1], v[116:117] op_sel_hi:[1,0,1]
	v_add_f32_e32 v114, 0, v178
	v_add_f32_e32 v142, v179, v114
	v_mul_f32_e32 v114, v179, v179
	v_pk_fma_f32 v[114:115], v[178:179], v[178:179], v[114:115] op_sel_hi:[1,1,0]
	v_add_f32_e32 v116, v180, v142
	v_pk_fma_f32 v[114:115], v[180:181], v[180:181], v[114:115]
	v_add_f32_e32 v117, v181, v116
	v_mul_f32_e32 v116, v181, v181
	v_pk_fma_f32 v[158:159], v[138:139], s[0:1], v[118:119] op_sel_hi:[1,0,1]
	v_pk_add_f32 v[114:115], v[116:117], v[114:115] op_sel_hi:[0,1]
	v_add_f32_e32 v116, v158, v117
	v_pk_fma_f32 v[114:115], v[158:159], v[158:159], v[114:115]
	v_add_f32_e32 v117, v159, v116
	v_mul_f32_e32 v116, v159, v159
	v_pk_fma_f32 v[160:161], v[140:141], s[0:1], v[120:121] op_sel_hi:[1,0,1]
	v_pk_add_f32 v[114:115], v[116:117], v[114:115] op_sel_hi:[0,1]
	v_add_f32_e32 v116, v160, v117
	v_pk_fma_f32 v[114:115], v[160:161], v[160:161], v[114:115]
	v_add_f32_e32 v117, v161, v116
	v_mul_f32_e32 v116, v161, v161
	v_pk_fma_f32 v[154:155], v[134:135], s[0:1], v[122:123] op_sel_hi:[1,0,1]
	v_pk_add_f32 v[114:115], v[116:117], v[114:115] op_sel_hi:[0,1]
	v_add_f32_e32 v116, v154, v117
	v_pk_fma_f32 v[114:115], v[154:155], v[154:155], v[114:115]
	v_add_f32_e32 v117, v155, v116
	v_mul_f32_e32 v116, v155, v155
	v_pk_fma_f32 v[156:157], v[136:137], s[0:1], v[124:125] op_sel_hi:[1,0,1]
	v_pk_add_f32 v[114:115], v[116:117], v[114:115] op_sel_hi:[0,1]
	v_add_f32_e32 v116, v156, v117
	v_pk_fma_f32 v[114:115], v[156:157], v[156:157], v[114:115]
	v_add_f32_e32 v124, v157, v116
	v_mul_f32_e32 v116, v157, v157
	v_pk_add_f32 v[114:115], v[116:117], v[114:115] op_sel_hi:[0,1]
	v_pk_fma_f32 v[152:153], v[130:131], s[0:1], v[126:127] op_sel_hi:[1,0,1]
	v_pk_fma_f32 v[150:151], v[132:133], s[0:1], v[128:129] op_sel_hi:[1,0,1]
	v_pk_fma_f32 v[114:115], v[152:153], v[152:153], v[114:115]
	v_mul_f32_e32 v116, v153, v153
	v_pk_add_f32 v[114:115], v[116:117], v[114:115] op_sel_hi:[0,1]
	v_pk_fma_f32 v[114:115], v[150:151], v[150:151], v[114:115]
	v_mul_f32_e32 v116, v151, v151
	v_pk_add_f32 v[118:119], v[116:117], v[114:115] op_sel_hi:[0,1]
	global_load_dwordx4 v[114:117], v[186:187], off offset:432
	global_load_dwordx4 v[246:249], v[186:187], off offset:416
	global_load_dwordx4 v[250:253], v[186:187], off offset:400
	global_load_dwordx4 v[120:123], v[186:187], off offset:384
	v_add_f32_e32 v124, v152, v124
	v_add_f32_e32 v124, v153, v124
	v_add_f32_e32 v124, v150, v124
	v_add_f32_e32 v124, v151, v124
	s_waitcnt vmcnt(8)
	v_pk_fma_f32 v[144:145], v[146:147], s[0:1], v[98:99] op_sel_hi:[1,0,1]
	v_pk_fma_f32 v[148:149], v[148:149], s[0:1], v[100:101] op_sel_hi:[1,0,1]
	v_add_f32_e32 v124, v144, v124
	v_pk_fma_f32 v[98:99], v[144:145], v[144:145], v[118:119]
	v_add_f32_e32 v119, v145, v124
	v_mul_f32_e32 v118, v145, v145
	v_pk_add_f32 v[98:99], v[118:119], v[98:99] op_sel_hi:[0,1]
	v_add_f32_e32 v100, v148, v119
	v_pk_fma_f32 v[98:99], v[148:149], v[148:149], v[98:99]
	v_add_f32_e32 v101, v149, v100
	v_mul_f32_e32 v100, v149, v149
	v_pk_fma_f32 v[138:139], v[226:227], s[0:1], v[102:103] op_sel_hi:[1,0,1]
	v_pk_add_f32 v[98:99], v[100:101], v[98:99] op_sel_hi:[0,1]
	v_add_f32_e32 v100, v138, v101
	v_pk_fma_f32 v[98:99], v[138:139], v[138:139], v[98:99]
	v_add_f32_e32 v101, v139, v100
	v_mul_f32_e32 v100, v139, v139
	v_pk_fma_f32 v[146:147], v[228:229], s[0:1], v[104:105] op_sel_hi:[1,0,1]
	v_pk_add_f32 v[98:99], v[100:101], v[98:99] op_sel_hi:[0,1]
	v_add_f32_e32 v100, v146, v101
	v_pk_fma_f32 v[98:99], v[146:147], v[146:147], v[98:99]
	v_add_f32_e32 v101, v147, v100
	v_mul_f32_e32 v100, v147, v147
	v_pk_fma_f32 v[130:131], v[202:203], s[0:1], v[106:107] op_sel_hi:[1,0,1]
	v_pk_add_f32 v[98:99], v[100:101], v[98:99] op_sel_hi:[0,1]
	v_add_f32_e32 v100, v130, v101
	v_pk_fma_f32 v[98:99], v[130:131], v[130:131], v[98:99]
	v_add_f32_e32 v101, v131, v100
	v_mul_f32_e32 v100, v131, v131
	v_pk_fma_f32 v[140:141], v[204:205], s[0:1], v[108:109] op_sel_hi:[1,0,1]
	v_pk_add_f32 v[98:99], v[100:101], v[98:99] op_sel_hi:[0,1]
	v_add_f32_e32 v100, v140, v101
	v_pk_fma_f32 v[98:99], v[140:141], v[140:141], v[98:99]
	v_add_f32_e32 v106, v141, v100
	v_mul_f32_e32 v100, v141, v141
	v_pk_add_f32 v[102:103], v[100:101], v[98:99] op_sel_hi:[0,1]
	v_pk_fma_f32 v[124:125], v[194:195], s[0:1], v[110:111] op_sel_hi:[1,0,1]
	v_pk_fma_f32 v[134:135], v[196:197], s[0:1], v[112:113] op_sel_hi:[1,0,1]
	v_add_co_u32_e32 v188, vcc, s91, v186
	s_mov_b64 s[20:21], 0x20000
	s_nop 0
	v_addc_co_u32_e32 v189, vcc, 0, v187, vcc
	v_lshl_add_u64 v[104:105], v[186:187], 0, s[20:21]
	global_load_dwordx4 v[194:197], v[188:189], off
	global_load_dwordx4 v[98:101], v[104:105], off offset:48
	global_load_dwordx4 v[202:205], v[104:105], off offset:32
	global_load_dwordx4 v[226:229], v[104:105], off offset:16
	v_add_f32_e32 v104, v124, v106
	v_pk_fma_f32 v[102:103], v[124:125], v[124:125], v[102:103]
	v_add_f32_e32 v105, v125, v104
	v_mul_f32_e32 v104, v125, v125
	v_pk_add_f32 v[102:103], v[104:105], v[102:103] op_sel_hi:[0,1]
	v_add_f32_e32 v104, v134, v105
	v_pk_fma_f32 v[102:103], v[134:135], v[134:135], v[102:103]
	v_add_f32_e32 v105, v135, v104
	v_mul_f32_e32 v104, v135, v135
	v_pk_add_f32 v[102:103], v[104:105], v[102:103] op_sel_hi:[0,1]
	s_waitcnt vmcnt(8)
; #define RL_LOAD(XV, G) { constexpr int mt__ = (G) >> 2, half__ = ((G) >> 1) & 1, nt__ = (G) & 1; \
;     _Pragma("unroll") for (int gq = 0; gq < 4; ++gq) XV[gq] = *(const f32x4*)(xin + rbase + (size_t)mt__ * 32 * 1024 + half__ * 64 + nt__ * 32 + 4 * gq); }
; #define RL_FOLD(XV, G, SM, SQ) { constexpr int mt__ = (G) >> 2, half__ = ((G) >> 1) & 1, nt__ = (G) & 1; \
;     _Pragma("unroll") for (int gq = 0; gq < 4; ++gq) _Pragma("unroll") for (int jj = 0; jj < 4; ++jj) { \
;       const float y = ALPHA * XV[gq][jj] + acc[half__][nt__][mt__][4 * gq + jj]; acc[half__][nt__][mt__][4 * gq + jj] = y; SM += y; SQ += y * y; } }
; #define SB __builtin_amdgcn_sched_barrier(0)
;   DI void full(const int mt_, const int nt_, f32x16 (&acc)[2][2][2], const int tw, const int fw, const int r, const int hh, char* lds, const int tid) const {
;     ...
;     float sm0 = 0.f, sq0 = 0.f, sm1 = 0.f, sq1 = 0.f;
;     RL_LOAD(xa, 0); RL_LOAD(xc, 1); RL_LOAD(xe, 2); SB;
;     RL_FOLD(xa, 0, sm0, sq0); SB; RL_LOAD(xa, 3); SB;
;     RL_FOLD(xc, 1, sm0, sq0); SB; RL_LOAD(xc, 4); SB;
;     RL_FOLD(xe, 2, sm0, sq0); SB; RL_LOAD(xe, 5); SB;
;     RL_FOLD(xa, 3, sm0, sq0); SB; RL_LOAD(xa, 6); SB;
;     RL_FOLD(xc, 4, sm1, sq1); SB; RL_LOAD(xc, 7); SB;
;     RL_FOLD(xe, 5, sm1, sq1); SB;
;     RL_FOLD(xa, 6, sm1, sq1); SB;
;     RL_FOLD(xc, 7, sm1, sq1);
	v_pk_fma_f32 v[132:133], v[242:243], s[0:1], v[82:83] op_sel_hi:[1,0,1]
	v_pk_fma_f32 v[142:143], v[244:245], s[0:1], v[84:85] op_sel_hi:[1,0,1]
	v_add_f32_e32 v104, v132, v105
	v_pk_fma_f32 v[82:83], v[132:133], v[132:133], v[102:103]
	v_add_f32_e32 v103, v133, v104
	v_mul_f32_e32 v102, v133, v133
	v_pk_add_f32 v[82:83], v[102:103], v[82:83] op_sel_hi:[0,1]
	v_add_f32_e32 v84, v142, v103
	v_pk_fma_f32 v[82:83], v[142:143], v[142:143], v[82:83]
	v_add_f32_e32 v85, v143, v84
	v_mul_f32_e32 v84, v143, v143
	v_pk_fma_f32 v[126:127], v[238:239], s[0:1], v[86:87] op_sel_hi:[1,0,1]
	v_pk_add_f32 v[82:83], v[84:85], v[82:83] op_sel_hi:[0,1]
	v_add_f32_e32 v84, v126, v85
	v_pk_fma_f32 v[82:83], v[126:127], v[126:127], v[82:83]
	v_add_f32_e32 v85, v127, v84
	v_mul_f32_e32 v84, v127, v127
	v_pk_fma_f32 v[136:137], v[240:241], s[0:1], v[88:89] op_sel_hi:[1,0,1]
	v_pk_add_f32 v[82:83], v[84:85], v[82:83] op_sel_hi:[0,1]
	v_add_f32_e32 v84, v136, v85
	v_pk_fma_f32 v[82:83], v[136:137], v[136:137], v[82:83]
	v_add_f32_e32 v85, v137, v84
	v_mul_f32_e32 v84, v137, v137
	v_pk_fma_f32 v[112:113], v[234:235], s[0:1], v[90:91] op_sel_hi:[1,0,1]
	v_pk_add_f32 v[82:83], v[84:85], v[82:83] op_sel_hi:[0,1]
	v_add_f32_e32 v84, v112, v85
	v_pk_fma_f32 v[82:83], v[112:113], v[112:113], v[82:83]
	v_add_f32_e32 v85, v113, v84
	v_mul_f32_e32 v84, v113, v113
	v_pk_fma_f32 v[128:129], v[236:237], s[0:1], v[92:93] op_sel_hi:[1,0,1]
	v_pk_add_f32 v[82:83], v[84:85], v[82:83] op_sel_hi:[0,1]
	v_add_f32_e32 v84, v128, v85
	v_pk_fma_f32 v[82:83], v[128:129], v[128:129], v[82:83]
	v_add_f32_e32 v90, v129, v84
	v_mul_f32_e32 v84, v129, v129
	v_pk_add_f32 v[86:87], v[84:85], v[82:83] op_sel_hi:[0,1]
	v_pk_fma_f32 v[106:107], v[230:231], s[0:1], v[94:95] op_sel_hi:[1,0,1]
	v_pk_fma_f32 v[118:119], v[232:233], s[0:1], v[96:97] op_sel_hi:[1,0,1]
	s_mov_b64 s[20:21], 0x20080
	v_lshl_add_u64 v[88:89], v[186:187], 0, s[20:21]
	global_load_dwordx4 v[82:85], v[88:89], off offset:48
	global_load_dwordx4 v[230:233], v[88:89], off offset:32
	global_load_dwordx4 v[234:237], v[188:189], off offset:128
	global_load_dwordx4 v[238:241], v[88:89], off offset:16
	v_add_f32_e32 v88, v106, v90
	v_pk_fma_f32 v[86:87], v[106:107], v[106:107], v[86:87]
	v_add_f32_e32 v89, v107, v88
	v_mul_f32_e32 v88, v107, v107
	v_pk_add_f32 v[86:87], v[88:89], v[86:87] op_sel_hi:[0,1]
	v_add_f32_e32 v88, v118, v89
	v_pk_fma_f32 v[86:87], v[118:119], v[118:119], v[86:87]
	v_add_f32_e32 v89, v119, v88
	v_mul_f32_e32 v88, v119, v119
	v_pk_add_f32 v[86:87], v[88:89], v[86:87] op_sel_hi:[0,1]
	s_waitcnt vmcnt(8)
	v_pk_fma_f32 v[104:105], v[120:121], s[0:1], v[50:51] op_sel_hi:[1,0,1]
	v_pk_fma_f32 v[122:123], v[122:123], s[0:1], v[52:53] op_sel_hi:[1,0,1]
	v_add_f32_e32 v88, v104, v89
	v_pk_fma_f32 v[50:51], v[104:105], v[104:105], v[86:87]
	v_add_f32_e32 v87, v105, v88
	v_mul_f32_e32 v86, v105, v105
	v_add_f32_e32 v52, v122, v87
	v_pk_add_f32 v[50:51], v[86:87], v[50:51] op_sel_hi:[0,1]
	v_add_f32_e32 v52, v123, v52
	v_pk_fma_f32 v[102:103], v[250:251], s[0:1], v[54:55] op_sel_hi:[1,0,1]
	v_pk_fma_f32 v[50:51], v[122:123], v[122:123], v[50:51]
	v_add_f32_e32 v55, v102, v52
	v_mul_f32_e32 v54, v123, v123
	v_mov_b32_e32 v52, v102
	v_mov_b32_e32 v53, v123
	v_pk_add_f32 v[50:51], v[54:55], v[50:51] op_sel_hi:[0,1]
	v_pk_fma_f32 v[50:51], v[52:53], v[52:53], v[50:51]
	v_add_f32_e32 v52, v103, v55
	v_pk_fma_f32 v[120:121], v[252:253], s[0:1], v[56:57] op_sel_hi:[1,0,1]
	v_mul_f32_e32 v54, v103, v103
	v_add_f32_e32 v55, v120, v52
	v_mov_b32_e32 v52, v120
	v_mov_b32_e32 v53, v103
	v_pk_add_f32 v[50:51], v[54:55], v[50:51] op_sel_hi:[0,1]
	v_pk_fma_f32 v[50:51], v[52:53], v[52:53], v[50:51]
	v_add_f32_e32 v52, v121, v55
	v_pk_fma_f32 v[94:95], v[246:247], s[0:1], v[58:59] op_sel_hi:[1,0,1]
	v_mul_f32_e32 v54, v121, v121
	v_add_f32_e32 v55, v94, v52
	v_mov_b32_e32 v52, v94
	v_mov_b32_e32 v53, v121
	v_pk_add_f32 v[50:51], v[54:55], v[50:51] op_sel_hi:[0,1]
	v_pk_fma_f32 v[50:51], v[52:53], v[52:53], v[50:51]
	v_add_f32_e32 v52, v95, v55
	v_pk_fma_f32 v[108:109], v[248:249], s[0:1], v[60:61] op_sel_hi:[1,0,1]
	v_mul_f32_e32 v54, v95, v95
	v_add_f32_e32 v55, v108, v52
	v_mov_b32_e32 v52, v108
	v_mov_b32_e32 v53, v95
	v_pk_add_f32 v[50:51], v[54:55], v[50:51] op_sel_hi:[0,1]
	v_pk_fma_f32 v[50:51], v[52:53], v[52:53], v[50:51]
	v_pk_fma_f32 v[96:97], v[114:115], s[0:1], v[62:63] op_sel_hi:[1,0,1]
	v_mul_f32_e32 v54, v109, v109
	v_pk_fma_f32 v[110:111], v[116:117], s[0:1], v[64:65] op_sel_hi:[1,0,1]
	v_add_f32_e32 v58, v109, v55
	v_pk_add_f32 v[50:51], v[54:55], v[50:51] op_sel_hi:[0,1]
	v_mov_b32_e32 v54, v110
	v_mov_b32_e32 v55, v97
	v_mov_b32_e32 v52, v96
	v_mov_b32_e32 v53, v109
	v_pk_mul_f32 v[114:115], v[110:111], v[110:111]
	s_mov_b64 s[20:21], 0x20100
	v_lshl_add_u64 v[56:57], v[186:187], 0, s[20:21]
	global_load_dwordx4 v[242:245], v[56:57], off offset:48
	global_load_dwordx4 v[246:249], v[56:57], off offset:32
	global_load_dwordx4 v[250:253], v[188:189], off offset:256
	global_load_dwordx4 v[166:169], v[56:57], off offset:16
	v_add_f32_e32 v56, v96, v58
	v_add_f32_e32 v56, v97, v56
	v_add_f32_e32 v114, v110, v56
	s_waitcnt vmcnt(11)
	v_pk_fma_f32 v[90:91], v[194:195], s[0:1], v[66:67] op_sel_hi:[1,0,1]
	v_pk_fma_f32 v[92:93], v[196:197], s[0:1], v[68:69] op_sel_hi:[1,0,1]
	v_add_f32_e32 v56, 0, v90
	v_add_f32_e32 v58, v91, v56
	v_mul_f32_e32 v56, v91, v91
	v_pk_fma_f32 v[56:57], v[90:91], v[90:91], v[56:57] op_sel_hi:[1,1,0]
	v_add_f32_e32 v58, v92, v58
	v_pk_fma_f32 v[56:57], v[92:93], v[92:93], v[56:57]
	v_add_f32_e32 v59, v93, v58
	v_mul_f32_e32 v58, v93, v93
	s_waitcnt vmcnt(8)
; #define RL_LOAD(XV, G) { constexpr int mt__ = (G) >> 2, half__ = ((G) >> 1) & 1, nt__ = (G) & 1; \
;     _Pragma("unroll") for (int gq = 0; gq < 4; ++gq) XV[gq] = *(const f32x4*)(xin + rbase + (size_t)mt__ * 32 * 1024 + half__ * 64 + nt__ * 32 + 4 * gq); }
; #define RL_FOLD(XV, G, SM, SQ) { constexpr int mt__ = (G) >> 2, half__ = ((G) >> 1) & 1, nt__ = (G) & 1; \
;     _Pragma("unroll") for (int gq = 0; gq < 4; ++gq) _Pragma("unroll") for (int jj = 0; jj < 4; ++jj) { \
;       const float y = ALPHA * XV[gq][jj] + acc[half__][nt__][mt__][4 * gq + jj]; acc[half__][nt__][mt__][4 * gq + jj] = y; SM += y; SQ += y * y; } }
; #define SB __builtin_amdgcn_sched_barrier(0)
;   DI void full(const int mt_, const int nt_, f32x16 (&acc)[2][2][2], const int tw, const int fw, const int r, const int hh, char* lds, const int tid) const {
;     ...
;     float sm0 = 0.f, sq0 = 0.f, sm1 = 0.f, sq1 = 0.f;
;     RL_LOAD(xa, 0); RL_LOAD(xc, 1); RL_LOAD(xe, 2); SB;
;     RL_FOLD(xa, 0, sm0, sq0); SB; RL_LOAD(xa, 3); SB;
;     RL_FOLD(xc, 1, sm0, sq0); SB; RL_LOAD(xc, 4); SB;
;     RL_FOLD(xe, 2, sm0, sq0); SB; RL_LOAD(xe, 5); SB;
;     RL_FOLD(xa, 3, sm0, sq0); SB; RL_LOAD(xa, 6); SB;
;     RL_FOLD(xc, 4, sm1, sq1); SB; RL_LOAD(xc, 7); SB;
;     RL_FOLD(xe, 5, sm1, sq1); SB;
;     RL_FOLD(xa, 6, sm1, sq1); SB;
;     RL_FOLD(xc, 7, sm1, sq1);
	v_pk_fma_f32 v[86:87], v[226:227], s[0:1], v[70:71] op_sel_hi:[1,0,1]
	v_pk_add_f32 v[56:57], v[58:59], v[56:57] op_sel_hi:[0,1]
	v_add_f32_e32 v58, v86, v59
	v_pk_fma_f32 v[56:57], v[86:87], v[86:87], v[56:57]
	v_add_f32_e32 v59, v87, v58
	v_mul_f32_e32 v58, v87, v87
	v_pk_fma_f32 v[88:89], v[228:229], s[0:1], v[72:73] op_sel_hi:[1,0,1]
	v_pk_add_f32 v[56:57], v[58:59], v[56:57] op_sel_hi:[0,1]
	v_add_f32_e32 v58, v88, v59
	v_pk_fma_f32 v[56:57], v[88:89], v[88:89], v[56:57]
	v_add_f32_e32 v59, v89, v58
	v_mul_f32_e32 v58, v89, v89
	v_pk_fma_f32 v[70:71], v[202:203], s[0:1], v[74:75] op_sel_hi:[1,0,1]
	v_pk_add_f32 v[56:57], v[58:59], v[56:57] op_sel_hi:[0,1]
	v_add_f32_e32 v58, v70, v59
	v_pk_fma_f32 v[56:57], v[70:71], v[70:71], v[56:57]
	v_add_f32_e32 v59, v71, v58
	v_mul_f32_e32 v58, v71, v71
	v_pk_fma_f32 v[72:73], v[204:205], s[0:1], v[76:77] op_sel_hi:[1,0,1]
	v_pk_add_f32 v[56:57], v[58:59], v[56:57] op_sel_hi:[0,1]
	v_add_f32_e32 v58, v72, v59
	v_pk_fma_f32 v[56:57], v[72:73], v[72:73], v[56:57]
	v_add_f32_e32 v59, v73, v58
	v_mul_f32_e32 v58, v73, v73
	v_pk_fma_f32 v[50:51], v[52:53], v[52:53], v[50:51]
	v_mul_f32_e32 v52, v97, v97
	v_pk_add_f32 v[56:57], v[58:59], v[56:57] op_sel_hi:[0,1]
	v_pk_fma_f32 v[68:69], v[98:99], s[0:1], v[78:79] op_sel_hi:[1,0,1]
	v_pk_fma_f32 v[66:67], v[100:101], s[0:1], v[80:81] op_sel_hi:[1,0,1]
	v_pk_add_f32 v[50:51], v[52:53], v[50:51] op_sel_hi:[0,1]
	v_pk_fma_f32 v[74:75], v[54:55], v[54:55], v[50:51]
	s_mov_b64 s[20:21], 0x20180
	v_lshl_add_u64 v[54:55], v[186:187], 0, s[20:21]
	global_load_dwordx4 v[50:53], v[54:55], off offset:48
	global_load_dwordx4 v[76:79], v[54:55], off offset:32
	global_load_dwordx4 v[98:101], v[188:189], off offset:384
	s_nop 0
	global_load_dwordx4 v[186:189], v[54:55], off offset:16
	v_add_f32_e32 v58, v68, v59
	v_pk_fma_f32 v[54:55], v[68:69], v[68:69], v[56:57]
	v_add_f32_e32 v57, v69, v58
	v_mul_f32_e32 v56, v69, v69
	v_pk_add_f32 v[54:55], v[56:57], v[54:55] op_sel_hi:[0,1]
	v_add_f32_e32 v56, v66, v57
	v_pk_fma_f32 v[54:55], v[66:67], v[66:67], v[54:55]
	v_add_f32_e32 v57, v67, v56
	v_mul_f32_e32 v56, v67, v67
	v_pk_add_f32 v[54:55], v[56:57], v[54:55] op_sel_hi:[0,1]
	s_waitcnt vmcnt(9)
	v_pk_fma_f32 v[60:61], v[234:235], s[0:1], v[34:35] op_sel_hi:[1,0,1]
	v_pk_fma_f32 v[64:65], v[236:237], s[0:1], v[36:37] op_sel_hi:[1,0,1]
	v_add_f32_e32 v56, v60, v57
	v_pk_fma_f32 v[34:35], v[60:61], v[60:61], v[54:55]
	v_add_f32_e32 v55, v61, v56
	v_mul_f32_e32 v54, v61, v61
	v_pk_add_f32 v[34:35], v[54:55], v[34:35] op_sel_hi:[0,1]
	v_add_f32_e32 v36, v64, v55
	v_pk_fma_f32 v[34:35], v[64:65], v[64:65], v[34:35]
	v_add_f32_e32 v37, v65, v36
	v_mul_f32_e32 v36, v65, v65
	s_waitcnt vmcnt(8)
	v_pk_fma_f32 v[56:57], v[238:239], s[0:1], v[38:39] op_sel_hi:[1,0,1]
	v_pk_add_f32 v[34:35], v[36:37], v[34:35] op_sel_hi:[0,1]
	v_add_f32_e32 v36, v56, v37
	v_pk_fma_f32 v[34:35], v[56:57], v[56:57], v[34:35]
	v_add_f32_e32 v37, v57, v36
	v_mul_f32_e32 v36, v57, v57
	v_pk_fma_f32 v[62:63], v[240:241], s[0:1], v[40:41] op_sel_hi:[1,0,1]
	v_pk_add_f32 v[34:35], v[36:37], v[34:35] op_sel_hi:[0,1]
	v_add_f32_e32 v36, v62, v37
	v_pk_fma_f32 v[34:35], v[62:63], v[62:63], v[34:35]
	v_add_f32_e32 v37, v63, v36
	v_mul_f32_e32 v36, v63, v63
	v_pk_fma_f32 v[54:55], v[230:231], s[0:1], v[42:43] op_sel_hi:[1,0,1]
	v_pk_add_f32 v[34:35], v[36:37], v[34:35] op_sel_hi:[0,1]
	v_add_f32_e32 v36, v54, v37
	v_pk_fma_f32 v[34:35], v[54:55], v[54:55], v[34:35]
	v_add_f32_e32 v37, v55, v36
	v_mul_f32_e32 v36, v55, v55
	v_pk_fma_f32 v[58:59], v[232:233], s[0:1], v[44:45] op_sel_hi:[1,0,1]
	v_pk_add_f32 v[34:35], v[36:37], v[34:35] op_sel_hi:[0,1]
	v_add_f32_e32 v36, v58, v37
	v_pk_fma_f32 v[34:35], v[58:59], v[58:59], v[34:35]
	v_add_f32_e32 v37, v59, v36
	v_mul_f32_e32 v36, v59, v59
	v_pk_fma_f32 v[44:45], v[82:83], s[0:1], v[46:47] op_sel_hi:[1,0,1]
	v_pk_add_f32 v[34:35], v[36:37], v[34:35] op_sel_hi:[0,1]
	v_add_f32_e32 v36, v44, v37
	v_pk_fma_f32 v[34:35], v[44:45], v[44:45], v[34:35]
	v_add_f32_e32 v37, v45, v36
	v_mul_f32_e32 v36, v45, v45
	v_pk_fma_f32 v[46:47], v[84:85], s[0:1], v[48:49] op_sel_hi:[1,0,1]
	v_pk_add_f32 v[34:35], v[36:37], v[34:35] op_sel_hi:[0,1]
	v_add_f32_e32 v36, v46, v37
	v_pk_fma_f32 v[34:35], v[46:47], v[46:47], v[34:35]
	v_add_f32_e32 v37, v47, v36
	v_mul_f32_e32 v36, v47, v47
	v_pk_add_f32 v[34:35], v[36:37], v[34:35] op_sel_hi:[0,1]
	s_waitcnt vmcnt(5)
	v_pk_fma_f32 v[38:39], v[250:251], s[0:1], v[18:19] op_sel_hi:[1,0,1]
	v_pk_fma_f32 v[42:43], v[252:253], s[0:1], v[20:21] op_sel_hi:[1,0,1]
	v_add_f32_e32 v36, v38, v37
	v_pk_fma_f32 v[18:19], v[38:39], v[38:39], v[34:35]
	v_add_f32_e32 v35, v39, v36
	v_mul_f32_e32 v34, v39, v39
	v_pk_add_f32 v[18:19], v[34:35], v[18:19] op_sel_hi:[0,1]
	v_add_f32_e32 v20, v42, v35
	v_pk_fma_f32 v[18:19], v[42:43], v[42:43], v[18:19]
	v_add_f32_e32 v21, v43, v20
	v_mul_f32_e32 v20, v43, v43
	s_waitcnt vmcnt(4)
; #define RL_LOAD(XV, G) { constexpr int mt__ = (G) >> 2, half__ = ((G) >> 1) & 1, nt__ = (G) & 1; \
;     _Pragma("unroll") for (int gq = 0; gq < 4; ++gq) XV[gq] = *(const f32x4*)(xin + rbase + (size_t)mt__ * 32 * 1024 + half__ * 64 + nt__ * 32 + 4 * gq); }
; #define RL_FOLD(XV, G, SM, SQ) { constexpr int mt__ = (G) >> 2, half__ = ((G) >> 1) & 1, nt__ = (G) & 1; \
;     _Pragma("unroll") for (int gq = 0; gq < 4; ++gq) _Pragma("unroll") for (int jj = 0; jj < 4; ++jj) { \
;       const float y = ALPHA * XV[gq][jj] + acc[half__][nt__][mt__][4 * gq + jj]; acc[half__][nt__][mt__][4 * gq + jj] = y; SM += y; SQ += y * y; } }
; #define SB __builtin_amdgcn_sched_barrier(0)
;   DI void full(const int mt_, const int nt_, f32x16 (&acc)[2][2][2], const int tw, const int fw, const int r, const int hh, char* lds, const int tid) const {
;     ...
;     float sm0 = 0.f, sq0 = 0.f, sm1 = 0.f, sq1 = 0.f;
;     RL_LOAD(xa, 0); RL_LOAD(xc, 1); RL_LOAD(xe, 2); SB;
;     RL_FOLD(xa, 0, sm0, sq0); SB; RL_LOAD(xa, 3); SB;
;     RL_FOLD(xc, 1, sm0, sq0); SB; RL_LOAD(xc, 4); SB;
;     RL_FOLD(xe, 2, sm0, sq0); SB; RL_LOAD(xe, 5); SB;
;     RL_FOLD(xa, 3, sm0, sq0); SB; RL_LOAD(xa, 6); SB;
;     RL_FOLD(xc, 4, sm1, sq1); SB; RL_LOAD(xc, 7); SB;
;     RL_FOLD(xe, 5, sm1, sq1); SB;
;     RL_FOLD(xa, 6, sm1, sq1); SB;
;     RL_FOLD(xc, 7, sm1, sq1);
;     ...
;     sm0 += __shfl_xor(sm0, 32, 64); sq0 += __shfl_xor(sq0, 32, 64); sm1 += __shfl_xor(sm1, 32, 64); sq1 += __shfl_xor(sq1, 32, 64);
;     if (hh == 0) {
;       float* pp = part + ((fw * 256) + tw * 64 + r) * 2; pp[0] = sm0; pp[1] = sq0;
;       pp[64] = sm1; pp[65] = sq1;
;     }
	v_pk_fma_f32 v[34:35], v[166:167], s[0:1], v[22:23] op_sel_hi:[1,0,1]
	v_pk_add_f32 v[18:19], v[20:21], v[18:19] op_sel_hi:[0,1]
	v_add_f32_e32 v20, v34, v21
	v_pk_fma_f32 v[18:19], v[34:35], v[34:35], v[18:19]
	v_add_f32_e32 v21, v35, v20
	v_mul_f32_e32 v20, v35, v35
	v_pk_fma_f32 v[40:41], v[168:169], s[0:1], v[24:25] op_sel_hi:[1,0,1]
	v_pk_add_f32 v[18:19], v[20:21], v[18:19] op_sel_hi:[0,1]
	v_add_f32_e32 v20, v40, v21
	v_pk_fma_f32 v[18:19], v[40:41], v[40:41], v[18:19]
	v_add_f32_e32 v21, v41, v20
	v_mul_f32_e32 v20, v41, v41
	v_pk_fma_f32 v[26:27], v[246:247], s[0:1], v[26:27] op_sel_hi:[1,0,1]
	v_pk_add_f32 v[18:19], v[20:21], v[18:19] op_sel_hi:[0,1]
	v_add_f32_e32 v20, v26, v21
	v_pk_fma_f32 v[18:19], v[26:27], v[26:27], v[18:19]
	v_add_f32_e32 v21, v27, v20
	v_mul_f32_e32 v20, v27, v27
	v_pk_fma_f32 v[36:37], v[248:249], s[0:1], v[28:29] op_sel_hi:[1,0,1]
	v_pk_add_f32 v[18:19], v[20:21], v[18:19] op_sel_hi:[0,1]
	v_add_f32_e32 v20, v36, v21
	v_pk_fma_f32 v[18:19], v[36:37], v[36:37], v[18:19]
	v_add_f32_e32 v21, v37, v20
	v_mul_f32_e32 v20, v37, v37
	v_pk_fma_f32 v[24:25], v[242:243], s[0:1], v[30:31] op_sel_hi:[1,0,1]
	v_pk_add_f32 v[18:19], v[20:21], v[18:19] op_sel_hi:[0,1]
	v_add_f32_e32 v20, v24, v21
	v_pk_fma_f32 v[18:19], v[24:25], v[24:25], v[18:19]
	v_add_f32_e32 v21, v25, v20
	v_mul_f32_e32 v20, v25, v25
	v_pk_fma_f32 v[28:29], v[244:245], s[0:1], v[32:33] op_sel_hi:[1,0,1]
	v_pk_add_f32 v[18:19], v[20:21], v[18:19] op_sel_hi:[0,1]
	v_add_f32_e32 v20, v28, v21
	v_pk_fma_f32 v[18:19], v[28:29], v[28:29], v[18:19]
	v_add_f32_e32 v22, v29, v20
	v_mul_f32_e32 v20, v29, v29
	v_pk_add_f32 v[20:21], v[20:21], v[18:19] op_sel_hi:[0,1]
	s_waitcnt vmcnt(1)
	v_pk_fma_f32 v[18:19], v[98:99], s[0:1], v[2:3] op_sel_hi:[1,0,1]
	s_waitcnt vmcnt(0)
	v_pk_fma_f32 v[6:7], v[186:187], s[0:1], v[6:7] op_sel_hi:[1,0,1]
	v_add_f32_e32 v22, v18, v22
	v_pk_fma_f32 v[2:3], v[18:19], v[18:19], v[20:21]
	v_add_f32_e32 v21, v19, v22
	v_pk_fma_f32 v[22:23], v[100:101], s[0:1], v[4:5] op_sel_hi:[1,0,1]
	v_mul_f32_e32 v20, v19, v19
	v_add_f32_e32 v4, v22, v21
	v_pk_add_f32 v[2:3], v[20:21], v[2:3] op_sel_hi:[0,1]
	v_add_f32_e32 v4, v23, v4
	v_pk_fma_f32 v[2:3], v[22:23], v[22:23], v[2:3]
	v_add_f32_e32 v21, v6, v4
	v_mul_f32_e32 v20, v23, v23
	v_mov_b32_e32 v4, v6
	v_mov_b32_e32 v5, v23
	v_pk_add_f32 v[2:3], v[20:21], v[2:3] op_sel_hi:[0,1]
	v_pk_fma_f32 v[2:3], v[4:5], v[4:5], v[2:3]
	v_add_f32_e32 v4, v7, v21
	v_pk_fma_f32 v[20:21], v[188:189], s[0:1], v[8:9] op_sel_hi:[1,0,1]
	v_mul_f32_e32 v8, v7, v7
	v_add_f32_e32 v9, v20, v4
	v_mov_b32_e32 v4, v20
	v_mov_b32_e32 v5, v7
	v_pk_add_f32 v[2:3], v[8:9], v[2:3] op_sel_hi:[0,1]
	v_pk_fma_f32 v[4:5], v[4:5], v[4:5], v[2:3]
	v_add_f32_e32 v8, v21, v9
	v_pk_fma_f32 v[2:3], v[76:77], s[0:1], v[10:11] op_sel_hi:[1,0,1]
	v_mul_f32_e32 v10, v21, v21
	v_add_f32_e32 v11, v2, v8
	v_mov_b32_e32 v8, v2
	v_mov_b32_e32 v9, v21
	v_pk_add_f32 v[4:5], v[10:11], v[4:5] op_sel_hi:[0,1]
	v_pk_fma_f32 v[4:5], v[8:9], v[8:9], v[4:5]
	v_add_f32_e32 v10, v3, v11
	v_pk_fma_f32 v[8:9], v[78:79], s[0:1], v[12:13] op_sel_hi:[1,0,1]
	v_mul_f32_e32 v12, v3, v3
	v_add_f32_e32 v13, v8, v10
	v_mov_b32_e32 v10, v8
	v_mov_b32_e32 v11, v3
	v_pk_add_f32 v[4:5], v[12:13], v[4:5] op_sel_hi:[0,1]
	v_pk_fma_f32 v[10:11], v[10:11], v[10:11], v[4:5]
	v_add_f32_e32 v12, v9, v13
	v_pk_fma_f32 v[4:5], v[50:51], s[0:1], v[14:15] op_sel_hi:[1,0,1]
	v_mul_f32_e32 v14, v9, v9
	v_add_f32_e32 v15, v4, v12
	v_mov_b32_e32 v12, v4
	v_mov_b32_e32 v13, v9
	v_pk_add_f32 v[10:11], v[14:15], v[10:11] op_sel_hi:[0,1]
	v_pk_fma_f32 v[12:13], v[12:13], v[12:13], v[10:11]
	v_pk_fma_f32 v[10:11], v[52:53], s[0:1], v[16:17] op_sel_hi:[1,0,1]
	v_mul_f32_e32 v30, v5, v5
	v_mov_b32_e32 v16, v10
	v_mov_b32_e32 v17, v5
	v_pk_add_f32 v[12:13], v[30:31], v[12:13] op_sel_hi:[0,1]
	v_pk_fma_f32 v[12:13], v[16:17], v[16:17], v[12:13]
	v_pk_mul_f32 v[16:17], v[10:11], v[10:11]
	v_add_f32_e32 v14, v5, v15
	v_mov_b32_e32 v15, v17
	v_and_b32_e32 v17, 64, v201
	v_xor_b32_e32 v16, 32, v201
	v_add_u32_e32 v17, 64, v17
	v_add_f32_e32 v14, v10, v14
	v_pk_mov_b32 v[12:13], v[10:11], v[12:13] op_sel:[1,0]
	v_cmp_lt_i32_e32 vcc, v16, v17
	v_pk_add_f32 v[12:13], v[12:13], v[14:15]
	v_pk_mov_b32 v[14:15], v[110:111], v[74:75] op_sel:[1,0]
	v_cndmask_b32_e32 v16, v201, v16, vcc
	v_pk_add_f32 v[14:15], v[14:15], v[114:115]
	v_lshlrev_b32_e32 v31, 2, v16
	ds_bpermute_b32 v16, v31, v14
	ds_bpermute_b32 v17, v31, v15
	ds_bpermute_b32 v30, v31, v12
	ds_bpermute_b32 v31, v31, v13
	v_cmp_eq_u32_e32 vcc, 0, v224
	s_and_saveexec_b64 s[20:21], vcc
	s_cbranch_execz .LBB0_272
	v_lshlrev_b32_e32 v32, 3, v184
	v_and_b32_e32 v32, 0xfffffef8, v32
	v_add_u32_e32 v32, 0, v32
	v_add_u32_e32 v32, 0x12000, v32
	s_waitcnt lgkmcnt(2)
	v_pk_add_f32 v[14:15], v[14:15], v[16:17]
	s_waitcnt lgkmcnt(0)
	v_pk_add_f32 v[12:13], v[12:13], v[30:31]
	ds_write2_b64 v32, v[14:15], v[12:13] offset1:32

.LBB0_311:
	v_add_u32_e32 v0, v184, v185
	ds_read_b128 v[216:219], v0
	ds_read_b128 v[220:223], v0 offset:4608
	v_add_u32_e32 v0, v184, v186
	ds_read_b128 v[162:165], v0 offset:36864
	ds_read_b128 v[166:169], v0 offset:41472
	ds_read_b128 v[176:179], v0 offset:46080
	ds_read_b128 v[180:183], v0 offset:50688
	ds_read_b128 v[224:227], v189 offset:32
	ds_read_b128 v[228:231], v189 offset:4640
.Lkloop_top_2:
	s_add_i32 s28, s13, -3
	s_cmp_lt_u32 s28, 14
	s_cselect_b64 s[38:39], -1, 0
	s_and_b64 s[10:11], s[38:39], exec
	s_cselect_b32 s11, s9, s27
	s_cselect_b32 s10, s8, s26
	s_cselect_b32 s41, s7, s15
	s_cselect_b32 s40, s6, s14
	s_add_i32 s29, s13, -1
	s_waitcnt lgkmcnt(5)
	v_mfma_f32_32x32x16_bf16 v[114:129], v[162:165], v[216:219], v[114:129]
	v_mfma_f32_32x32x16_bf16 v[82:97], v[162:165], v[220:223], v[82:97]
	s_waitcnt lgkmcnt(4)
	v_mfma_f32_32x32x16_bf16 v[98:113], v[166:169], v[216:219], v[98:113]
	v_mfma_f32_32x32x16_bf16 v[66:81], v[166:169], v[220:223], v[66:81]
	s_waitcnt lgkmcnt(3)
	v_mfma_f32_32x32x16_bf16 v[50:65], v[176:179], v[216:219], v[50:65]
	s_and_b64 s[38:39], s[38:39], exec
	s_cselect_b32 s29, s29, s5
	v_mfma_f32_32x32x16_bf16 v[18:33], v[176:179], v[220:223], v[18:33]
	s_waitcnt lgkmcnt(2)
	v_mfma_f32_32x32x16_bf16 v[34:49], v[180:183], v[216:219], v[34:49]
	ds_read_b128 v[162:165], v190 offset:36896
	ds_read_b128 v[176:179], v190 offset:41504
	v_mfma_f32_32x32x16_bf16 v[2:17], v[180:183], v[220:223], v[2:17]
	s_lshl_b32 s96, s29, 7
	v_lshl_add_u64 v[166:167], s[40:41], 0, v[170:171]
	v_lshl_add_u64 v[166:167], v[166:167], 0, s[96:97]
	s_waitcnt vmcnt(3)
	ds_write_b128 v191, v[138:141] offset:9216
	v_add_co_u32_e32 v138, vcc, s91, v166
	ds_write_b128 v191, v[134:137]
	s_nop 0
	v_addc_co_u32_e32 v139, vcc, 0, v167, vcc
	global_load_dwordx4 v[134:137], v[166:167], off
	s_nop 0
	global_load_dwordx4 v[138:141], v[138:139], off
	ds_write_b128 v191, v[130:133] offset:18432
	v_add_co_u32_e32 v130, vcc, s1, v166
	ds_write_b128 v191, v[142:145] offset:27648
	s_nop 0
	v_addc_co_u32_e32 v131, vcc, 0, v167, vcc
	v_add_co_u32_e32 v142, vcc, s76, v166
	global_load_dwordx4 v[130:133], v[130:131], off
	s_nop 0
	v_addc_co_u32_e32 v143, vcc, 0, v167, vcc
	global_load_dwordx4 v[142:145], v[142:143], off
	ds_read_b128 v[166:169], v190 offset:46112
	ds_read_b128 v[180:183], v190 offset:50720
	ds_read_b128 v[216:219], v189 offset:64
	ds_read_b128 v[220:223], v189 offset:4672
	s_waitcnt lgkmcnt(9)
	v_mfma_f32_32x32x16_bf16 v[114:129], v[162:165], v[224:227], v[114:129]
	v_mfma_f32_32x32x16_bf16 v[82:97], v[162:165], v[228:231], v[82:97]
	s_waitcnt lgkmcnt(8)
	v_mfma_f32_32x32x16_bf16 v[98:113], v[176:179], v[224:227], v[98:113]
	v_mfma_f32_32x32x16_bf16 v[66:81], v[176:179], v[228:231], v[66:81]
	s_waitcnt lgkmcnt(3)
	v_mfma_f32_32x32x16_bf16 v[50:65], v[166:169], v[224:227], v[50:65]
	v_mfma_f32_32x32x16_bf16 v[18:33], v[166:169], v[228:231], v[18:33]
	ds_read_b128 v[162:165], v190 offset:36928
	ds_read_b128 v[166:169], v190 offset:41536
	s_waitcnt lgkmcnt(4)
	v_mfma_f32_32x32x16_bf16 v[34:49], v[180:183], v[224:227], v[34:49]
	v_mfma_f32_32x32x16_bf16 v[2:17], v[180:183], v[228:231], v[2:17]
	v_lshl_add_u64 v[172:173], s[10:11], 0, v[170:171]
	v_lshl_add_u64 v[172:173], v[172:173], 0, s[96:97]
	s_waitcnt vmcnt(6)
	ds_write_b128 v208, v[154:157] offset:9216
	v_add_co_u32_e32 v154, vcc, s91, v172
	s_waitcnt vmcnt(5)
	ds_write_b128 v208, v[146:149]
	v_addc_co_u32_e32 v155, vcc, 0, v173, vcc
	global_load_dwordx4 v[146:149], v[172:173], off
	s_nop 0
	global_load_dwordx4 v[154:157], v[154:155], off
	ds_read_b128 v[176:179], v190 offset:46144
	ds_read_b128 v[180:183], v190 offset:50752
	ds_read_b128 v[224:227], v189 offset:96
	ds_read_b128 v[228:231], v189 offset:4704
	s_waitcnt lgkmcnt(7)
	v_mfma_f32_32x32x16_bf16 v[114:129], v[162:165], v[216:219], v[114:129]
	v_mfma_f32_32x32x16_bf16 v[82:97], v[162:165], v[220:223], v[82:97]
	s_waitcnt lgkmcnt(6)
	v_mfma_f32_32x32x16_bf16 v[98:113], v[166:169], v[216:219], v[98:113]
	v_mfma_f32_32x32x16_bf16 v[66:81], v[166:169], v[220:223], v[66:81]
	s_waitcnt lgkmcnt(3)
	v_mfma_f32_32x32x16_bf16 v[50:65], v[176:179], v[216:219], v[50:65]
	ds_read_b128 v[162:165], v190 offset:36960
	ds_read_b128 v[166:169], v190 offset:41568
	v_mfma_f32_32x32x16_bf16 v[18:33], v[176:179], v[220:223], v[18:33]
	s_waitcnt lgkmcnt(4)
	v_mfma_f32_32x32x16_bf16 v[34:49], v[180:183], v[216:219], v[34:49]
	v_mfma_f32_32x32x16_bf16 v[2:17], v[180:183], v[220:223], v[2:17]
	ds_write_b128 v208, v[150:153] offset:18432
	v_add_co_u32_e32 v150, vcc, s1, v172
	s_waitcnt vmcnt(6)
	ds_write_b128 v208, v[158:161] offset:27648
	v_addc_co_u32_e32 v151, vcc, 0, v173, vcc
	v_add_co_u32_e32 v158, vcc, s76, v172
	global_load_dwordx4 v[150:153], v[150:151], off
	s_nop 0
	v_addc_co_u32_e32 v159, vcc, 0, v173, vcc
	global_load_dwordx4 v[158:161], v[158:159], off
	ds_read_b128 v[176:179], v190 offset:46176
	ds_read_b128 v[180:183], v190 offset:50784
	s_waitcnt lgkmcnt(5)
	v_mfma_f32_32x32x16_bf16 v[114:129], v[162:165], v[224:227], v[114:129]
	v_mfma_f32_32x32x16_bf16 v[82:97], v[162:165], v[228:231], v[82:97]
	s_waitcnt lgkmcnt(4)
	v_mfma_f32_32x32x16_bf16 v[98:113], v[166:169], v[224:227], v[98:113]
	v_mfma_f32_32x32x16_bf16 v[66:81], v[166:169], v[228:231], v[66:81]
	s_waitcnt lgkmcnt(0)
	s_barrier
	ds_read_b128 v[216:219], v209
	ds_read_b128 v[220:223], v209 offset:4608
	ds_read_b128 v[162:165], v210
	ds_read_b128 v[166:169], v210 offset:4608
	v_mfma_f32_32x32x16_bf16 v[50:65], v[176:179], v[224:227], v[50:65]
	v_mfma_f32_32x32x16_bf16 v[18:33], v[176:179], v[228:231], v[18:33]
	ds_read_b128 v[176:179], v210 offset:9216
	v_mfma_f32_32x32x16_bf16 v[34:49], v[180:183], v[224:227], v[34:49]
	v_mfma_f32_32x32x16_bf16 v[2:17], v[180:183], v[228:231], v[2:17]
	ds_read_b128 v[180:183], v210 offset:13824
	v_add_u32_e32 v0, v187, v175
	ds_read_b128 v[224:227], v0 offset:32
	ds_read_b128 v[228:231], v211 offset:32
	s_cmp_lt_u32 s28, 13
	s_cselect_b64 s[10:11], -1, 0
	s_and_b64 s[10:11], s[10:11], exec
	s_cselect_b32 s39, s7, s15
	s_cselect_b32 s38, s6, s14
	s_cselect_b32 s11, s9, s27
	s_cselect_b32 s10, s8, s26
	s_waitcnt lgkmcnt(5)
	v_mfma_f32_32x32x16_bf16 v[114:129], v[162:165], v[216:219], v[114:129]
	v_mfma_f32_32x32x16_bf16 v[82:97], v[162:165], v[220:223], v[82:97]
	s_waitcnt lgkmcnt(4)
	v_mfma_f32_32x32x16_bf16 v[98:113], v[166:169], v[216:219], v[98:113]
	v_mfma_f32_32x32x16_bf16 v[66:81], v[166:169], v[220:223], v[66:81]
	s_waitcnt lgkmcnt(3)
	v_mfma_f32_32x32x16_bf16 v[50:65], v[176:179], v[216:219], v[50:65]
	v_add_u32_e32 v174, v188, v175
	s_cselect_b32 s29, s13, s12
	v_mfma_f32_32x32x16_bf16 v[18:33], v[176:179], v[220:223], v[18:33]
	s_waitcnt lgkmcnt(2)
	v_mfma_f32_32x32x16_bf16 v[34:49], v[180:183], v[216:219], v[34:49]
	ds_read_b128 v[162:165], v174 offset:32
	ds_read_b128 v[176:179], v212 offset:32
	v_mfma_f32_32x32x16_bf16 v[2:17], v[180:183], v[220:223], v[2:17]
	s_lshl_b32 s96, s29, 7
	v_lshl_add_u64 v[166:167], s[38:39], 0, v[170:171]
	v_lshl_add_u64 v[166:167], v[166:167], 0, s[96:97]
	s_waitcnt vmcnt(6)
	ds_write_b128 v215, v[138:141] offset:9216
	v_add_co_u32_e32 v138, vcc, s91, v166
	ds_write_b128 v215, v[134:137]
	s_nop 0
	v_addc_co_u32_e32 v139, vcc, 0, v167, vcc
	global_load_dwordx4 v[134:137], v[166:167], off
	s_nop 0
	global_load_dwordx4 v[138:141], v[138:139], off
	s_waitcnt vmcnt(7)
	ds_write_b128 v215, v[130:133] offset:18432
	v_add_co_u32_e32 v130, vcc, s1, v166
	s_waitcnt vmcnt(6)
	ds_write_b128 v215, v[142:145] offset:27648
	v_addc_co_u32_e32 v131, vcc, 0, v167, vcc
	v_add_co_u32_e32 v142, vcc, s76, v166
	global_load_dwordx4 v[130:133], v[130:131], off
	s_nop 0
	v_addc_co_u32_e32 v143, vcc, 0, v167, vcc
	global_load_dwordx4 v[142:145], v[142:143], off
	ds_read_b128 v[166:169], v213 offset:32
	ds_read_b128 v[180:183], v214 offset:32
	ds_read_b128 v[216:219], v0 offset:64
	ds_read_b128 v[220:223], v211 offset:64
	s_waitcnt lgkmcnt(9)
	v_mfma_f32_32x32x16_bf16 v[114:129], v[162:165], v[224:227], v[114:129]
	v_mfma_f32_32x32x16_bf16 v[82:97], v[162:165], v[228:231], v[82:97]
	s_waitcnt lgkmcnt(8)
	v_mfma_f32_32x32x16_bf16 v[98:113], v[176:179], v[224:227], v[98:113]
	v_mfma_f32_32x32x16_bf16 v[66:81], v[176:179], v[228:231], v[66:81]
	s_waitcnt lgkmcnt(3)
	v_mfma_f32_32x32x16_bf16 v[50:65], v[166:169], v[224:227], v[50:65]
	v_mfma_f32_32x32x16_bf16 v[18:33], v[166:169], v[228:231], v[18:33]
	ds_read_b128 v[162:165], v174 offset:64
	ds_read_b128 v[166:169], v212 offset:64
	s_waitcnt lgkmcnt(4)
	v_mfma_f32_32x32x16_bf16 v[34:49], v[180:183], v[224:227], v[34:49]
	v_mfma_f32_32x32x16_bf16 v[2:17], v[180:183], v[228:231], v[2:17]
	v_lshl_add_u64 v[172:173], s[10:11], 0, v[170:171]
	v_lshl_add_u64 v[172:173], v[172:173], 0, s[96:97]
	s_waitcnt vmcnt(6)
	ds_write_b128 v215, v[154:157] offset:46080
	v_add_co_u32_e32 v154, vcc, s91, v172
	ds_write_b128 v215, v[146:149] offset:36864
	s_nop 0
	v_addc_co_u32_e32 v155, vcc, 0, v173, vcc
	global_load_dwordx4 v[146:149], v[172:173], off
	s_nop 0
	global_load_dwordx4 v[154:157], v[154:155], off
	ds_read_b128 v[176:179], v213 offset:64
	ds_read_b128 v[180:183], v214 offset:64
	ds_read_b128 v[224:227], v0 offset:96
	ds_read_b128 v[228:231], v211 offset:96
	s_waitcnt lgkmcnt(7)
	v_mfma_f32_32x32x16_bf16 v[114:129], v[162:165], v[216:219], v[114:129]
	v_mfma_f32_32x32x16_bf16 v[82:97], v[162:165], v[220:223], v[82:97]
	s_waitcnt lgkmcnt(6)
	v_mfma_f32_32x32x16_bf16 v[98:113], v[166:169], v[216:219], v[98:113]
	v_mfma_f32_32x32x16_bf16 v[66:81], v[166:169], v[220:223], v[66:81]
	s_waitcnt lgkmcnt(3)
	v_mfma_f32_32x32x16_bf16 v[50:65], v[176:179], v[216:219], v[50:65]
	ds_read_b128 v[162:165], v174 offset:96
	ds_read_b128 v[166:169], v212 offset:96
	v_mfma_f32_32x32x16_bf16 v[18:33], v[176:179], v[220:223], v[18:33]
	s_waitcnt lgkmcnt(4)
	v_mfma_f32_32x32x16_bf16 v[34:49], v[180:183], v[216:219], v[34:49]
	v_mfma_f32_32x32x16_bf16 v[2:17], v[180:183], v[220:223], v[2:17]
	s_waitcnt vmcnt(7)
	ds_write_b128 v215, v[150:153] offset:55296
	v_add_co_u32_e32 v150, vcc, s1, v172
	s_waitcnt vmcnt(6)
	ds_write_b128 v215, v[158:161] offset:64512
	v_addc_co_u32_e32 v151, vcc, 0, v173, vcc
	v_add_co_u32_e32 v158, vcc, s76, v172
	global_load_dwordx4 v[150:153], v[150:151], off
	s_nop 0
	v_addc_co_u32_e32 v159, vcc, 0, v173, vcc
	global_load_dwordx4 v[158:161], v[158:159], off
	ds_read_b128 v[176:179], v213 offset:96
	ds_read_b128 v[180:183], v214 offset:96
	s_waitcnt lgkmcnt(5)
	v_mfma_f32_32x32x16_bf16 v[114:129], v[162:165], v[224:227], v[114:129]
	v_mfma_f32_32x32x16_bf16 v[82:97], v[162:165], v[228:231], v[82:97]
	s_waitcnt lgkmcnt(4)
	v_mfma_f32_32x32x16_bf16 v[98:113], v[166:169], v[224:227], v[98:113]
	v_mfma_f32_32x32x16_bf16 v[66:81], v[166:169], v[228:231], v[66:81]
	s_waitcnt lgkmcnt(0)
	s_barrier
; DI unsigned pk2(float lo, float hi) { f32x2 v = {lo, hi}; bf16x2v b = __builtin_convertvector(v, bf16x2v); return __builtin_bit_cast(unsigned, b); }
; DI bf16_t f2bf(float x) { return (bf16_t)(pk2(x, 0.f) & 0xffffu); }
; DI float sigmoidf_(float x) { return __builtin_amdgcn_rcpf(1.f + __builtin_amdgcn_exp2f(-LOG2E * x)); }
; DI float siluf_(float x) { return x * __builtin_amdgcn_rcpf(1.f + __builtin_amdgcn_exp2f(-LOG2E * x)); }
; DI int swz32(int s) { return (s & ~12) | ((s & 4) << 1) | ((s & 8) >> 1); }
;   DI void operator()(int tok0, int feat0, f32x16 (&acc)[2][2], int r, int hh) const {
;     const int seg = feat0 >> 9, c0 = feat0 & 511;
; #pragma unroll
;     for (int mt = 0; mt < 2; ++mt) {
;       const int tok = tok0 + mt * 32 + r, b = tok >> 14, s = tok & (SEQ - 1);
; #pragma unroll
;       for (int nt = 0; nt < 2; ++nt)
; #pragma unroll
;         for (int gp = 0; gp < 2; ++gp) {
;           const int c = c0 + nt * 32 + 16 * hh + 8 * gp;
;           float v[8];
; #pragma unroll
;           for (int e = 0; e < 8; ++e) v[e] = acc[nt][mt][8 * gp + e];
;           if (seg == 0 || seg == 3) {
;             u32x4 o = {pk2(siluf_(v[0]), siluf_(v[1])), pk2(siluf_(v[2]), siluf_(v[3])), pk2(siluf_(v[4]), siluf_(v[5])), pk2(siluf_(v[6]), siluf_(v[7]))};
;             *(u32x4*)((seg == 0 ? aq : ag) + (size_t)tok * 512 + c) = o;
;           } else if (seg == 1) {
; #pragma unroll
;             for (int h2 = 0; h2 < 2; ++h2) {
;               f32x4 lbv = *(const f32x4*)(lb + c + 4 * h2), o;
; #pragma unroll
;               for (int e = 0; e < 4; ++e) o[e] = __logf(lbv[e] + (1.f - lbv[e]) * sigmoidf_(v[4 * h2 + e]));
;               *(f32x4*)(alf + (size_t)tok * 512 + c + 4 * h2) = o;
;             }
;           } else if (seg == 4 || seg == 5) {
;             const float sc = seg == 4 ? 0.125f * LOG2E : 1.f;
;             u32x4 o = {pk2(v[0] * sc, v[1] * sc), pk2(v[2] * sc, v[3] * sc), pk2(v[4] * sc, v[5] * sc), pk2(v[6] * sc, v[7] * sc)};
;             *(u32x4*)((seg == 4 ? bq : bk) + (size_t)tok * 512 + c) = o;
;           } else {
;             bf16_t* dst = (seg == 2 ? aiT : bvT) + ((size_t)((b * 4 + (c >> 7)) * 128 + (c & 127))) * SEQ + (seg == 2 ? s : swz32(s));
; #pragma unroll
;             for (int e = 0; e < 8; ++e) dst[(size_t)e * SEQ] = f2bf(v[e]);
;           }
	v_add_u32_e32 v0, v184, v185
	ds_read_b128 v[216:219], v0
	ds_read_b128 v[220:223], v0 offset:4608
	v_add_u32_e32 v0, v184, v186
	ds_read_b128 v[162:165], v0 offset:36864
	ds_read_b128 v[166:169], v0 offset:41472
	v_mfma_f32_32x32x16_bf16 v[50:65], v[176:179], v[224:227], v[50:65]
	v_mfma_f32_32x32x16_bf16 v[18:33], v[176:179], v[228:231], v[18:33]
	ds_read_b128 v[176:179], v0 offset:46080
	v_mfma_f32_32x32x16_bf16 v[34:49], v[180:183], v[224:227], v[34:49]
	v_mfma_f32_32x32x16_bf16 v[2:17], v[180:183], v[228:231], v[2:17]
	ds_read_b128 v[180:183], v0 offset:50688
	ds_read_b128 v[224:227], v189 offset:32
	ds_read_b128 v[228:231], v189 offset:4640
	s_add_i32 s13, s13, 2
	s_cmp_gt_u32 s28, 13
	s_cbranch_scc0 .Lkloop_top_2
	s_waitcnt lgkmcnt(0)
	v_mov_b32_e32 v0, v192
	s_ashr_i32 s2, s2, 5
	v_ashrrev_i32_e32 v162, 1, v0
	v_and_b32_e32 v162, 0xffffff80, v162
	v_lshrrev_b32_e32 v165, 1, v0
	v_add_u32_e32 v162, s3, v162
	v_and_b32_e32 v164, 0xdf, v0
	v_and_b32_e32 v0, 16, v165
	s_movk_i32 s3, 0x180
	v_and_or_b32 v216, v162, s3, v0
	s_movk_i32 s3, 0x200
	v_ashrrev_i32_e32 v163, 9, v162
	v_cmp_gt_u32_e64 s[12:13], s3, v162
	s_movk_i32 s3, 0x1ff
	v_cmp_lt_u32_e32 vcc, s3, v162
	v_cmp_ne_u32_e64 s[6:7], 3, v163
	s_and_b64 s[26:27], vcc, s[6:7]
	v_and_b32_e32 v0, 0xfffffc00, v162
	v_cmp_eq_u32_e32 vcc, 4, v163
	v_mov_b32_e32 v162, 0x3e38aa3b
	v_cmp_ne_u32_e64 s[8:9], 1, v163
	v_cmp_eq_u32_e64 s[10:11], 2, v163
	v_cndmask_b32_e32 v174, 1.0, v162, vcc
	v_bfrev_b32_e32 v162, 48
	v_mov_b32_e32 v163, 0xa000000
	v_or_b32_e32 v180, s4, v164
	v_cndmask_b32_e32 v172, v162, v163, vcc
	v_mov_b32_e32 v162, s4
	s_and_b32 s37, s2, 0xfffffe00
	s_movk_i32 s2, 0x3fd3
	v_bitop3_b32 v163, v164, s53, v162 bitop3:0xc8
	v_bitop3_b32 v162, v164, s2, v162 bitop3:0xc8
	v_lshlrev_b32_e32 v164, 1, v180
	s_movk_i32 s3, 0x800
	v_and_b32_e32 v218, 8, v164
	v_and_b32_e32 v219, 4, v165
	v_cmp_ne_u32_e64 s[6:7], s3, v0
	v_mov_b32_e32 v0, 0x6000000
	v_or3_b32 v162, v162, v218, v219
	v_ashrrev_i32_e32 v181, 31, v180
	v_cndmask_b32_e64 v0, v207, v0, s[10:11]
	v_mov_b32_e32 v173, v1
	v_cndmask_b32_e64 v217, v162, v163, s[10:11]
	v_lshlrev_b64 v[178:179], 10, v[180:181]
	v_lshlrev_b64 v[176:177], 11, v[180:181]
	s_and_saveexec_b64 s[2:3], s[26:27]
	s_xor_b64 s[4:5], exec, s[2:3]
	s_cbranch_execz .LBB0_322
	s_and_saveexec_b64 s[2:3], s[8:9]
	s_xor_b64 s[14:15], exec, s[2:3]
	s_cbranch_execz .LBB0_319
	s_and_saveexec_b64 s[2:3], s[6:7]
	s_xor_b64 s[28:29], exec, s[2:3]
	s_cbranch_execz .LBB0_316
	v_or_b32_e32 v164, s37, v216
	v_ashrrev_i32_e32 v165, 31, v164
	v_lshl_add_u64 v[162:163], s[16:17], 0, v[0:1]
	v_lshlrev_b64 v[164:165], 15, v[164:165]
	v_lshl_add_u64 v[162:163], v[162:163], 0, v[164:165]
	v_lshlrev_b32_e32 v164, 1, v217
	v_mov_b32_e32 v165, v1
	v_lshl_add_u64 v[162:163], v[162:163], 0, v[164:165]
	v_cvt_pk_bf16_f32 v164, v114, s0
	global_store_short v[162:163], v164, off
	v_add_co_u32_e32 v164, vcc, 0x8000, v162
	v_cvt_pk_bf16_f32 v166, v115, s0
	s_nop 0
	v_addc_co_u32_e32 v165, vcc, 0, v163, vcc
	global_store_short v[164:165], v166, off
	v_add_co_u32_e32 v164, vcc, s65, v162
	v_cvt_pk_bf16_f32 v166, v116, s0
	s_nop 0
	v_addc_co_u32_e32 v165, vcc, 0, v163, vcc
	global_store_short v[164:165], v166, off
	v_add_co_u32_e32 v164, vcc, 0x18000, v162
	v_cvt_pk_bf16_f32 v166, v117, s0
	s_nop 0
	v_addc_co_u32_e32 v165, vcc, 0, v163, vcc
	global_store_short v[164:165], v166, off
	v_add_co_u32_e32 v164, vcc, s91, v162
	v_cvt_pk_bf16_f32 v166, v118, s0
	s_nop 0
	v_addc_co_u32_e32 v165, vcc, 0, v163, vcc
	global_store_short v[164:165], v166, off
	v_add_co_u32_e32 v164, vcc, 0x28000, v162
	v_cvt_pk_bf16_f32 v166, v119, s0
	s_nop 0
	v_addc_co_u32_e32 v165, vcc, 0, v163, vcc
	global_store_short v[164:165], v166, off
	v_add_co_u32_e32 v164, vcc, 0x30000, v162
	v_cvt_pk_bf16_f32 v166, v120, s0
	s_nop 0
	v_addc_co_u32_e32 v165, vcc, 0, v163, vcc
	v_add_co_u32_e32 v162, vcc, 0x38000, v162
	global_store_short v[164:165], v166, off
	v_cvt_pk_bf16_f32 v164, v121, s0
	v_addc_co_u32_e32 v163, vcc, 0, v163, vcc
	global_store_short v[162:163], v164, off

.Lkloop_top_3:
	s_add_i32 s5, s19, 2
	s_cmp_lt_u32 s19, 14
	s_cselect_b32 s96, s3, 0x780
	s_min_u32 s18, s19, 12
	s_lshl_b32 s18, s18, 7
	s_addk_i32 s3, 0x100
	s_cmp_gt_u32 s19, 13
	s_waitcnt lgkmcnt(5)
	v_mfma_f32_32x32x16_bf16 v[114:129], v[166:169], v[224:227], v[114:129]
	v_mfma_f32_32x32x16_bf16 v[66:81], v[166:169], v[228:231], v[66:81]
	s_waitcnt lgkmcnt(4)
	v_mfma_f32_32x32x16_bf16 v[98:113], v[184:187], v[224:227], v[98:113]
	v_mfma_f32_32x32x16_bf16 v[34:49], v[184:187], v[228:231], v[34:49]
	s_waitcnt lgkmcnt(3)
	v_mfma_f32_32x32x16_bf16 v[82:97], v[194:197], v[224:227], v[82:97]
	v_mfma_f32_32x32x16_bf16 v[18:33], v[194:197], v[228:231], v[18:33]
	s_waitcnt lgkmcnt(2)
	v_mfma_f32_32x32x16_bf16 v[50:65], v[202:205], v[224:227], v[50:65]
	ds_read_b128 v[166:169], v213 offset:36896
	ds_read_b128 v[194:197], v213 offset:41504
	v_mfma_f32_32x32x16_bf16 v[2:17], v[202:205], v[228:231], v[2:17]
	v_lshl_add_u64 v[184:185], v[178:179], 0, s[96:97]
	s_waitcnt vmcnt(1)
	ds_write_b128 v214, v[154:157] offset:9216
	v_add_co_u32_e32 v154, vcc, s91, v184
	s_waitcnt vmcnt(0)
	ds_write_b128 v214, v[142:145]
	v_addc_co_u32_e32 v155, vcc, 0, v185, vcc
	global_load_dwordx4 v[142:145], v[184:185], off
	s_nop 0
	global_load_dwordx4 v[154:157], v[154:155], off
	ds_write_b128 v214, v[134:137] offset:18432
	v_lshl_add_u64 v[134:135], v[180:181], 0, s[96:97]
	ds_write_b128 v214, v[146:149] offset:27648
	v_lshl_add_u64 v[146:147], v[182:183], 0, s[96:97]
	global_load_dwordx4 v[134:137], v[134:135], off
	s_nop 0
	global_load_dwordx4 v[146:149], v[146:147], off
	ds_read_b128 v[184:187], v213 offset:46112
	ds_read_b128 v[202:205], v213 offset:50720
	ds_read_b128 v[224:227], v212 offset:64
	ds_read_b128 v[228:231], v212 offset:4672
	s_waitcnt lgkmcnt(9)
	v_mfma_f32_32x32x16_bf16 v[114:129], v[166:169], v[232:235], v[114:129]
	v_mfma_f32_32x32x16_bf16 v[66:81], v[166:169], v[236:239], v[66:81]
	s_waitcnt lgkmcnt(8)
	v_mfma_f32_32x32x16_bf16 v[98:113], v[194:197], v[232:235], v[98:113]
	v_mfma_f32_32x32x16_bf16 v[34:49], v[194:197], v[236:239], v[34:49]
	s_waitcnt lgkmcnt(3)
	v_mfma_f32_32x32x16_bf16 v[82:97], v[184:187], v[232:235], v[82:97]
	v_mfma_f32_32x32x16_bf16 v[18:33], v[184:187], v[236:239], v[18:33]
	ds_read_b128 v[166:169], v213 offset:36928
	ds_read_b128 v[184:187], v213 offset:41536
	s_waitcnt lgkmcnt(4)
	v_mfma_f32_32x32x16_bf16 v[50:65], v[202:205], v[232:235], v[50:65]
	v_mfma_f32_32x32x16_bf16 v[2:17], v[202:205], v[236:239], v[2:17]
	v_lshl_add_u64 v[188:189], v[164:165], 0, s[96:97]
	ds_write_b128 v215, v[150:153] offset:9216
	v_add_co_u32_e32 v150, vcc, s91, v188
	ds_write_b128 v215, v[138:141]
	s_nop 0
	v_addc_co_u32_e32 v151, vcc, 0, v189, vcc
	global_load_dwordx4 v[138:141], v[188:189], off
	s_nop 0
	global_load_dwordx4 v[150:153], v[150:151], off
	ds_read_b128 v[194:197], v213 offset:46144
	ds_read_b128 v[202:205], v213 offset:50752
	ds_read_b128 v[232:235], v212 offset:96
	ds_read_b128 v[236:239], v212 offset:4704
	s_waitcnt lgkmcnt(7)
	v_mfma_f32_32x32x16_bf16 v[114:129], v[166:169], v[224:227], v[114:129]
	v_mfma_f32_32x32x16_bf16 v[66:81], v[166:169], v[228:231], v[66:81]
	s_waitcnt lgkmcnt(6)
	v_mfma_f32_32x32x16_bf16 v[98:113], v[184:187], v[224:227], v[98:113]
	v_mfma_f32_32x32x16_bf16 v[34:49], v[184:187], v[228:231], v[34:49]
	s_waitcnt lgkmcnt(3)
	v_mfma_f32_32x32x16_bf16 v[82:97], v[194:197], v[224:227], v[82:97]
	ds_read_b128 v[166:169], v213 offset:36960
	ds_read_b128 v[184:187], v213 offset:41568
	v_mfma_f32_32x32x16_bf16 v[18:33], v[194:197], v[228:231], v[18:33]
	s_waitcnt lgkmcnt(4)
	v_mfma_f32_32x32x16_bf16 v[50:65], v[202:205], v[224:227], v[50:65]
	v_mfma_f32_32x32x16_bf16 v[2:17], v[202:205], v[228:231], v[2:17]
	ds_write_b128 v215, v[130:133] offset:18432
	v_add_co_u32_e32 v130, vcc, s1, v188
	ds_write_b128 v215, v[158:161] offset:27648
	s_nop 0
	v_addc_co_u32_e32 v131, vcc, 0, v189, vcc
	v_add_co_u32_e32 v158, vcc, s76, v188
	global_load_dwordx4 v[130:133], v[130:131], off
	s_nop 0
	v_addc_co_u32_e32 v159, vcc, 0, v189, vcc
	global_load_dwordx4 v[158:161], v[158:159], off
	ds_read_b128 v[194:197], v213 offset:46176
	ds_read_b128 v[202:205], v213 offset:50784
	s_waitcnt lgkmcnt(5)
	v_mfma_f32_32x32x16_bf16 v[114:129], v[166:169], v[232:235], v[114:129]
	v_mfma_f32_32x32x16_bf16 v[66:81], v[166:169], v[236:239], v[66:81]
	s_waitcnt lgkmcnt(4)
	v_mfma_f32_32x32x16_bf16 v[98:113], v[184:187], v[232:235], v[98:113]
	v_mfma_f32_32x32x16_bf16 v[34:49], v[184:187], v[236:239], v[34:49]
	s_waitcnt lgkmcnt(0)
	s_barrier
	ds_read_b128 v[224:227], v216
	ds_read_b128 v[228:231], v216 offset:4608
	ds_read_b128 v[166:169], v217
	ds_read_b128 v[184:187], v217 offset:4608
	v_mfma_f32_32x32x16_bf16 v[82:97], v[194:197], v[232:235], v[82:97]
	v_mfma_f32_32x32x16_bf16 v[18:33], v[194:197], v[236:239], v[18:33]
	ds_read_b128 v[194:197], v217 offset:9216
	v_mfma_f32_32x32x16_bf16 v[50:65], v[202:205], v[232:235], v[50:65]
	v_mfma_f32_32x32x16_bf16 v[2:17], v[202:205], v[236:239], v[2:17]
	ds_read_b128 v[202:205], v217 offset:13824
	v_add_u32_e32 v0, v210, v190
	ds_read_b128 v[232:235], v0 offset:32
	ds_read_b128 v[236:239], v218 offset:32
	s_waitcnt lgkmcnt(5)
	v_mfma_f32_32x32x16_bf16 v[114:129], v[166:169], v[224:227], v[114:129]
	v_mfma_f32_32x32x16_bf16 v[66:81], v[166:169], v[228:231], v[66:81]
	s_waitcnt lgkmcnt(4)
	v_mfma_f32_32x32x16_bf16 v[98:113], v[184:187], v[224:227], v[98:113]
	v_mfma_f32_32x32x16_bf16 v[34:49], v[184:187], v[228:231], v[34:49]
	s_waitcnt lgkmcnt(3)
	v_mfma_f32_32x32x16_bf16 v[82:97], v[194:197], v[224:227], v[82:97]
	v_add_u32_e32 v223, v211, v190
	v_mfma_f32_32x32x16_bf16 v[18:33], v[194:197], v[228:231], v[18:33]
	s_waitcnt lgkmcnt(2)
	v_mfma_f32_32x32x16_bf16 v[50:65], v[202:205], v[224:227], v[50:65]
	ds_read_b128 v[166:169], v223 offset:32
	ds_read_b128 v[194:197], v219 offset:32
	v_mfma_f32_32x32x16_bf16 v[2:17], v[202:205], v[228:231], v[2:17]
	s_mov_b32 s19, s97
	v_lshl_add_u64 v[184:185], v[178:179], 0, s[18:19]
	s_waitcnt vmcnt(6)
	ds_write_b128 v222, v[154:157] offset:9216
	v_add_co_u32_e32 v154, vcc, s91, v184
	ds_write_b128 v222, v[142:145]
	s_nop 0
	v_addc_co_u32_e32 v155, vcc, 0, v185, vcc
	global_load_dwordx4 v[142:145], v[184:185], off offset:384
	s_nop 0
	global_load_dwordx4 v[154:157], v[154:155], off offset:384
	s_waitcnt vmcnt(7)
	ds_write_b128 v222, v[134:137] offset:18432
	v_add_co_u32_e32 v134, vcc, s1, v184
	s_waitcnt vmcnt(6)
	ds_write_b128 v222, v[146:149] offset:27648
	v_addc_co_u32_e32 v135, vcc, 0, v185, vcc
	v_lshl_add_u64 v[146:147], v[182:183], 0, s[18:19]
	global_load_dwordx4 v[134:137], v[134:135], off offset:384
	s_nop 0
	global_load_dwordx4 v[146:149], v[146:147], off offset:384
	ds_read_b128 v[184:187], v220 offset:32
	ds_read_b128 v[202:205], v221 offset:32
	ds_read_b128 v[224:227], v0 offset:64
	ds_read_b128 v[228:231], v218 offset:64
	s_waitcnt lgkmcnt(9)
	v_mfma_f32_32x32x16_bf16 v[114:129], v[166:169], v[232:235], v[114:129]
	v_mfma_f32_32x32x16_bf16 v[66:81], v[166:169], v[236:239], v[66:81]
	s_waitcnt lgkmcnt(8)
	v_mfma_f32_32x32x16_bf16 v[98:113], v[194:197], v[232:235], v[98:113]
	v_mfma_f32_32x32x16_bf16 v[34:49], v[194:197], v[236:239], v[34:49]
	s_waitcnt lgkmcnt(3)
	v_mfma_f32_32x32x16_bf16 v[82:97], v[184:187], v[232:235], v[82:97]
	v_mfma_f32_32x32x16_bf16 v[18:33], v[184:187], v[236:239], v[18:33]
	ds_read_b128 v[166:169], v223 offset:64
	ds_read_b128 v[184:187], v219 offset:64
	s_waitcnt lgkmcnt(4)
	v_mfma_f32_32x32x16_bf16 v[50:65], v[202:205], v[232:235], v[50:65]
	v_mfma_f32_32x32x16_bf16 v[2:17], v[202:205], v[236:239], v[2:17]
	v_lshl_add_u64 v[188:189], v[164:165], 0, s[18:19]
	s_waitcnt vmcnt(6)
	ds_write_b128 v222, v[150:153] offset:46080
	v_add_co_u32_e32 v150, vcc, s91, v188
	ds_write_b128 v222, v[138:141] offset:36864
	s_nop 0
	v_addc_co_u32_e32 v151, vcc, 0, v189, vcc
	global_load_dwordx4 v[138:141], v[188:189], off offset:384
	s_nop 0
	global_load_dwordx4 v[150:153], v[150:151], off offset:384
	ds_read_b128 v[194:197], v220 offset:64
	ds_read_b128 v[202:205], v221 offset:64
	ds_read_b128 v[232:235], v0 offset:96
	ds_read_b128 v[236:239], v218 offset:96
	s_waitcnt lgkmcnt(7)
	v_mfma_f32_32x32x16_bf16 v[114:129], v[166:169], v[224:227], v[114:129]
	v_mfma_f32_32x32x16_bf16 v[66:81], v[166:169], v[228:231], v[66:81]
	s_waitcnt lgkmcnt(6)
	v_mfma_f32_32x32x16_bf16 v[98:113], v[184:187], v[224:227], v[98:113]
	v_mfma_f32_32x32x16_bf16 v[34:49], v[184:187], v[228:231], v[34:49]
	s_waitcnt lgkmcnt(3)
	v_mfma_f32_32x32x16_bf16 v[82:97], v[194:197], v[224:227], v[82:97]
	ds_read_b128 v[166:169], v223 offset:96
	ds_read_b128 v[184:187], v219 offset:96
	v_mfma_f32_32x32x16_bf16 v[18:33], v[194:197], v[228:231], v[18:33]
	s_waitcnt lgkmcnt(4)
	v_mfma_f32_32x32x16_bf16 v[50:65], v[202:205], v[224:227], v[50:65]
	v_mfma_f32_32x32x16_bf16 v[2:17], v[202:205], v[228:231], v[2:17]
	s_waitcnt vmcnt(7)
	ds_write_b128 v222, v[130:133] offset:55296
	v_add_co_u32_e32 v130, vcc, s1, v188
	s_waitcnt vmcnt(6)
	ds_write_b128 v222, v[158:161] offset:64512
	v_addc_co_u32_e32 v131, vcc, 0, v189, vcc
	v_add_co_u32_e32 v158, vcc, s76, v188
	global_load_dwordx4 v[130:133], v[130:131], off offset:384
	s_nop 0
	v_addc_co_u32_e32 v159, vcc, 0, v189, vcc
	global_load_dwordx4 v[158:161], v[158:159], off offset:384
	ds_read_b128 v[194:197], v220 offset:96
	ds_read_b128 v[202:205], v221 offset:96
	s_waitcnt lgkmcnt(5)
	v_mfma_f32_32x32x16_bf16 v[114:129], v[166:169], v[232:235], v[114:129]
	v_mfma_f32_32x32x16_bf16 v[66:81], v[166:169], v[236:239], v[66:81]
	s_waitcnt lgkmcnt(4)
	v_mfma_f32_32x32x16_bf16 v[98:113], v[184:187], v[232:235], v[98:113]
	v_mfma_f32_32x32x16_bf16 v[34:49], v[184:187], v[236:239], v[34:49]
	s_waitcnt lgkmcnt(0)
	s_barrier
	v_add_u32_e32 v0, v191, v208
	ds_read_b128 v[224:227], v0
	ds_read_b128 v[228:231], v0 offset:4608
	v_add_u32_e32 v0, v191, v209
	ds_read_b128 v[166:169], v0 offset:36864
	ds_read_b128 v[184:187], v0 offset:41472
	v_mfma_f32_32x32x16_bf16 v[82:97], v[194:197], v[232:235], v[82:97]
	v_mfma_f32_32x32x16_bf16 v[18:33], v[194:197], v[236:239], v[18:33]
	ds_read_b128 v[194:197], v0 offset:46080
	v_mfma_f32_32x32x16_bf16 v[50:65], v[202:205], v[232:235], v[50:65]
	v_mfma_f32_32x32x16_bf16 v[2:17], v[202:205], v[236:239], v[2:17]
	ds_read_b128 v[202:205], v0 offset:50688
	ds_read_b128 v[232:235], v212 offset:32
	ds_read_b128 v[236:239], v212 offset:4640
	s_mov_b32 s19, s5
	s_cbranch_scc0 .Lkloop_top_3
; #define RL_LOAD(XV, G) { constexpr int mt__ = (G) >> 2, half__ = ((G) >> 1) & 1, nt__ = (G) & 1; \
;     _Pragma("unroll") for (int gq = 0; gq < 4; ++gq) XV[gq] = *(const f32x4*)(xin + rbase + (size_t)mt__ * 32 * 1024 + half__ * 64 + nt__ * 32 + 4 * gq); }
; #define RL_FOLD(XV, G, SM, SQ) { constexpr int mt__ = (G) >> 2, half__ = ((G) >> 1) & 1, nt__ = (G) & 1; \
;     _Pragma("unroll") for (int gq = 0; gq < 4; ++gq) _Pragma("unroll") for (int jj = 0; jj < 4; ++jj) { \
;       const float y = ALPHA * XV[gq][jj] + acc[half__][nt__][mt__][4 * gq + jj]; acc[half__][nt__][mt__][4 * gq + jj] = y; SM += y; SQ += y * y; } }
; #define SB __builtin_amdgcn_sched_barrier(0)
;   DI void full(const int mt_, const int nt_, f32x16 (&acc)[2][2][2], const int tw, const int fw, const int r, const int hh, char* lds, const int tid) const {
;     float* part = (float*)(lds + G_STAGE);
;     const size_t rbase = (size_t)(mt_ * 256 + tw * 64 + r) * 1024 + nt_ * 256 + fw * 128 + 16 * hh;
;     f32x4 xa[4], xc[4], xe[4];
;     ...
;     float sm0 = 0.f, sq0 = 0.f, sm1 = 0.f, sq1 = 0.f;
;     RL_LOAD(xa, 0); RL_LOAD(xc, 1); RL_LOAD(xe, 2); SB;
;     RL_FOLD(xa, 0, sm0, sq0); SB; RL_LOAD(xa, 3); SB;
;     RL_FOLD(xc, 1, sm0, sq0); SB; RL_LOAD(xc, 4); SB;
;     RL_FOLD(xe, 2, sm0, sq0); SB; RL_LOAD(xe, 5); SB;
;     RL_FOLD(xa, 3, sm0, sq0); SB; RL_LOAD(xa, 6); SB;
	s_waitcnt lgkmcnt(0)
	v_mov_b32_e32 v184, v192
	s_waitcnt vmcnt(1)
	v_ashrrev_i32_e32 v130, 1, v184
	v_and_b32_e32 v223, 0xdf, v184
	v_and_b32_e32 v182, 0xffffff80, v130
	v_or_b32_e32 v0, s4, v223
	v_ashrrev_i32_e32 v183, 31, v182
	v_bfe_u32 v224, v184, 5, 1
	v_lshl_add_u64 v[130:131], v[182:183], 2, s[16:17]
	v_lshlrev_b64 v[132:133], 12, v[0:1]
	v_lshl_add_u64 v[130:131], v[130:131], 0, v[132:133]
	v_lshlrev_b32_e32 v132, 6, v224
	v_mov_b32_e32 v133, v1
	v_lshl_add_u64 v[186:187], v[130:131], 0, v[132:133]
	global_load_dwordx4 v[130:133], v[186:187], off offset:48
	global_load_dwordx4 v[134:137], v[186:187], off offset:32
	global_load_dwordx4 v[138:141], v[186:187], off offset:16
	global_load_dwordx4 v[142:145], v[186:187], off
	global_load_dwordx4 v[226:229], v[186:187], off offset:176
	global_load_dwordx4 v[230:233], v[186:187], off offset:160
	global_load_dwordx4 v[234:237], v[186:187], off offset:144
	global_load_dwordx4 v[146:149], v[186:187], off offset:128
	global_load_dwordx4 v[238:241], v[186:187], off offset:304
	global_load_dwordx4 v[242:245], v[186:187], off offset:288
	global_load_dwordx4 v[246:249], v[186:187], off offset:272
	global_load_dwordx4 v[250:253], v[186:187], off offset:256
	s_waitcnt vmcnt(8)
	v_pk_fma_f32 v[178:179], v[142:143], s[0:1], v[114:115] op_sel_hi:[1,0,1]
	v_pk_fma_f32 v[180:181], v[144:145], s[0:1], v[116:117] op_sel_hi:[1,0,1]
	v_add_f32_e32 v114, 0, v178
	v_add_f32_e32 v142, v179, v114
	v_mul_f32_e32 v114, v179, v179
	v_pk_fma_f32 v[114:115], v[178:179], v[178:179], v[114:115] op_sel_hi:[1,1,0]
	v_add_f32_e32 v116, v180, v142
	v_pk_fma_f32 v[114:115], v[180:181], v[180:181], v[114:115]
	v_add_f32_e32 v117, v181, v116
	v_mul_f32_e32 v116, v181, v181
	v_pk_fma_f32 v[158:159], v[138:139], s[0:1], v[118:119] op_sel_hi:[1,0,1]
	v_pk_add_f32 v[114:115], v[116:117], v[114:115] op_sel_hi:[0,1]
	v_add_f32_e32 v116, v158, v117
	v_pk_fma_f32 v[114:115], v[158:159], v[158:159], v[114:115]
	v_add_f32_e32 v117, v159, v116
	v_mul_f32_e32 v116, v159, v159
	v_pk_fma_f32 v[160:161], v[140:141], s[0:1], v[120:121] op_sel_hi:[1,0,1]
	v_pk_add_f32 v[114:115], v[116:117], v[114:115] op_sel_hi:[0,1]
	v_add_f32_e32 v116, v160, v117
	v_pk_fma_f32 v[114:115], v[160:161], v[160:161], v[114:115]
	v_add_f32_e32 v117, v161, v116
	v_mul_f32_e32 v116, v161, v161
	v_pk_fma_f32 v[154:155], v[134:135], s[0:1], v[122:123] op_sel_hi:[1,0,1]
	v_pk_add_f32 v[114:115], v[116:117], v[114:115] op_sel_hi:[0,1]
	v_add_f32_e32 v116, v154, v117
	v_pk_fma_f32 v[114:115], v[154:155], v[154:155], v[114:115]
	v_add_f32_e32 v117, v155, v116
	v_mul_f32_e32 v116, v155, v155
	v_pk_fma_f32 v[156:157], v[136:137], s[0:1], v[124:125] op_sel_hi:[1,0,1]
	v_pk_add_f32 v[114:115], v[116:117], v[114:115] op_sel_hi:[0,1]
	v_add_f32_e32 v116, v156, v117
	v_pk_fma_f32 v[114:115], v[156:157], v[156:157], v[114:115]
	v_add_f32_e32 v124, v157, v116
	v_mul_f32_e32 v116, v157, v157
	v_pk_add_f32 v[114:115], v[116:117], v[114:115] op_sel_hi:[0,1]
	v_pk_fma_f32 v[152:153], v[130:131], s[0:1], v[126:127] op_sel_hi:[1,0,1]
	v_pk_fma_f32 v[150:151], v[132:133], s[0:1], v[128:129] op_sel_hi:[1,0,1]
	v_pk_fma_f32 v[114:115], v[152:153], v[152:153], v[114:115]
	v_mul_f32_e32 v116, v153, v153
	v_pk_add_f32 v[114:115], v[116:117], v[114:115] op_sel_hi:[0,1]
	v_pk_fma_f32 v[114:115], v[150:151], v[150:151], v[114:115]
	v_mul_f32_e32 v116, v151, v151
	v_pk_add_f32 v[118:119], v[116:117], v[114:115] op_sel_hi:[0,1]
	global_load_dwordx4 v[114:117], v[186:187], off offset:432
	global_load_dwordx4 v[202:205], v[186:187], off offset:416
	global_load_dwordx4 v[194:197], v[186:187], off offset:400
	global_load_dwordx4 v[120:123], v[186:187], off offset:384
	v_add_f32_e32 v124, v152, v124
	v_add_f32_e32 v124, v153, v124
	v_add_f32_e32 v124, v150, v124
	v_add_f32_e32 v124, v151, v124
	s_waitcnt vmcnt(8)
	v_pk_fma_f32 v[144:145], v[146:147], s[0:1], v[98:99] op_sel_hi:[1,0,1]
	v_pk_fma_f32 v[148:149], v[148:149], s[0:1], v[100:101] op_sel_hi:[1,0,1]
	v_add_f32_e32 v124, v144, v124
	v_pk_fma_f32 v[98:99], v[144:145], v[144:145], v[118:119]
	v_add_f32_e32 v119, v145, v124
	v_mul_f32_e32 v118, v145, v145
	v_pk_add_f32 v[98:99], v[118:119], v[98:99] op_sel_hi:[0,1]
	v_add_f32_e32 v100, v148, v119
	v_pk_fma_f32 v[98:99], v[148:149], v[148:149], v[98:99]
	v_add_f32_e32 v101, v149, v100
	v_mul_f32_e32 v100, v149, v149
	v_pk_fma_f32 v[138:139], v[234:235], s[0:1], v[102:103] op_sel_hi:[1,0,1]
	v_pk_add_f32 v[98:99], v[100:101], v[98:99] op_sel_hi:[0,1]
	v_add_f32_e32 v100, v138, v101
	v_pk_fma_f32 v[98:99], v[138:139], v[138:139], v[98:99]
	v_add_f32_e32 v101, v139, v100
	v_mul_f32_e32 v100, v139, v139
	v_pk_fma_f32 v[146:147], v[236:237], s[0:1], v[104:105] op_sel_hi:[1,0,1]
	v_pk_add_f32 v[98:99], v[100:101], v[98:99] op_sel_hi:[0,1]
	v_add_f32_e32 v100, v146, v101
	v_pk_fma_f32 v[98:99], v[146:147], v[146:147], v[98:99]
	v_add_f32_e32 v101, v147, v100
	v_mul_f32_e32 v100, v147, v147
	v_pk_fma_f32 v[130:131], v[230:231], s[0:1], v[106:107] op_sel_hi:[1,0,1]
	v_pk_add_f32 v[98:99], v[100:101], v[98:99] op_sel_hi:[0,1]
	v_add_f32_e32 v100, v130, v101
	v_pk_fma_f32 v[98:99], v[130:131], v[130:131], v[98:99]
	v_add_f32_e32 v101, v131, v100
	v_mul_f32_e32 v100, v131, v131
	v_pk_fma_f32 v[140:141], v[232:233], s[0:1], v[108:109] op_sel_hi:[1,0,1]
	v_pk_add_f32 v[98:99], v[100:101], v[98:99] op_sel_hi:[0,1]
	v_add_f32_e32 v100, v140, v101
	v_pk_fma_f32 v[98:99], v[140:141], v[140:141], v[98:99]
	v_add_f32_e32 v106, v141, v100
	v_mul_f32_e32 v100, v141, v141
	v_pk_add_f32 v[102:103], v[100:101], v[98:99] op_sel_hi:[0,1]
	v_pk_fma_f32 v[124:125], v[226:227], s[0:1], v[110:111] op_sel_hi:[1,0,1]
	v_pk_fma_f32 v[134:135], v[228:229], s[0:1], v[112:113] op_sel_hi:[1,0,1]
	v_add_co_u32_e32 v188, vcc, s91, v186
	s_mov_b64 s[18:19], 0x20000
	s_nop 0
	v_addc_co_u32_e32 v189, vcc, 0, v187, vcc
	v_lshl_add_u64 v[104:105], v[186:187], 0, s[18:19]
	global_load_dwordx4 v[226:229], v[188:189], off
	global_load_dwordx4 v[98:101], v[104:105], off offset:48
	global_load_dwordx4 v[230:233], v[104:105], off offset:32
	global_load_dwordx4 v[234:237], v[104:105], off offset:16
	v_add_f32_e32 v104, v124, v106
	v_pk_fma_f32 v[102:103], v[124:125], v[124:125], v[102:103]
	v_add_f32_e32 v105, v125, v104
	v_mul_f32_e32 v104, v125, v125
	v_pk_add_f32 v[102:103], v[104:105], v[102:103] op_sel_hi:[0,1]
	v_add_f32_e32 v104, v134, v105
	v_pk_fma_f32 v[102:103], v[134:135], v[134:135], v[102:103]
	v_add_f32_e32 v105, v135, v104
	v_mul_f32_e32 v104, v135, v135
	v_pk_add_f32 v[102:103], v[104:105], v[102:103] op_sel_hi:[0,1]
	s_waitcnt vmcnt(8)
; #define RL_LOAD(XV, G) { constexpr int mt__ = (G) >> 2, half__ = ((G) >> 1) & 1, nt__ = (G) & 1; \
;     _Pragma("unroll") for (int gq = 0; gq < 4; ++gq) XV[gq] = *(const f32x4*)(xin + rbase + (size_t)mt__ * 32 * 1024 + half__ * 64 + nt__ * 32 + 4 * gq); }
; #define RL_FOLD(XV, G, SM, SQ) { constexpr int mt__ = (G) >> 2, half__ = ((G) >> 1) & 1, nt__ = (G) & 1; \
;     _Pragma("unroll") for (int gq = 0; gq < 4; ++gq) _Pragma("unroll") for (int jj = 0; jj < 4; ++jj) { \
;       const float y = ALPHA * XV[gq][jj] + acc[half__][nt__][mt__][4 * gq + jj]; acc[half__][nt__][mt__][4 * gq + jj] = y; SM += y; SQ += y * y; } }
; #define SB __builtin_amdgcn_sched_barrier(0)
;   DI void full(const int mt_, const int nt_, f32x16 (&acc)[2][2][2], const int tw, const int fw, const int r, const int hh, char* lds, const int tid) const {
;     ...
;     float sm0 = 0.f, sq0 = 0.f, sm1 = 0.f, sq1 = 0.f;
;     RL_LOAD(xa, 0); RL_LOAD(xc, 1); RL_LOAD(xe, 2); SB;
;     RL_FOLD(xa, 0, sm0, sq0); SB; RL_LOAD(xa, 3); SB;
;     RL_FOLD(xc, 1, sm0, sq0); SB; RL_LOAD(xc, 4); SB;
;     RL_FOLD(xe, 2, sm0, sq0); SB; RL_LOAD(xe, 5); SB;
;     RL_FOLD(xa, 3, sm0, sq0); SB; RL_LOAD(xa, 6); SB;
;     RL_FOLD(xc, 4, sm1, sq1); SB; RL_LOAD(xc, 7); SB;
;     RL_FOLD(xe, 5, sm1, sq1); SB;
;     RL_FOLD(xa, 6, sm1, sq1); SB;
;     RL_FOLD(xc, 7, sm1, sq1);
	v_pk_fma_f32 v[132:133], v[250:251], s[0:1], v[82:83] op_sel_hi:[1,0,1]
	v_pk_fma_f32 v[142:143], v[252:253], s[0:1], v[84:85] op_sel_hi:[1,0,1]
	v_add_f32_e32 v104, v132, v105
	v_pk_fma_f32 v[82:83], v[132:133], v[132:133], v[102:103]
	v_add_f32_e32 v103, v133, v104
	v_mul_f32_e32 v102, v133, v133
	v_pk_add_f32 v[82:83], v[102:103], v[82:83] op_sel_hi:[0,1]
	v_add_f32_e32 v84, v142, v103
	v_pk_fma_f32 v[82:83], v[142:143], v[142:143], v[82:83]
	v_add_f32_e32 v85, v143, v84
	v_mul_f32_e32 v84, v143, v143
	v_pk_fma_f32 v[126:127], v[246:247], s[0:1], v[86:87] op_sel_hi:[1,0,1]
	v_pk_add_f32 v[82:83], v[84:85], v[82:83] op_sel_hi:[0,1]
	v_add_f32_e32 v84, v126, v85
	v_pk_fma_f32 v[82:83], v[126:127], v[126:127], v[82:83]
	v_add_f32_e32 v85, v127, v84
	v_mul_f32_e32 v84, v127, v127
	v_pk_fma_f32 v[136:137], v[248:249], s[0:1], v[88:89] op_sel_hi:[1,0,1]
	v_pk_add_f32 v[82:83], v[84:85], v[82:83] op_sel_hi:[0,1]
	v_add_f32_e32 v84, v136, v85
	v_pk_fma_f32 v[82:83], v[136:137], v[136:137], v[82:83]
	v_add_f32_e32 v85, v137, v84
	v_mul_f32_e32 v84, v137, v137
	v_pk_fma_f32 v[112:113], v[242:243], s[0:1], v[90:91] op_sel_hi:[1,0,1]
	v_pk_add_f32 v[82:83], v[84:85], v[82:83] op_sel_hi:[0,1]
	v_add_f32_e32 v84, v112, v85
	v_pk_fma_f32 v[82:83], v[112:113], v[112:113], v[82:83]
	v_add_f32_e32 v85, v113, v84
	v_mul_f32_e32 v84, v113, v113
	v_pk_fma_f32 v[128:129], v[244:245], s[0:1], v[92:93] op_sel_hi:[1,0,1]
	v_pk_add_f32 v[82:83], v[84:85], v[82:83] op_sel_hi:[0,1]
	v_add_f32_e32 v84, v128, v85
	v_pk_fma_f32 v[82:83], v[128:129], v[128:129], v[82:83]
	v_add_f32_e32 v90, v129, v84
	v_mul_f32_e32 v84, v129, v129
	v_pk_add_f32 v[86:87], v[84:85], v[82:83] op_sel_hi:[0,1]
	v_pk_fma_f32 v[106:107], v[238:239], s[0:1], v[94:95] op_sel_hi:[1,0,1]
	v_pk_fma_f32 v[118:119], v[240:241], s[0:1], v[96:97] op_sel_hi:[1,0,1]
	s_mov_b64 s[18:19], 0x20080
	v_lshl_add_u64 v[88:89], v[186:187], 0, s[18:19]
	global_load_dwordx4 v[82:85], v[88:89], off offset:48
	global_load_dwordx4 v[238:241], v[88:89], off offset:32
	global_load_dwordx4 v[242:245], v[188:189], off offset:128
	global_load_dwordx4 v[246:249], v[88:89], off offset:16
	v_add_f32_e32 v88, v106, v90
	v_pk_fma_f32 v[86:87], v[106:107], v[106:107], v[86:87]
	v_add_f32_e32 v89, v107, v88
	v_mul_f32_e32 v88, v107, v107
	v_pk_add_f32 v[86:87], v[88:89], v[86:87] op_sel_hi:[0,1]
	v_add_f32_e32 v88, v118, v89
	v_pk_fma_f32 v[86:87], v[118:119], v[118:119], v[86:87]
	v_add_f32_e32 v89, v119, v88
	v_mul_f32_e32 v88, v119, v119
	v_pk_add_f32 v[86:87], v[88:89], v[86:87] op_sel_hi:[0,1]
	s_waitcnt vmcnt(8)
	v_pk_fma_f32 v[104:105], v[120:121], s[0:1], v[50:51] op_sel_hi:[1,0,1]
	v_pk_fma_f32 v[122:123], v[122:123], s[0:1], v[52:53] op_sel_hi:[1,0,1]
	v_add_f32_e32 v88, v104, v89
	v_pk_fma_f32 v[50:51], v[104:105], v[104:105], v[86:87]
	v_add_f32_e32 v87, v105, v88
	v_mul_f32_e32 v86, v105, v105
	v_add_f32_e32 v52, v122, v87
	v_pk_add_f32 v[50:51], v[86:87], v[50:51] op_sel_hi:[0,1]
	v_add_f32_e32 v52, v123, v52
	v_pk_fma_f32 v[102:103], v[194:195], s[0:1], v[54:55] op_sel_hi:[1,0,1]
	v_pk_fma_f32 v[50:51], v[122:123], v[122:123], v[50:51]
	v_add_f32_e32 v55, v102, v52
	v_mul_f32_e32 v54, v123, v123
	v_mov_b32_e32 v52, v102
	v_mov_b32_e32 v53, v123
	v_pk_add_f32 v[50:51], v[54:55], v[50:51] op_sel_hi:[0,1]
	v_pk_fma_f32 v[50:51], v[52:53], v[52:53], v[50:51]
	v_add_f32_e32 v52, v103, v55
	v_pk_fma_f32 v[120:121], v[196:197], s[0:1], v[56:57] op_sel_hi:[1,0,1]
	v_mul_f32_e32 v54, v103, v103
	v_add_f32_e32 v55, v120, v52
	v_mov_b32_e32 v52, v120
	v_mov_b32_e32 v53, v103
	v_pk_add_f32 v[50:51], v[54:55], v[50:51] op_sel_hi:[0,1]
	v_pk_fma_f32 v[50:51], v[52:53], v[52:53], v[50:51]
	v_add_f32_e32 v52, v121, v55
	v_pk_fma_f32 v[94:95], v[202:203], s[0:1], v[58:59] op_sel_hi:[1,0,1]
	v_mul_f32_e32 v54, v121, v121
	v_add_f32_e32 v55, v94, v52
	v_mov_b32_e32 v52, v94
	v_mov_b32_e32 v53, v121
	v_pk_add_f32 v[50:51], v[54:55], v[50:51] op_sel_hi:[0,1]
	v_pk_fma_f32 v[50:51], v[52:53], v[52:53], v[50:51]
	v_add_f32_e32 v52, v95, v55
	v_pk_fma_f32 v[108:109], v[204:205], s[0:1], v[60:61] op_sel_hi:[1,0,1]
	v_mul_f32_e32 v54, v95, v95
	v_add_f32_e32 v55, v108, v52
	v_mov_b32_e32 v52, v108
	v_mov_b32_e32 v53, v95
	v_pk_add_f32 v[50:51], v[54:55], v[50:51] op_sel_hi:[0,1]
	v_pk_fma_f32 v[50:51], v[52:53], v[52:53], v[50:51]
	v_pk_fma_f32 v[96:97], v[114:115], s[0:1], v[62:63] op_sel_hi:[1,0,1]
	v_mul_f32_e32 v54, v109, v109
	v_pk_fma_f32 v[110:111], v[116:117], s[0:1], v[64:65] op_sel_hi:[1,0,1]
	v_add_f32_e32 v58, v109, v55
	v_pk_add_f32 v[50:51], v[54:55], v[50:51] op_sel_hi:[0,1]
	v_mov_b32_e32 v54, v110
	v_mov_b32_e32 v55, v97
	v_mov_b32_e32 v52, v96
	v_mov_b32_e32 v53, v109
	v_pk_mul_f32 v[114:115], v[110:111], v[110:111]
	s_mov_b64 s[18:19], 0x20100
	v_lshl_add_u64 v[56:57], v[186:187], 0, s[18:19]
	global_load_dwordx4 v[194:197], v[56:57], off offset:48
	global_load_dwordx4 v[202:205], v[56:57], off offset:32
	global_load_dwordx4 v[250:253], v[188:189], off offset:256
	global_load_dwordx4 v[166:169], v[56:57], off offset:16
	v_add_f32_e32 v56, v96, v58
	v_add_f32_e32 v56, v97, v56
	v_add_f32_e32 v114, v110, v56
	s_waitcnt vmcnt(11)
	v_pk_fma_f32 v[90:91], v[226:227], s[0:1], v[66:67] op_sel_hi:[1,0,1]
	v_pk_fma_f32 v[92:93], v[228:229], s[0:1], v[68:69] op_sel_hi:[1,0,1]
	v_add_f32_e32 v56, 0, v90
	v_add_f32_e32 v58, v91, v56
	v_mul_f32_e32 v56, v91, v91
	v_pk_fma_f32 v[56:57], v[90:91], v[90:91], v[56:57] op_sel_hi:[1,1,0]
	v_add_f32_e32 v58, v92, v58
	v_pk_fma_f32 v[56:57], v[92:93], v[92:93], v[56:57]
	v_add_f32_e32 v59, v93, v58
	v_mul_f32_e32 v58, v93, v93
	s_waitcnt vmcnt(8)
; #define RL_LOAD(XV, G) { constexpr int mt__ = (G) >> 2, half__ = ((G) >> 1) & 1, nt__ = (G) & 1; \
;     _Pragma("unroll") for (int gq = 0; gq < 4; ++gq) XV[gq] = *(const f32x4*)(xin + rbase + (size_t)mt__ * 32 * 1024 + half__ * 64 + nt__ * 32 + 4 * gq); }
; #define RL_FOLD(XV, G, SM, SQ) { constexpr int mt__ = (G) >> 2, half__ = ((G) >> 1) & 1, nt__ = (G) & 1; \
;     _Pragma("unroll") for (int gq = 0; gq < 4; ++gq) _Pragma("unroll") for (int jj = 0; jj < 4; ++jj) { \
;       const float y = ALPHA * XV[gq][jj] + acc[half__][nt__][mt__][4 * gq + jj]; acc[half__][nt__][mt__][4 * gq + jj] = y; SM += y; SQ += y * y; } }
; #define SB __builtin_amdgcn_sched_barrier(0)
;   DI void full(const int mt_, const int nt_, f32x16 (&acc)[2][2][2], const int tw, const int fw, const int r, const int hh, char* lds, const int tid) const {
;     ...
;     float sm0 = 0.f, sq0 = 0.f, sm1 = 0.f, sq1 = 0.f;
;     RL_LOAD(xa, 0); RL_LOAD(xc, 1); RL_LOAD(xe, 2); SB;
;     RL_FOLD(xa, 0, sm0, sq0); SB; RL_LOAD(xa, 3); SB;
;     RL_FOLD(xc, 1, sm0, sq0); SB; RL_LOAD(xc, 4); SB;
;     RL_FOLD(xe, 2, sm0, sq0); SB; RL_LOAD(xe, 5); SB;
;     RL_FOLD(xa, 3, sm0, sq0); SB; RL_LOAD(xa, 6); SB;
;     RL_FOLD(xc, 4, sm1, sq1); SB; RL_LOAD(xc, 7); SB;
;     RL_FOLD(xe, 5, sm1, sq1); SB;
;     RL_FOLD(xa, 6, sm1, sq1); SB;
;     RL_FOLD(xc, 7, sm1, sq1);
	v_pk_fma_f32 v[86:87], v[234:235], s[0:1], v[70:71] op_sel_hi:[1,0,1]
	v_pk_add_f32 v[56:57], v[58:59], v[56:57] op_sel_hi:[0,1]
	v_add_f32_e32 v58, v86, v59
	v_pk_fma_f32 v[56:57], v[86:87], v[86:87], v[56:57]
	v_add_f32_e32 v59, v87, v58
	v_mul_f32_e32 v58, v87, v87
	v_pk_fma_f32 v[88:89], v[236:237], s[0:1], v[72:73] op_sel_hi:[1,0,1]
	v_pk_add_f32 v[56:57], v[58:59], v[56:57] op_sel_hi:[0,1]
	v_add_f32_e32 v58, v88, v59
	v_pk_fma_f32 v[56:57], v[88:89], v[88:89], v[56:57]
	v_add_f32_e32 v59, v89, v58
	v_mul_f32_e32 v58, v89, v89
	v_pk_fma_f32 v[70:71], v[230:231], s[0:1], v[74:75] op_sel_hi:[1,0,1]
	v_pk_add_f32 v[56:57], v[58:59], v[56:57] op_sel_hi:[0,1]
	v_add_f32_e32 v58, v70, v59
	v_pk_fma_f32 v[56:57], v[70:71], v[70:71], v[56:57]
	v_add_f32_e32 v59, v71, v58
	v_mul_f32_e32 v58, v71, v71
	v_pk_fma_f32 v[72:73], v[232:233], s[0:1], v[76:77] op_sel_hi:[1,0,1]
	v_pk_add_f32 v[56:57], v[58:59], v[56:57] op_sel_hi:[0,1]
	v_add_f32_e32 v58, v72, v59
	v_pk_fma_f32 v[56:57], v[72:73], v[72:73], v[56:57]
	v_add_f32_e32 v59, v73, v58
	v_mul_f32_e32 v58, v73, v73
	v_pk_fma_f32 v[50:51], v[52:53], v[52:53], v[50:51]
	v_mul_f32_e32 v52, v97, v97
	v_pk_add_f32 v[56:57], v[58:59], v[56:57] op_sel_hi:[0,1]
	v_pk_fma_f32 v[68:69], v[98:99], s[0:1], v[78:79] op_sel_hi:[1,0,1]
	v_pk_fma_f32 v[66:67], v[100:101], s[0:1], v[80:81] op_sel_hi:[1,0,1]
	v_pk_add_f32 v[50:51], v[52:53], v[50:51] op_sel_hi:[0,1]
	v_pk_fma_f32 v[74:75], v[54:55], v[54:55], v[50:51]
	s_mov_b64 s[18:19], 0x20180
	v_lshl_add_u64 v[54:55], v[186:187], 0, s[18:19]
	global_load_dwordx4 v[50:53], v[54:55], off offset:48
	global_load_dwordx4 v[76:79], v[54:55], off offset:32
	global_load_dwordx4 v[98:101], v[188:189], off offset:384
	s_nop 0
	global_load_dwordx4 v[186:189], v[54:55], off offset:16
	v_add_f32_e32 v58, v68, v59
	v_pk_fma_f32 v[54:55], v[68:69], v[68:69], v[56:57]
	v_add_f32_e32 v57, v69, v58
	v_mul_f32_e32 v56, v69, v69
	v_pk_add_f32 v[54:55], v[56:57], v[54:55] op_sel_hi:[0,1]
	v_add_f32_e32 v56, v66, v57
	v_pk_fma_f32 v[54:55], v[66:67], v[66:67], v[54:55]
	v_add_f32_e32 v57, v67, v56
	v_mul_f32_e32 v56, v67, v67
	v_pk_add_f32 v[54:55], v[56:57], v[54:55] op_sel_hi:[0,1]
	s_waitcnt vmcnt(9)
	v_pk_fma_f32 v[60:61], v[242:243], s[0:1], v[34:35] op_sel_hi:[1,0,1]
	v_pk_fma_f32 v[64:65], v[244:245], s[0:1], v[36:37] op_sel_hi:[1,0,1]
	v_add_f32_e32 v56, v60, v57
	v_pk_fma_f32 v[34:35], v[60:61], v[60:61], v[54:55]
	v_add_f32_e32 v55, v61, v56
	v_mul_f32_e32 v54, v61, v61
	v_pk_add_f32 v[34:35], v[54:55], v[34:35] op_sel_hi:[0,1]
	v_add_f32_e32 v36, v64, v55
	v_pk_fma_f32 v[34:35], v[64:65], v[64:65], v[34:35]
	v_add_f32_e32 v37, v65, v36
	v_mul_f32_e32 v36, v65, v65
	s_waitcnt vmcnt(8)
	v_pk_fma_f32 v[56:57], v[246:247], s[0:1], v[38:39] op_sel_hi:[1,0,1]
	v_pk_add_f32 v[34:35], v[36:37], v[34:35] op_sel_hi:[0,1]
	v_add_f32_e32 v36, v56, v37
	v_pk_fma_f32 v[34:35], v[56:57], v[56:57], v[34:35]
	v_add_f32_e32 v37, v57, v36
	v_mul_f32_e32 v36, v57, v57
	v_pk_fma_f32 v[62:63], v[248:249], s[0:1], v[40:41] op_sel_hi:[1,0,1]
	v_pk_add_f32 v[34:35], v[36:37], v[34:35] op_sel_hi:[0,1]
	v_add_f32_e32 v36, v62, v37
	v_pk_fma_f32 v[34:35], v[62:63], v[62:63], v[34:35]
	v_add_f32_e32 v37, v63, v36
	v_mul_f32_e32 v36, v63, v63
	v_pk_fma_f32 v[54:55], v[238:239], s[0:1], v[42:43] op_sel_hi:[1,0,1]
	v_pk_add_f32 v[34:35], v[36:37], v[34:35] op_sel_hi:[0,1]
	v_add_f32_e32 v36, v54, v37
	v_pk_fma_f32 v[34:35], v[54:55], v[54:55], v[34:35]
	v_add_f32_e32 v37, v55, v36
	v_mul_f32_e32 v36, v55, v55
	v_pk_fma_f32 v[58:59], v[240:241], s[0:1], v[44:45] op_sel_hi:[1,0,1]
	v_pk_add_f32 v[34:35], v[36:37], v[34:35] op_sel_hi:[0,1]
	v_add_f32_e32 v36, v58, v37
	v_pk_fma_f32 v[34:35], v[58:59], v[58:59], v[34:35]
	v_add_f32_e32 v37, v59, v36
	v_mul_f32_e32 v36, v59, v59
	v_pk_fma_f32 v[44:45], v[82:83], s[0:1], v[46:47] op_sel_hi:[1,0,1]
	v_pk_add_f32 v[34:35], v[36:37], v[34:35] op_sel_hi:[0,1]
	v_add_f32_e32 v36, v44, v37
	v_pk_fma_f32 v[34:35], v[44:45], v[44:45], v[34:35]
	v_add_f32_e32 v37, v45, v36
	v_mul_f32_e32 v36, v45, v45
	v_pk_fma_f32 v[46:47], v[84:85], s[0:1], v[48:49] op_sel_hi:[1,0,1]
	v_pk_add_f32 v[34:35], v[36:37], v[34:35] op_sel_hi:[0,1]
	v_add_f32_e32 v36, v46, v37
	v_pk_fma_f32 v[34:35], v[46:47], v[46:47], v[34:35]
	v_add_f32_e32 v37, v47, v36
	v_mul_f32_e32 v36, v47, v47
	v_pk_add_f32 v[34:35], v[36:37], v[34:35] op_sel_hi:[0,1]
	s_waitcnt vmcnt(5)
	v_pk_fma_f32 v[38:39], v[250:251], s[0:1], v[18:19] op_sel_hi:[1,0,1]
	v_pk_fma_f32 v[42:43], v[252:253], s[0:1], v[20:21] op_sel_hi:[1,0,1]
	v_add_f32_e32 v36, v38, v37
	v_pk_fma_f32 v[18:19], v[38:39], v[38:39], v[34:35]
	v_add_f32_e32 v35, v39, v36
	v_mul_f32_e32 v34, v39, v39
	v_pk_add_f32 v[18:19], v[34:35], v[18:19] op_sel_hi:[0,1]
	v_add_f32_e32 v20, v42, v35
	v_pk_fma_f32 v[18:19], v[42:43], v[42:43], v[18:19]
	v_add_f32_e32 v21, v43, v20
	v_mul_f32_e32 v20, v43, v43
	s_waitcnt vmcnt(4)
; #define RL_LOAD(XV, G) { constexpr int mt__ = (G) >> 2, half__ = ((G) >> 1) & 1, nt__ = (G) & 1; \
;     _Pragma("unroll") for (int gq = 0; gq < 4; ++gq) XV[gq] = *(const f32x4*)(xin + rbase + (size_t)mt__ * 32 * 1024 + half__ * 64 + nt__ * 32 + 4 * gq); }
; #define RL_FOLD(XV, G, SM, SQ) { constexpr int mt__ = (G) >> 2, half__ = ((G) >> 1) & 1, nt__ = (G) & 1; \
;     _Pragma("unroll") for (int gq = 0; gq < 4; ++gq) _Pragma("unroll") for (int jj = 0; jj < 4; ++jj) { \
;       const float y = ALPHA * XV[gq][jj] + acc[half__][nt__][mt__][4 * gq + jj]; acc[half__][nt__][mt__][4 * gq + jj] = y; SM += y; SQ += y * y; } }
; #define SB __builtin_amdgcn_sched_barrier(0)
;   DI void full(const int mt_, const int nt_, f32x16 (&acc)[2][2][2], const int tw, const int fw, const int r, const int hh, char* lds, const int tid) const {
;     ...
;     float sm0 = 0.f, sq0 = 0.f, sm1 = 0.f, sq1 = 0.f;
;     RL_LOAD(xa, 0); RL_LOAD(xc, 1); RL_LOAD(xe, 2); SB;
;     RL_FOLD(xa, 0, sm0, sq0); SB; RL_LOAD(xa, 3); SB;
;     RL_FOLD(xc, 1, sm0, sq0); SB; RL_LOAD(xc, 4); SB;
;     RL_FOLD(xe, 2, sm0, sq0); SB; RL_LOAD(xe, 5); SB;
;     RL_FOLD(xa, 3, sm0, sq0); SB; RL_LOAD(xa, 6); SB;
;     RL_FOLD(xc, 4, sm1, sq1); SB; RL_LOAD(xc, 7); SB;
;     RL_FOLD(xe, 5, sm1, sq1); SB;
;     RL_FOLD(xa, 6, sm1, sq1); SB;
;     RL_FOLD(xc, 7, sm1, sq1);
;     ...
;     sm0 += __shfl_xor(sm0, 32, 64); sq0 += __shfl_xor(sq0, 32, 64); sm1 += __shfl_xor(sm1, 32, 64); sq1 += __shfl_xor(sq1, 32, 64);
;     if (hh == 0) {
;       float* pp = part + ((fw * 256) + tw * 64 + r) * 2; pp[0] = sm0; pp[1] = sq0;
;       pp[64] = sm1; pp[65] = sq1;
	v_pk_fma_f32 v[34:35], v[166:167], s[0:1], v[22:23] op_sel_hi:[1,0,1]
	v_pk_add_f32 v[18:19], v[20:21], v[18:19] op_sel_hi:[0,1]
	v_add_f32_e32 v20, v34, v21
	v_pk_fma_f32 v[18:19], v[34:35], v[34:35], v[18:19]
	v_add_f32_e32 v21, v35, v20
	v_mul_f32_e32 v20, v35, v35
	v_pk_fma_f32 v[40:41], v[168:169], s[0:1], v[24:25] op_sel_hi:[1,0,1]
	v_pk_add_f32 v[18:19], v[20:21], v[18:19] op_sel_hi:[0,1]
	v_add_f32_e32 v20, v40, v21
	v_pk_fma_f32 v[18:19], v[40:41], v[40:41], v[18:19]
	v_add_f32_e32 v21, v41, v20
	v_mul_f32_e32 v20, v41, v41
	v_pk_fma_f32 v[26:27], v[202:203], s[0:1], v[26:27] op_sel_hi:[1,0,1]
	v_pk_add_f32 v[18:19], v[20:21], v[18:19] op_sel_hi:[0,1]
	v_add_f32_e32 v20, v26, v21
	v_pk_fma_f32 v[18:19], v[26:27], v[26:27], v[18:19]
	v_add_f32_e32 v21, v27, v20
	v_mul_f32_e32 v20, v27, v27
	v_pk_fma_f32 v[36:37], v[204:205], s[0:1], v[28:29] op_sel_hi:[1,0,1]
	v_pk_add_f32 v[18:19], v[20:21], v[18:19] op_sel_hi:[0,1]
	v_add_f32_e32 v20, v36, v21
	v_pk_fma_f32 v[18:19], v[36:37], v[36:37], v[18:19]
	v_add_f32_e32 v21, v37, v20
	v_mul_f32_e32 v20, v37, v37
	v_pk_fma_f32 v[24:25], v[194:195], s[0:1], v[30:31] op_sel_hi:[1,0,1]
	v_pk_add_f32 v[18:19], v[20:21], v[18:19] op_sel_hi:[0,1]
	v_add_f32_e32 v20, v24, v21
	v_pk_fma_f32 v[18:19], v[24:25], v[24:25], v[18:19]
	v_add_f32_e32 v21, v25, v20
	v_mul_f32_e32 v20, v25, v25
	v_pk_fma_f32 v[28:29], v[196:197], s[0:1], v[32:33] op_sel_hi:[1,0,1]
	v_pk_add_f32 v[18:19], v[20:21], v[18:19] op_sel_hi:[0,1]
	v_add_f32_e32 v20, v28, v21
	v_pk_fma_f32 v[18:19], v[28:29], v[28:29], v[18:19]
	v_add_f32_e32 v22, v29, v20
	v_mul_f32_e32 v20, v29, v29
	v_pk_add_f32 v[20:21], v[20:21], v[18:19] op_sel_hi:[0,1]
	s_waitcnt vmcnt(1)
	v_pk_fma_f32 v[18:19], v[98:99], s[0:1], v[2:3] op_sel_hi:[1,0,1]
	s_waitcnt vmcnt(0)
	v_pk_fma_f32 v[6:7], v[186:187], s[0:1], v[6:7] op_sel_hi:[1,0,1]
	v_add_f32_e32 v22, v18, v22
	v_pk_fma_f32 v[2:3], v[18:19], v[18:19], v[20:21]
	v_add_f32_e32 v21, v19, v22
	v_pk_fma_f32 v[22:23], v[100:101], s[0:1], v[4:5] op_sel_hi:[1,0,1]
	v_mul_f32_e32 v20, v19, v19
	v_add_f32_e32 v4, v22, v21
	v_pk_add_f32 v[2:3], v[20:21], v[2:3] op_sel_hi:[0,1]
	v_add_f32_e32 v4, v23, v4
	v_pk_fma_f32 v[2:3], v[22:23], v[22:23], v[2:3]
	v_add_f32_e32 v21, v6, v4
	v_mul_f32_e32 v20, v23, v23
	v_mov_b32_e32 v4, v6
	v_mov_b32_e32 v5, v23
	v_pk_add_f32 v[2:3], v[20:21], v[2:3] op_sel_hi:[0,1]
	v_pk_fma_f32 v[2:3], v[4:5], v[4:5], v[2:3]
	v_add_f32_e32 v4, v7, v21
	v_pk_fma_f32 v[20:21], v[188:189], s[0:1], v[8:9] op_sel_hi:[1,0,1]
	v_mul_f32_e32 v8, v7, v7
	v_add_f32_e32 v9, v20, v4
	v_mov_b32_e32 v4, v20
	v_mov_b32_e32 v5, v7
	v_pk_add_f32 v[2:3], v[8:9], v[2:3] op_sel_hi:[0,1]
	v_pk_fma_f32 v[4:5], v[4:5], v[4:5], v[2:3]
	v_add_f32_e32 v8, v21, v9
	v_pk_fma_f32 v[2:3], v[76:77], s[0:1], v[10:11] op_sel_hi:[1,0,1]
	v_mul_f32_e32 v10, v21, v21
	v_add_f32_e32 v11, v2, v8
	v_mov_b32_e32 v8, v2
	v_mov_b32_e32 v9, v21
	v_pk_add_f32 v[4:5], v[10:11], v[4:5] op_sel_hi:[0,1]
	v_pk_fma_f32 v[4:5], v[8:9], v[8:9], v[4:5]
	v_add_f32_e32 v10, v3, v11
	v_pk_fma_f32 v[8:9], v[78:79], s[0:1], v[12:13] op_sel_hi:[1,0,1]
	v_mul_f32_e32 v12, v3, v3
	v_add_f32_e32 v13, v8, v10
	v_mov_b32_e32 v10, v8
	v_mov_b32_e32 v11, v3
	v_pk_add_f32 v[4:5], v[12:13], v[4:5] op_sel_hi:[0,1]
	v_pk_fma_f32 v[10:11], v[10:11], v[10:11], v[4:5]
	v_add_f32_e32 v12, v9, v13
	v_pk_fma_f32 v[4:5], v[50:51], s[0:1], v[14:15] op_sel_hi:[1,0,1]
	v_mul_f32_e32 v14, v9, v9
	v_add_f32_e32 v15, v4, v12
	v_mov_b32_e32 v12, v4
	v_mov_b32_e32 v13, v9
	v_pk_add_f32 v[10:11], v[14:15], v[10:11] op_sel_hi:[0,1]
	v_pk_fma_f32 v[12:13], v[12:13], v[12:13], v[10:11]
	v_pk_fma_f32 v[10:11], v[52:53], s[0:1], v[16:17] op_sel_hi:[1,0,1]
	v_mul_f32_e32 v30, v5, v5
	v_mov_b32_e32 v16, v10
	v_mov_b32_e32 v17, v5
	v_pk_add_f32 v[12:13], v[30:31], v[12:13] op_sel_hi:[0,1]
	v_pk_fma_f32 v[12:13], v[16:17], v[16:17], v[12:13]
	v_pk_mul_f32 v[16:17], v[10:11], v[10:11]
	v_add_f32_e32 v14, v5, v15
	v_mov_b32_e32 v15, v17
	v_and_b32_e32 v17, 64, v201
	v_xor_b32_e32 v16, 32, v201
	v_add_u32_e32 v17, 64, v17
	v_add_f32_e32 v14, v10, v14
	v_pk_mov_b32 v[12:13], v[10:11], v[12:13] op_sel:[1,0]
	v_cmp_lt_i32_e32 vcc, v16, v17
	v_pk_add_f32 v[12:13], v[12:13], v[14:15]
	v_pk_mov_b32 v[14:15], v[110:111], v[74:75] op_sel:[1,0]
	v_cndmask_b32_e32 v16, v201, v16, vcc
	v_pk_add_f32 v[14:15], v[14:15], v[114:115]
	v_lshlrev_b32_e32 v31, 2, v16
	ds_bpermute_b32 v16, v31, v14
	ds_bpermute_b32 v17, v31, v15
	ds_bpermute_b32 v30, v31, v12
	ds_bpermute_b32 v31, v31, v13
	v_cmp_eq_u32_e32 vcc, 0, v224
	s_and_saveexec_b64 s[18:19], vcc
	s_cbranch_execz .LBB0_704
	v_lshlrev_b32_e32 v32, 3, v184
	v_and_b32_e32 v32, 0xfffffef8, v32
	v_add_u32_e32 v32, 0, v32
	v_add_u32_e32 v32, 0x12000, v32
	s_waitcnt lgkmcnt(2)
	v_pk_add_f32 v[14:15], v[14:15], v[16:17]
	s_waitcnt lgkmcnt(0)
	v_pk_add_f32 v[12:13], v[12:13], v[30:31]
	ds_write2_b64 v32, v[14:15], v[12:13] offset1:32

.LBB0_739:
	v_add_u32_e32 v0, v171, v172
	ds_read_b128 v[206:209], v0
	ds_read_b128 v[210:213], v0 offset:4608
	v_add_u32_e32 v0, v171, v173
	ds_read_b128 v[164:167], v0 offset:36864
	ds_read_b128 v[188:191], v0 offset:41472
	ds_read_b128 v[194:197], v0 offset:46080
	ds_read_b128 v[202:205], v0 offset:50688
	ds_read_b128 v[214:217], v176 offset:32
	ds_read_b128 v[218:221], v176 offset:4640
.Lkloop_top_4:
	s_add_i32 s29, s28, -3
	s_cmp_lt_u32 s29, 14
	s_cselect_b64 s[30:31], -1, 0
	s_and_b64 s[16:17], s[30:31], exec
	s_cselect_b32 s17, s15, s27
	s_cselect_b32 s16, s14, s26
	s_cselect_b32 s35, s13, s25
	s_cselect_b32 s34, s12, s23
	s_add_i32 s33, s28, -1
	s_waitcnt lgkmcnt(5)
	v_mfma_f32_32x32x16_bf16 v[114:129], v[164:167], v[206:209], v[114:129]
	v_mfma_f32_32x32x16_bf16 v[82:97], v[164:167], v[210:213], v[82:97]
	s_waitcnt lgkmcnt(4)
	v_mfma_f32_32x32x16_bf16 v[98:113], v[188:191], v[206:209], v[98:113]
	v_mfma_f32_32x32x16_bf16 v[66:81], v[188:191], v[210:213], v[66:81]
	s_waitcnt lgkmcnt(3)
	v_mfma_f32_32x32x16_bf16 v[50:65], v[194:197], v[206:209], v[50:65]
	s_and_b64 s[30:31], s[30:31], exec
	s_cselect_b32 s30, s33, s21
	v_mfma_f32_32x32x16_bf16 v[18:33], v[194:197], v[210:213], v[18:33]
	s_waitcnt lgkmcnt(2)
	v_mfma_f32_32x32x16_bf16 v[34:49], v[202:205], v[206:209], v[34:49]
	ds_read_b128 v[164:167], v177 offset:36896
	ds_read_b128 v[194:197], v177 offset:41504
	v_mfma_f32_32x32x16_bf16 v[2:17], v[202:205], v[210:213], v[2:17]
	s_lshl_b32 s96, s30, 7
	v_lshl_add_u64 v[168:169], s[34:35], 0, v[162:163]
	v_lshl_add_u64 v[168:169], v[168:169], 0, s[96:97]
	s_waitcnt vmcnt(6)
	ds_write_b128 v178, v[142:145] offset:9216
	v_add_co_u32_e32 v142, vcc, s91, v168
	ds_write_b128 v178, v[134:137]
	s_nop 0
	v_addc_co_u32_e32 v143, vcc, 0, v169, vcc
	global_load_dwordx4 v[134:137], v[168:169], off
	s_nop 0
	global_load_dwordx4 v[142:145], v[142:143], off
	s_waitcnt vmcnt(7)
	ds_write_b128 v178, v[130:133] offset:18432
	v_add_co_u32_e32 v130, vcc, s1, v168
	s_waitcnt vmcnt(6)
	ds_write_b128 v178, v[150:153] offset:27648
	v_addc_co_u32_e32 v131, vcc, 0, v169, vcc
	v_add_co_u32_e32 v150, vcc, s76, v168
	global_load_dwordx4 v[130:133], v[130:131], off
	s_nop 0
	v_addc_co_u32_e32 v151, vcc, 0, v169, vcc
	global_load_dwordx4 v[150:153], v[150:151], off
	ds_read_b128 v[188:191], v177 offset:46112
	ds_read_b128 v[202:205], v177 offset:50720
	ds_read_b128 v[206:209], v176 offset:64
	ds_read_b128 v[210:213], v176 offset:4672
	s_waitcnt lgkmcnt(9)
	v_mfma_f32_32x32x16_bf16 v[114:129], v[164:167], v[214:217], v[114:129]
	v_mfma_f32_32x32x16_bf16 v[82:97], v[164:167], v[218:221], v[82:97]
	s_waitcnt lgkmcnt(8)
	v_mfma_f32_32x32x16_bf16 v[98:113], v[194:197], v[214:217], v[98:113]
	v_mfma_f32_32x32x16_bf16 v[66:81], v[194:197], v[218:221], v[66:81]
	s_waitcnt lgkmcnt(3)
	v_mfma_f32_32x32x16_bf16 v[50:65], v[188:191], v[214:217], v[50:65]
	v_mfma_f32_32x32x16_bf16 v[18:33], v[188:191], v[218:221], v[18:33]
	ds_read_b128 v[164:167], v177 offset:36928
	ds_read_b128 v[188:191], v177 offset:41536
	s_waitcnt lgkmcnt(4)
	v_mfma_f32_32x32x16_bf16 v[34:49], v[202:205], v[214:217], v[34:49]
	v_mfma_f32_32x32x16_bf16 v[2:17], v[202:205], v[218:221], v[2:17]
	v_lshl_add_u64 v[168:169], s[16:17], 0, v[162:163]
	v_lshl_add_u64 v[168:169], v[168:169], 0, s[96:97]
	s_waitcnt vmcnt(6)
	ds_write_b128 v179, v[154:157] offset:9216
	v_add_co_u32_e32 v154, vcc, s91, v168
	ds_write_b128 v179, v[138:141]
	s_nop 0
	v_addc_co_u32_e32 v155, vcc, 0, v169, vcc
	global_load_dwordx4 v[138:141], v[168:169], off
	s_nop 0
	global_load_dwordx4 v[154:157], v[154:155], off
	ds_read_b128 v[194:197], v177 offset:46144
	ds_read_b128 v[202:205], v177 offset:50752
	ds_read_b128 v[214:217], v176 offset:96
	ds_read_b128 v[218:221], v176 offset:4704
	s_waitcnt lgkmcnt(7)
	v_mfma_f32_32x32x16_bf16 v[114:129], v[164:167], v[206:209], v[114:129]
	v_mfma_f32_32x32x16_bf16 v[82:97], v[164:167], v[210:213], v[82:97]
	s_waitcnt lgkmcnt(6)
	v_mfma_f32_32x32x16_bf16 v[98:113], v[188:191], v[206:209], v[98:113]
	v_mfma_f32_32x32x16_bf16 v[66:81], v[188:191], v[210:213], v[66:81]
	s_waitcnt lgkmcnt(3)
	v_mfma_f32_32x32x16_bf16 v[50:65], v[194:197], v[206:209], v[50:65]
	ds_read_b128 v[164:167], v177 offset:36960
	ds_read_b128 v[188:191], v177 offset:41568
	v_mfma_f32_32x32x16_bf16 v[18:33], v[194:197], v[210:213], v[18:33]
	s_waitcnt lgkmcnt(4)
	v_mfma_f32_32x32x16_bf16 v[34:49], v[202:205], v[206:209], v[34:49]
	v_mfma_f32_32x32x16_bf16 v[2:17], v[202:205], v[210:213], v[2:17]
	s_waitcnt vmcnt(7)
	ds_write_b128 v179, v[146:149] offset:18432
	v_add_co_u32_e32 v146, vcc, s1, v168
	s_waitcnt vmcnt(6)
	ds_write_b128 v179, v[158:161] offset:27648
	v_addc_co_u32_e32 v147, vcc, 0, v169, vcc
	v_add_co_u32_e32 v158, vcc, s76, v168
	global_load_dwordx4 v[146:149], v[146:147], off
	s_nop 0
	v_addc_co_u32_e32 v159, vcc, 0, v169, vcc
	global_load_dwordx4 v[158:161], v[158:159], off
	ds_read_b128 v[194:197], v177 offset:46176
	ds_read_b128 v[202:205], v177 offset:50784
	s_waitcnt lgkmcnt(5)
	v_mfma_f32_32x32x16_bf16 v[114:129], v[164:167], v[214:217], v[114:129]
	v_mfma_f32_32x32x16_bf16 v[82:97], v[164:167], v[218:221], v[82:97]
	s_waitcnt lgkmcnt(4)
	v_mfma_f32_32x32x16_bf16 v[98:113], v[188:191], v[214:217], v[98:113]
	v_mfma_f32_32x32x16_bf16 v[66:81], v[188:191], v[218:221], v[66:81]
	s_waitcnt lgkmcnt(0)
	s_barrier
	ds_read_b128 v[206:209], v180
	ds_read_b128 v[210:213], v180 offset:4608
	ds_read_b128 v[164:167], v181
	ds_read_b128 v[188:191], v181 offset:4608
	v_mfma_f32_32x32x16_bf16 v[50:65], v[194:197], v[214:217], v[50:65]
	v_mfma_f32_32x32x16_bf16 v[18:33], v[194:197], v[218:221], v[18:33]
	ds_read_b128 v[194:197], v181 offset:9216
	v_mfma_f32_32x32x16_bf16 v[34:49], v[202:205], v[214:217], v[34:49]
	v_mfma_f32_32x32x16_bf16 v[2:17], v[202:205], v[218:221], v[2:17]
	ds_read_b128 v[202:205], v181 offset:13824
	v_add_u32_e32 v0, v174, v170
	ds_read_b128 v[214:217], v0 offset:32
	ds_read_b128 v[218:221], v182 offset:32
	s_cmp_lt_u32 s29, 13
	s_cselect_b64 s[16:17], -1, 0
	s_and_b64 s[16:17], s[16:17], exec
	s_cselect_b32 s31, s13, s25
	s_cselect_b32 s30, s12, s23
	s_cselect_b32 s17, s15, s27
	s_cselect_b32 s16, s14, s26
	s_waitcnt lgkmcnt(5)
	v_mfma_f32_32x32x16_bf16 v[114:129], v[164:167], v[206:209], v[114:129]
	v_mfma_f32_32x32x16_bf16 v[82:97], v[164:167], v[210:213], v[82:97]
	s_waitcnt lgkmcnt(4)
	v_mfma_f32_32x32x16_bf16 v[98:113], v[188:191], v[206:209], v[98:113]
	v_mfma_f32_32x32x16_bf16 v[66:81], v[188:191], v[210:213], v[66:81]
	s_waitcnt lgkmcnt(3)
	v_mfma_f32_32x32x16_bf16 v[50:65], v[194:197], v[206:209], v[50:65]
	v_add_u32_e32 v187, v175, v170
	s_cselect_b32 s33, s28, s22
	v_mfma_f32_32x32x16_bf16 v[18:33], v[194:197], v[210:213], v[18:33]
	s_waitcnt lgkmcnt(2)
	v_mfma_f32_32x32x16_bf16 v[34:49], v[202:205], v[206:209], v[34:49]
	ds_read_b128 v[164:167], v187 offset:32
	ds_read_b128 v[194:197], v183 offset:32
	v_mfma_f32_32x32x16_bf16 v[2:17], v[202:205], v[210:213], v[2:17]
	s_lshl_b32 s96, s33, 7
	v_lshl_add_u64 v[168:169], s[30:31], 0, v[162:163]
	v_lshl_add_u64 v[168:169], v[168:169], 0, s[96:97]
	s_waitcnt vmcnt(6)
	ds_write_b128 v186, v[142:145] offset:9216
	v_add_co_u32_e32 v142, vcc, s91, v168
	ds_write_b128 v186, v[134:137]
	s_nop 0
	v_addc_co_u32_e32 v143, vcc, 0, v169, vcc
	global_load_dwordx4 v[134:137], v[168:169], off
	s_nop 0
	global_load_dwordx4 v[142:145], v[142:143], off
	s_waitcnt vmcnt(7)
	ds_write_b128 v186, v[130:133] offset:18432
	v_add_co_u32_e32 v130, vcc, s1, v168
	s_waitcnt vmcnt(6)
	ds_write_b128 v186, v[150:153] offset:27648
	v_addc_co_u32_e32 v131, vcc, 0, v169, vcc
	v_add_co_u32_e32 v150, vcc, s76, v168
	global_load_dwordx4 v[130:133], v[130:131], off
	s_nop 0
	v_addc_co_u32_e32 v151, vcc, 0, v169, vcc
	global_load_dwordx4 v[150:153], v[150:151], off
	ds_read_b128 v[188:191], v184 offset:32
	ds_read_b128 v[202:205], v185 offset:32
	ds_read_b128 v[206:209], v0 offset:64
	ds_read_b128 v[210:213], v182 offset:64
	s_waitcnt lgkmcnt(9)
	v_mfma_f32_32x32x16_bf16 v[114:129], v[164:167], v[214:217], v[114:129]
	v_mfma_f32_32x32x16_bf16 v[82:97], v[164:167], v[218:221], v[82:97]
	s_waitcnt lgkmcnt(8)
	v_mfma_f32_32x32x16_bf16 v[98:113], v[194:197], v[214:217], v[98:113]
	v_mfma_f32_32x32x16_bf16 v[66:81], v[194:197], v[218:221], v[66:81]
	s_waitcnt lgkmcnt(3)
	v_mfma_f32_32x32x16_bf16 v[50:65], v[188:191], v[214:217], v[50:65]
	v_mfma_f32_32x32x16_bf16 v[18:33], v[188:191], v[218:221], v[18:33]
	ds_read_b128 v[164:167], v187 offset:64
	ds_read_b128 v[188:191], v183 offset:64
	s_waitcnt lgkmcnt(4)
	v_mfma_f32_32x32x16_bf16 v[34:49], v[202:205], v[214:217], v[34:49]
	v_mfma_f32_32x32x16_bf16 v[2:17], v[202:205], v[218:221], v[2:17]
	v_lshl_add_u64 v[168:169], s[16:17], 0, v[162:163]
	v_lshl_add_u64 v[168:169], v[168:169], 0, s[96:97]
	s_waitcnt vmcnt(6)
	ds_write_b128 v186, v[154:157] offset:46080
	v_add_co_u32_e32 v154, vcc, s91, v168
	ds_write_b128 v186, v[138:141] offset:36864
	s_nop 0
	v_addc_co_u32_e32 v155, vcc, 0, v169, vcc
	global_load_dwordx4 v[138:141], v[168:169], off
	s_nop 0
	global_load_dwordx4 v[154:157], v[154:155], off
	ds_read_b128 v[194:197], v184 offset:64
	ds_read_b128 v[202:205], v185 offset:64
	ds_read_b128 v[214:217], v0 offset:96
	ds_read_b128 v[218:221], v182 offset:96
	s_waitcnt lgkmcnt(7)
	v_mfma_f32_32x32x16_bf16 v[114:129], v[164:167], v[206:209], v[114:129]
	v_mfma_f32_32x32x16_bf16 v[82:97], v[164:167], v[210:213], v[82:97]
	s_waitcnt lgkmcnt(6)
	v_mfma_f32_32x32x16_bf16 v[98:113], v[188:191], v[206:209], v[98:113]
	v_mfma_f32_32x32x16_bf16 v[66:81], v[188:191], v[210:213], v[66:81]
	s_waitcnt lgkmcnt(3)
	v_mfma_f32_32x32x16_bf16 v[50:65], v[194:197], v[206:209], v[50:65]
	ds_read_b128 v[164:167], v187 offset:96
	ds_read_b128 v[188:191], v183 offset:96
	v_mfma_f32_32x32x16_bf16 v[18:33], v[194:197], v[210:213], v[18:33]
	s_waitcnt lgkmcnt(4)
	v_mfma_f32_32x32x16_bf16 v[34:49], v[202:205], v[206:209], v[34:49]
	v_mfma_f32_32x32x16_bf16 v[2:17], v[202:205], v[210:213], v[2:17]
	s_waitcnt vmcnt(7)
	ds_write_b128 v186, v[146:149] offset:55296
	v_add_co_u32_e32 v146, vcc, s1, v168
	s_waitcnt vmcnt(6)
	ds_write_b128 v186, v[158:161] offset:64512
	v_addc_co_u32_e32 v147, vcc, 0, v169, vcc
	v_add_co_u32_e32 v158, vcc, s76, v168
	global_load_dwordx4 v[146:149], v[146:147], off
	s_nop 0
	v_addc_co_u32_e32 v159, vcc, 0, v169, vcc
	global_load_dwordx4 v[158:161], v[158:159], off
	ds_read_b128 v[194:197], v184 offset:96
	ds_read_b128 v[202:205], v185 offset:96
	s_waitcnt lgkmcnt(5)
	v_mfma_f32_32x32x16_bf16 v[114:129], v[164:167], v[214:217], v[114:129]
	v_mfma_f32_32x32x16_bf16 v[82:97], v[164:167], v[218:221], v[82:97]
	s_waitcnt lgkmcnt(4)
	v_mfma_f32_32x32x16_bf16 v[98:113], v[188:191], v[214:217], v[98:113]
	v_mfma_f32_32x32x16_bf16 v[66:81], v[188:191], v[218:221], v[66:81]
	s_waitcnt lgkmcnt(0)
	s_barrier
; DI unsigned pk2(float lo, float hi) { f32x2 v = {lo, hi}; bf16x2v b = __builtin_convertvector(v, bf16x2v); return __builtin_bit_cast(unsigned, b); }
; DI float siluf_(float x) { return x * __builtin_amdgcn_rcpf(1.f + __builtin_amdgcn_exp2f(-LOG2E * x)); }
;   DI void operator()(int tok0, int feat0, f32x16 (&acc)[2][2], int r, int hh) const {
;     const int u0 = (feat0 >> 6) * 32;
; #pragma unroll
;     for (int mt = 0; mt < 2; ++mt) {
;       bf16_t* dst = act + (size_t)(tok0 + mt * 32 + r) * DFF + u0 + 16 * hh;
; #pragma unroll
;       for (int gp = 0; gp < 2; ++gp) {
;         u32x4 o;
; #pragma unroll
;         for (int q = 0; q < 4; ++q) { const int i = 8 * gp + 2 * q; o[q] = pk2(siluf_(acc[0][mt][i]) * acc[1][mt][i], siluf_(acc[0][mt][i + 1]) * acc[1][mt][i + 1]); }
;         *(u32x4*)(dst + 8 * gp) = o;
;       }
;     }
	v_add_u32_e32 v0, v171, v172
	ds_read_b128 v[206:209], v0
	ds_read_b128 v[210:213], v0 offset:4608
	v_add_u32_e32 v0, v171, v173
	ds_read_b128 v[164:167], v0 offset:36864
	ds_read_b128 v[188:191], v0 offset:41472
	v_mfma_f32_32x32x16_bf16 v[50:65], v[194:197], v[214:217], v[50:65]
	v_mfma_f32_32x32x16_bf16 v[18:33], v[194:197], v[218:221], v[18:33]
	ds_read_b128 v[194:197], v0 offset:46080
	v_mfma_f32_32x32x16_bf16 v[34:49], v[202:205], v[214:217], v[34:49]
	v_mfma_f32_32x32x16_bf16 v[2:17], v[202:205], v[218:221], v[2:17]
	ds_read_b128 v[202:205], v0 offset:50688
	ds_read_b128 v[214:217], v176 offset:32
	ds_read_b128 v[218:221], v176 offset:4640
	s_add_i32 s28, s28, 2
	s_cmp_gt_u32 s29, 13
	s_cbranch_scc0 .Lkloop_top_4
	s_waitcnt lgkmcnt(0)
	v_mov_b32_e32 v0, v192
	v_mov_b64_e32 v[166:167], s[6:7]
	v_ashrrev_i32_e32 v164, 1, v0
	v_and_b32_e32 v164, 0xffffff80, v164
	v_add_u32_e32 v164, s3, v164
	v_ashrrev_i32_e32 v164, 1, v164
	v_and_b32_e32 v165, 0xdf, v0
	v_or_b32_e32 v187, s8, v165
	v_ashrrev_i32_e32 v165, 31, v164
	v_mad_i64_i32 v[188:189], s[12:13], v187, s69, v[166:167]
	v_lshlrev_b64 v[168:169], 1, v[164:165]
	v_lshl_add_u64 v[164:165], v[188:189], 0, v[168:169]
	v_mul_f32_e32 v188, 0xbfb8aa3b, v114
	v_mul_f32_e32 v189, 0xbfb8aa3b, v115
	v_exp_f32_e32 v188, v188
	v_exp_f32_e32 v189, v189
	v_and_b32_e32 v0, 32, v0
	v_lshl_add_u64 v[164:165], v[164:165], 0, v[0:1]
	v_add_f32_e32 v188, 1.0, v188
	v_add_f32_e32 v189, 1.0, v189
	v_rcp_f32_e32 v188, v188
	v_rcp_f32_e32 v189, v189
	s_nop 0
	v_pk_mul_f32 v[114:115], v[114:115], v[188:189]
	s_nop 0
	v_pk_mul_f32 v[98:99], v[98:99], v[114:115]
	s_nop 0
	v_cvt_pk_bf16_f32 v98, v98, v99
	v_mul_f32_e32 v99, 0xbfb8aa3b, v116
	v_exp_f32_e32 v99, v99
	s_nop 0
	v_add_f32_e32 v99, 1.0, v99
	v_rcp_f32_e32 v114, v99
	v_mul_f32_e32 v99, 0xbfb8aa3b, v117
	v_exp_f32_e32 v99, v99
	s_nop 0
	v_add_f32_e32 v99, 1.0, v99
	v_rcp_f32_e32 v115, v99
	s_nop 0
	v_pk_mul_f32 v[114:115], v[116:117], v[114:115]
	s_nop 0
	v_pk_mul_f32 v[100:101], v[100:101], v[114:115]
	s_nop 0
	v_cvt_pk_bf16_f32 v99, v100, v101
	v_mul_f32_e32 v100, 0xbfb8aa3b, v118
	v_mul_f32_e32 v101, 0xbfb8aa3b, v119
	v_exp_f32_e32 v100, v100
	v_exp_f32_e32 v101, v101
	v_add_f32_e32 v100, 1.0, v100
	v_add_f32_e32 v101, 1.0, v101
	v_rcp_f32_e32 v100, v100
	v_rcp_f32_e32 v101, v101
	s_nop 0
	v_pk_mul_f32 v[100:101], v[118:119], v[100:101]
	s_nop 0
	v_pk_mul_f32 v[100:101], v[102:103], v[100:101]
	s_nop 0
	v_cvt_pk_bf16_f32 v100, v100, v101
	v_mul_f32_e32 v101, 0xbfb8aa3b, v120
	v_exp_f32_e32 v101, v101
	s_nop 0
	v_add_f32_e32 v101, 1.0, v101
	v_rcp_f32_e32 v102, v101
	v_mul_f32_e32 v101, 0xbfb8aa3b, v121
	v_exp_f32_e32 v101, v101
	s_nop 0
	v_add_f32_e32 v101, 1.0, v101
	v_rcp_f32_e32 v103, v101
	s_nop 0
	v_pk_mul_f32 v[102:103], v[120:121], v[102:103]
	s_nop 0
	v_pk_mul_f32 v[102:103], v[104:105], v[102:103]
	s_nop 0
	v_cvt_pk_bf16_f32 v101, v102, v103
	global_store_dwordx4 v[164:165], v[98:101], off
	s_nop 1
	v_mul_f32_e32 v98, 0xbfb8aa3b, v122
	v_mul_f32_e32 v99, 0xbfb8aa3b, v123
	v_exp_f32_e32 v98, v98
	v_exp_f32_e32 v99, v99
	v_add_f32_e32 v98, 1.0, v98
	v_add_f32_e32 v99, 1.0, v99
	v_rcp_f32_e32 v98, v98
	v_rcp_f32_e32 v99, v99
	s_nop 0
	v_pk_mul_f32 v[98:99], v[122:123], v[98:99]
	s_nop 0
	v_pk_mul_f32 v[98:99], v[106:107], v[98:99]
	s_nop 0
	v_cvt_pk_bf16_f32 v98, v98, v99
	v_mul_f32_e32 v99, 0xbfb8aa3b, v124
	v_exp_f32_e32 v99, v99
	s_nop 0
	v_add_f32_e32 v99, 1.0, v99
	v_rcp_f32_e32 v100, v99
	v_mul_f32_e32 v99, 0xbfb8aa3b, v125
	v_exp_f32_e32 v99, v99
	s_nop 0
	v_add_f32_e32 v99, 1.0, v99
	v_rcp_f32_e32 v101, v99
	s_nop 0
	v_pk_mul_f32 v[100:101], v[124:125], v[100:101]
	s_nop 0
	v_pk_mul_f32 v[100:101], v[108:109], v[100:101]
	s_nop 0
	v_cvt_pk_bf16_f32 v99, v100, v101
	v_mul_f32_e32 v100, 0xbfb8aa3b, v126
	v_mul_f32_e32 v101, 0xbfb8aa3b, v127
	v_exp_f32_e32 v100, v100
	v_exp_f32_e32 v101, v101
	v_add_f32_e32 v100, 1.0, v100
	v_add_f32_e32 v101, 1.0, v101
	v_rcp_f32_e32 v100, v100
	v_rcp_f32_e32 v101, v101
	s_nop 0
	v_pk_mul_f32 v[100:101], v[126:127], v[100:101]
	s_nop 0
	v_pk_mul_f32 v[100:101], v[110:111], v[100:101]
	s_nop 0
	v_cvt_pk_bf16_f32 v100, v100, v101
	v_mul_f32_e32 v101, 0xbfb8aa3b, v128
	v_exp_f32_e32 v101, v101
	s_nop 0
	v_add_f32_e32 v101, 1.0, v101
	v_rcp_f32_e32 v102, v101
	v_mul_f32_e32 v101, 0xbfb8aa3b, v129
	v_exp_f32_e32 v101, v101
	s_nop 0
	v_add_f32_e32 v101, 1.0, v101
	v_rcp_f32_e32 v103, v101
	s_nop 0
	v_pk_mul_f32 v[102:103], v[128:129], v[102:103]
	s_nop 0
	v_pk_mul_f32 v[102:103], v[112:113], v[102:103]
	s_nop 0
	v_cvt_pk_bf16_f32 v101, v102, v103
	global_store_dwordx4 v[164:165], v[98:101], off offset:16
	s_nop 1
	v_or_b32_e32 v98, 32, v187
	v_mad_i64_i32 v[98:99], s[12:13], v98, s69, v[166:167]
	v_lshl_add_u64 v[98:99], v[98:99], 0, v[168:169]
	v_lshl_add_u64 v[98:99], v[98:99], 0, v[0:1]
	v_mul_f32_e32 v0, 0xbfb8aa3b, v82
	v_exp_f32_e32 v0, v0
	s_nop 0
	v_add_f32_e32 v0, 1.0, v0
	v_rcp_f32_e32 v100, v0
	v_mul_f32_e32 v0, 0xbfb8aa3b, v83
	v_exp_f32_e32 v0, v0
	s_nop 0
	v_add_f32_e32 v0, 1.0, v0
	v_rcp_f32_e32 v101, v0
	v_mul_f32_e32 v0, 0xbfb8aa3b, v84
	v_exp_f32_e32 v0, v0
	v_pk_mul_f32 v[82:83], v[82:83], v[100:101]
	s_nop 0
	v_pk_mul_f32 v[66:67], v[66:67], v[82:83]
	v_add_f32_e32 v0, 1.0, v0
	v_rcp_f32_e32 v82, v0
	v_mul_f32_e32 v0, 0xbfb8aa3b, v85
	v_exp_f32_e32 v0, v0
	v_cvt_pk_bf16_f32 v66, v66, v67
	v_add_f32_e32 v0, 1.0, v0
	v_rcp_f32_e32 v83, v0
	v_mul_f32_e32 v0, 0xbfb8aa3b, v86
	v_exp_f32_e32 v0, v0
	v_pk_mul_f32 v[82:83], v[84:85], v[82:83]
	s_nop 0
	v_pk_mul_f32 v[68:69], v[68:69], v[82:83]
	v_add_f32_e32 v0, 1.0, v0
	v_cvt_pk_bf16_f32 v67, v68, v69
	v_rcp_f32_e32 v68, v0
; DI unsigned pk2(float lo, float hi) { f32x2 v = {lo, hi}; bf16x2v b = __builtin_convertvector(v, bf16x2v); return __builtin_bit_cast(unsigned, b); }
; DI float siluf_(float x) { return x * __builtin_amdgcn_rcpf(1.f + __builtin_amdgcn_exp2f(-LOG2E * x)); }
;   DI void operator()(int tok0, int feat0, f32x16 (&acc)[2][2], int r, int hh) const {
;     const int u0 = (feat0 >> 6) * 32;
; #pragma unroll
;     for (int mt = 0; mt < 2; ++mt) {
;       bf16_t* dst = act + (size_t)(tok0 + mt * 32 + r) * DFF + u0 + 16 * hh;
; #pragma unroll
;       for (int gp = 0; gp < 2; ++gp) {
;         u32x4 o;
; #pragma unroll
;         for (int q = 0; q < 4; ++q) { const int i = 8 * gp + 2 * q; o[q] = pk2(siluf_(acc[0][mt][i]) * acc[1][mt][i], siluf_(acc[0][mt][i + 1]) * acc[1][mt][i + 1]); }
;         *(u32x4*)(dst + 8 * gp) = o;
;       }
;     }
	v_mul_f32_e32 v0, 0xbfb8aa3b, v87
	v_exp_f32_e32 v0, v0
	s_nop 0
	v_add_f32_e32 v0, 1.0, v0
	v_rcp_f32_e32 v69, v0
	v_mul_f32_e32 v0, 0xbfb8aa3b, v88
	v_exp_f32_e32 v0, v0
	v_pk_mul_f32 v[68:69], v[86:87], v[68:69]
	s_nop 0
	v_pk_mul_f32 v[68:69], v[70:71], v[68:69]
	v_add_f32_e32 v0, 1.0, v0
	v_rcp_f32_e32 v70, v0
	v_mul_f32_e32 v0, 0xbfb8aa3b, v89
	v_exp_f32_e32 v0, v0
	v_cvt_pk_bf16_f32 v68, v68, v69
	v_add_f32_e32 v0, 1.0, v0
	v_rcp_f32_e32 v71, v0
	v_mul_f32_e32 v0, 0xbfb8aa3b, v90
	v_exp_f32_e32 v0, v0
	v_pk_mul_f32 v[70:71], v[88:89], v[70:71]
	s_nop 0
	v_pk_mul_f32 v[70:71], v[72:73], v[70:71]
	v_add_f32_e32 v0, 1.0, v0
	v_cvt_pk_bf16_f32 v69, v70, v71
	global_store_dwordx4 v[98:99], v[66:69], off
	s_nop 1
	v_rcp_f32_e32 v66, v0
	v_mul_f32_e32 v0, 0xbfb8aa3b, v91
	v_exp_f32_e32 v0, v0
	s_nop 0
	v_add_f32_e32 v0, 1.0, v0
	v_rcp_f32_e32 v67, v0
	v_mul_f32_e32 v0, 0xbfb8aa3b, v92
	v_exp_f32_e32 v0, v0
	v_pk_mul_f32 v[66:67], v[90:91], v[66:67]
	s_nop 0
	v_pk_mul_f32 v[66:67], v[74:75], v[66:67]
	v_add_f32_e32 v0, 1.0, v0
	v_rcp_f32_e32 v68, v0
	v_mul_f32_e32 v0, 0xbfb8aa3b, v93
	v_exp_f32_e32 v0, v0
	v_cvt_pk_bf16_f32 v66, v66, v67
	v_add_f32_e32 v0, 1.0, v0
	v_rcp_f32_e32 v69, v0
	v_mul_f32_e32 v0, 0xbfb8aa3b, v94
	v_exp_f32_e32 v0, v0
	v_pk_mul_f32 v[68:69], v[92:93], v[68:69]
	s_nop 0
	v_pk_mul_f32 v[68:69], v[76:77], v[68:69]
	v_add_f32_e32 v0, 1.0, v0
	v_cvt_pk_bf16_f32 v67, v68, v69
	v_rcp_f32_e32 v68, v0
	v_mul_f32_e32 v0, 0xbfb8aa3b, v95
	v_exp_f32_e32 v0, v0
	s_nop 0
	v_add_f32_e32 v0, 1.0, v0
	v_rcp_f32_e32 v69, v0
	v_mul_f32_e32 v0, 0xbfb8aa3b, v96
	v_exp_f32_e32 v0, v0
	v_pk_mul_f32 v[68:69], v[94:95], v[68:69]
	s_nop 0
	v_pk_mul_f32 v[68:69], v[78:79], v[68:69]
	v_add_f32_e32 v0, 1.0, v0
	v_rcp_f32_e32 v70, v0
	v_mul_f32_e32 v0, 0xbfb8aa3b, v97
	v_exp_f32_e32 v0, v0
	v_cvt_pk_bf16_f32 v68, v68, v69
	v_add_f32_e32 v0, 1.0, v0
	v_rcp_f32_e32 v71, v0
	s_nop 0
	v_pk_mul_f32 v[70:71], v[96:97], v[70:71]
	s_nop 0
	v_pk_mul_f32 v[70:71], v[80:81], v[70:71]
	s_nop 0
	v_cvt_pk_bf16_f32 v69, v70, v71
	global_store_dwordx4 v[98:99], v[66:69], off offset:16
	v_mul_f32_e32 v0, 0xbfb8aa3b, v50
	v_exp_f32_e32 v0, v0
	s_nop 0
	v_add_f32_e32 v0, 1.0, v0
	v_rcp_f32_e32 v66, v0
	v_mul_f32_e32 v0, 0xbfb8aa3b, v51
	v_exp_f32_e32 v0, v0
	s_nop 0
	v_add_f32_e32 v0, 1.0, v0
	v_rcp_f32_e32 v67, v0
	v_mul_f32_e32 v0, 0xbfb8aa3b, v52
	v_exp_f32_e32 v0, v0
	v_pk_mul_f32 v[50:51], v[50:51], v[66:67]
	s_nop 0
	v_pk_mul_f32 v[34:35], v[34:35], v[50:51]
	v_add_f32_e32 v0, 1.0, v0
	v_rcp_f32_e32 v50, v0
	v_mul_f32_e32 v0, 0xbfb8aa3b, v53
	v_exp_f32_e32 v0, v0
	v_cvt_pk_bf16_f32 v34, v34, v35
	v_add_f32_e32 v0, 1.0, v0
	v_rcp_f32_e32 v51, v0
	v_mul_f32_e32 v0, 0xbfb8aa3b, v54
	v_exp_f32_e32 v0, v0
	v_pk_mul_f32 v[50:51], v[52:53], v[50:51]
	s_nop 0
	v_pk_mul_f32 v[36:37], v[36:37], v[50:51]
	v_add_f32_e32 v0, 1.0, v0
	v_cvt_pk_bf16_f32 v35, v36, v37
	v_rcp_f32_e32 v36, v0
	v_mul_f32_e32 v0, 0xbfb8aa3b, v55
	v_exp_f32_e32 v0, v0
	s_nop 0
	v_add_f32_e32 v0, 1.0, v0
	v_rcp_f32_e32 v37, v0
	v_mul_f32_e32 v0, 0xbfb8aa3b, v56
	v_exp_f32_e32 v0, v0
	v_pk_mul_f32 v[36:37], v[54:55], v[36:37]
	s_nop 0
	v_pk_mul_f32 v[36:37], v[38:39], v[36:37]
	v_add_f32_e32 v0, 1.0, v0
	v_rcp_f32_e32 v38, v0
	v_mul_f32_e32 v0, 0xbfb8aa3b, v57
	v_exp_f32_e32 v0, v0
	v_cvt_pk_bf16_f32 v36, v36, v37
	v_add_f32_e32 v0, 1.0, v0
	v_rcp_f32_e32 v39, v0
	v_mul_f32_e32 v0, 0xbfb8aa3b, v58
	v_exp_f32_e32 v0, v0
	v_pk_mul_f32 v[38:39], v[56:57], v[38:39]
	s_nop 0
	v_pk_mul_f32 v[38:39], v[40:41], v[38:39]
	v_add_f32_e32 v0, 1.0, v0
	v_cvt_pk_bf16_f32 v37, v38, v39
	global_store_dwordx4 v[164:165], v[34:37], off offset:64
	s_nop 1
	v_rcp_f32_e32 v34, v0
	v_mul_f32_e32 v0, 0xbfb8aa3b, v59
	v_exp_f32_e32 v0, v0
	s_nop 0
	v_add_f32_e32 v0, 1.0, v0
	v_rcp_f32_e32 v35, v0
	v_mul_f32_e32 v0, 0xbfb8aa3b, v60
	v_exp_f32_e32 v0, v0
	v_pk_mul_f32 v[34:35], v[58:59], v[34:35]
	s_nop 0
	v_pk_mul_f32 v[34:35], v[42:43], v[34:35]
	v_add_f32_e32 v0, 1.0, v0
	v_rcp_f32_e32 v36, v0
	v_mul_f32_e32 v0, 0xbfb8aa3b, v61
	v_exp_f32_e32 v0, v0
	v_cvt_pk_bf16_f32 v34, v34, v35
	v_add_f32_e32 v0, 1.0, v0
	v_rcp_f32_e32 v37, v0
	v_mul_f32_e32 v0, 0xbfb8aa3b, v62
	v_exp_f32_e32 v0, v0
	v_pk_mul_f32 v[36:37], v[60:61], v[36:37]
	s_nop 0
	v_pk_mul_f32 v[36:37], v[44:45], v[36:37]
	v_add_f32_e32 v0, 1.0, v0
	v_cvt_pk_bf16_f32 v35, v36, v37
	v_rcp_f32_e32 v36, v0
; #define GAS __attribute__((address_space(1)))
; DI unsigned pk2(float lo, float hi) { f32x2 v = {lo, hi}; bf16x2v b = __builtin_convertvector(v, bf16x2v); return __builtin_bit_cast(unsigned, b); }
; DI float siluf_(float x) { return x * __builtin_amdgcn_rcpf(1.f + __builtin_amdgcn_exp2f(-LOG2E * x)); }
;   DI void operator()(int tok0, int feat0, f32x16 (&acc)[2][2], int r, int hh) const {
;     const int u0 = (feat0 >> 6) * 32;
; #pragma unroll
;     for (int mt = 0; mt < 2; ++mt) {
;       bf16_t* dst = act + (size_t)(tok0 + mt * 32 + r) * DFF + u0 + 16 * hh;
; #pragma unroll
;       for (int gp = 0; gp < 2; ++gp) {
;         u32x4 o;
; #pragma unroll
;         for (int q = 0; q < 4; ++q) { const int i = 8 * gp + 2 * q; o[q] = pk2(siluf_(acc[0][mt][i]) * acc[1][mt][i], siluf_(acc[0][mt][i + 1]) * acc[1][mt][i + 1]); }
;         *(u32x4*)(dst + 8 * gp) = o;
;       }
;     }
; DI void grid_barrier(unsigned* ctr, const unsigned target) {
;   asm volatile("s_waitcnt vmcnt(0)" ::: "memory");
;   __syncthreads();
;   if (threadIdx.x == 0) {
;     __builtin_amdgcn_fence(__ATOMIC_RELEASE, "agent");
;     asm volatile("s_waitcnt vmcnt(0)" ::: "memory");
;     __hip_atomic_fetch_add((GAS unsigned*)ctr, 1u, __ATOMIC_RELAXED, __HIP_MEMORY_SCOPE_AGENT);
;     while (__hip_atomic_load((GAS unsigned*)ctr, __ATOMIC_RELAXED, __HIP_MEMORY_SCOPE_AGENT) < target) __builtin_amdgcn_s_sleep(1);
	v_mul_f32_e32 v0, 0xbfb8aa3b, v63
	v_exp_f32_e32 v0, v0
	s_nop 0
	v_add_f32_e32 v0, 1.0, v0
	v_rcp_f32_e32 v37, v0
	v_mul_f32_e32 v0, 0xbfb8aa3b, v64
	v_exp_f32_e32 v0, v0
	v_pk_mul_f32 v[36:37], v[62:63], v[36:37]
	s_nop 0
	v_pk_mul_f32 v[36:37], v[46:47], v[36:37]
	v_add_f32_e32 v0, 1.0, v0
	v_rcp_f32_e32 v38, v0
	v_mul_f32_e32 v0, 0xbfb8aa3b, v65
	v_exp_f32_e32 v0, v0
	v_cvt_pk_bf16_f32 v36, v36, v37
	v_add_f32_e32 v0, 1.0, v0
	v_rcp_f32_e32 v39, v0
	v_mul_f32_e32 v0, 0xbfb8aa3b, v18
	v_exp_f32_e32 v0, v0
	v_pk_mul_f32 v[38:39], v[64:65], v[38:39]
	s_nop 0
	v_pk_mul_f32 v[38:39], v[48:49], v[38:39]
	v_add_f32_e32 v0, 1.0, v0
	v_cvt_pk_bf16_f32 v37, v38, v39
	global_store_dwordx4 v[164:165], v[34:37], off offset:80
	s_nop 1
	v_rcp_f32_e32 v34, v0
	v_mul_f32_e32 v0, 0xbfb8aa3b, v19
	v_exp_f32_e32 v0, v0
	s_nop 0
	v_add_f32_e32 v0, 1.0, v0
	v_rcp_f32_e32 v35, v0
	v_mul_f32_e32 v0, 0xbfb8aa3b, v20
	v_exp_f32_e32 v0, v0
	v_pk_mul_f32 v[18:19], v[18:19], v[34:35]
	s_nop 0
	v_pk_mul_f32 v[2:3], v[2:3], v[18:19]
	v_add_f32_e32 v0, 1.0, v0
	v_rcp_f32_e32 v18, v0
	v_mul_f32_e32 v0, 0xbfb8aa3b, v21
	v_exp_f32_e32 v0, v0
	v_cvt_pk_bf16_f32 v2, v2, v3
	v_add_f32_e32 v0, 1.0, v0
	v_rcp_f32_e32 v19, v0
	v_mul_f32_e32 v0, 0xbfb8aa3b, v22
	v_exp_f32_e32 v0, v0
	v_pk_mul_f32 v[18:19], v[20:21], v[18:19]
	s_nop 0
	v_pk_mul_f32 v[4:5], v[4:5], v[18:19]
	v_add_f32_e32 v0, 1.0, v0
	v_cvt_pk_bf16_f32 v3, v4, v5
	v_rcp_f32_e32 v4, v0
	v_mul_f32_e32 v0, 0xbfb8aa3b, v23
	v_exp_f32_e32 v0, v0
	s_nop 0
	v_add_f32_e32 v0, 1.0, v0
	v_rcp_f32_e32 v5, v0
	v_mul_f32_e32 v0, 0xbfb8aa3b, v24
	v_exp_f32_e32 v0, v0
	v_pk_mul_f32 v[4:5], v[22:23], v[4:5]
	s_nop 0
	v_pk_mul_f32 v[4:5], v[6:7], v[4:5]
	v_add_f32_e32 v0, 1.0, v0
	v_rcp_f32_e32 v6, v0
	v_mul_f32_e32 v0, 0xbfb8aa3b, v25
	v_exp_f32_e32 v0, v0
	v_cvt_pk_bf16_f32 v4, v4, v5
	v_add_f32_e32 v0, 1.0, v0
	v_rcp_f32_e32 v7, v0
	v_mul_f32_e32 v0, 0xbfb8aa3b, v26
	v_exp_f32_e32 v0, v0
	v_pk_mul_f32 v[6:7], v[24:25], v[6:7]
	s_nop 0
	v_pk_mul_f32 v[6:7], v[8:9], v[6:7]
	v_add_f32_e32 v0, 1.0, v0
	v_cvt_pk_bf16_f32 v5, v6, v7
	global_store_dwordx4 v[98:99], v[2:5], off offset:64
	s_nop 1
	v_rcp_f32_e32 v2, v0
	v_mul_f32_e32 v0, 0xbfb8aa3b, v27
	v_exp_f32_e32 v0, v0
	s_nop 0
	v_add_f32_e32 v0, 1.0, v0
	v_rcp_f32_e32 v3, v0
	v_mul_f32_e32 v0, 0xbfb8aa3b, v28
	v_exp_f32_e32 v0, v0
	v_pk_mul_f32 v[2:3], v[26:27], v[2:3]
	s_nop 0
	v_pk_mul_f32 v[2:3], v[10:11], v[2:3]
	v_add_f32_e32 v0, 1.0, v0
	v_rcp_f32_e32 v4, v0
	v_mul_f32_e32 v0, 0xbfb8aa3b, v29
	v_exp_f32_e32 v0, v0
	v_cvt_pk_bf16_f32 v2, v2, v3
	v_add_f32_e32 v0, 1.0, v0
	v_rcp_f32_e32 v5, v0
	v_mul_f32_e32 v0, 0xbfb8aa3b, v30
	v_exp_f32_e32 v0, v0
	v_pk_mul_f32 v[4:5], v[28:29], v[4:5]
	s_nop 0
	v_pk_mul_f32 v[4:5], v[12:13], v[4:5]
	v_add_f32_e32 v0, 1.0, v0
	v_cvt_pk_bf16_f32 v3, v4, v5
	v_rcp_f32_e32 v4, v0
	v_mul_f32_e32 v0, 0xbfb8aa3b, v31
	v_exp_f32_e32 v0, v0
	s_nop 0
	v_add_f32_e32 v0, 1.0, v0
	v_rcp_f32_e32 v5, v0
	v_mul_f32_e32 v0, 0xbfb8aa3b, v32
	v_exp_f32_e32 v0, v0
	v_pk_mul_f32 v[4:5], v[30:31], v[4:5]
	s_nop 0
	v_pk_mul_f32 v[4:5], v[14:15], v[4:5]
	v_add_f32_e32 v0, 1.0, v0
	v_rcp_f32_e32 v6, v0
	v_mul_f32_e32 v0, 0xbfb8aa3b, v33
	v_exp_f32_e32 v0, v0
	v_cvt_pk_bf16_f32 v4, v4, v5
	v_add_f32_e32 v0, 1.0, v0
	v_rcp_f32_e32 v7, v0
	s_nop 0
	v_pk_mul_f32 v[6:7], v[32:33], v[6:7]
	s_nop 0
	v_pk_mul_f32 v[6:7], v[16:17], v[6:7]
	s_nop 0
	v_cvt_pk_bf16_f32 v5, v6, v7
	global_store_dwordx4 v[98:99], v[2:5], off offset:80
	s_and_b64 vcc, exec, s[4:5]
	s_mov_b32 s16, s9
	s_cbranch_vccz .LBB0_736
	s_add_i32 s25, s24, 1
	s_cmp_ge_i32 s25, s79
	s_cbranch_scc1 .LBB0_762
	s_cmp_lg_u32 s24, s78
	s_mov_b64 s[4:5], -1
	v_mov_b32_e32 v206, v198
	v_mov_b32_e32 v207, v199
	s_cbranch_scc0 .LBB0_750
	s_waitcnt vmcnt(0)
	s_barrier
	s_mov_b64 s[4:5], exec
	v_readlane_b32 s2, v254, 26
	v_readlane_b32 s3, v254, 27
	s_and_b64 s[2:3], s[4:5], s[2:3]
	s_mov_b64 exec, s[2:3]
	s_cbranch_execz .LBB0_749
	s_load_dword s2, s[80:81], 0x0
	s_mov_b64 s[8:9], exec
	buffer_wbl2 sc1
	s_waitcnt vmcnt(0) lgkmcnt(0)
	s_waitcnt vmcnt(0)
	v_mbcnt_lo_u32_b32 v0, s8, 0
	s_add_u32 s6, s10, 0x1ee14400
	v_mbcnt_hi_u32_b32 v0, s9, v0
	s_addc_u32 s7, s11, 0
	v_cmp_eq_u32_e32 vcc, 0, v0
	s_and_saveexec_b64 s[10:11], vcc
	s_cbranch_execz .LBB0_746
	s_bcnt1_i32_b64 s3, s[8:9]
	v_mov_b32_e32 v0, s3
	global_atomic_add v1, v0, s[6:7]

.LBB0_769:
	v_add_u32_e32 v0, v209, v210
	ds_read_b128 v[202:205], v0
	ds_read_b128 v[226:229], v0 offset:4608
	v_add_u32_e32 v0, v209, v211
	ds_read_b128 v[166:169], v0 offset:36864
	ds_read_b128 v[184:187], v0 offset:41472
	ds_read_b128 v[188:191], v0 offset:46080
	ds_read_b128 v[194:197], v0 offset:50688
	ds_read_b128 v[230:233], v214 offset:32
	ds_read_b128 v[234:237], v214 offset:4640
.Lkloop_top_5:
	s_add_i32 s18, s5, 2
	s_cmp_lt_u32 s5, 42
	s_cselect_b32 s96, s3, 0x1580
	s_min_u32 s4, s5, 40
	s_lshl_b32 s4, s4, 7
	s_addk_i32 s3, 0x100
	s_cmp_gt_u32 s5, 41
	s_waitcnt lgkmcnt(5)
	v_mfma_f32_32x32x16_bf16 v[114:129], v[166:169], v[202:205], v[114:129]
	v_mfma_f32_32x32x16_bf16 v[66:81], v[166:169], v[226:229], v[66:81]
	s_waitcnt lgkmcnt(4)
	v_mfma_f32_32x32x16_bf16 v[98:113], v[184:187], v[202:205], v[98:113]
	v_mfma_f32_32x32x16_bf16 v[50:65], v[184:187], v[226:229], v[50:65]
	s_waitcnt lgkmcnt(3)
	v_mfma_f32_32x32x16_bf16 v[82:97], v[188:191], v[202:205], v[82:97]
	v_mfma_f32_32x32x16_bf16 v[18:33], v[188:191], v[226:229], v[18:33]
	s_waitcnt lgkmcnt(2)
	v_mfma_f32_32x32x16_bf16 v[34:49], v[194:197], v[202:205], v[34:49]
	ds_read_b128 v[166:169], v215 offset:36896
	ds_read_b128 v[188:191], v215 offset:41504
	v_mfma_f32_32x32x16_bf16 v[2:17], v[194:197], v[226:229], v[2:17]
	v_lshl_add_u64 v[184:185], v[178:179], 0, s[96:97]
	s_waitcnt vmcnt(1)
	ds_write_b128 v216, v[154:157] offset:9216
	v_add_co_u32_e32 v154, vcc, s93, v184
	s_waitcnt vmcnt(0)
	ds_write_b128 v216, v[142:145]
	v_addc_co_u32_e32 v155, vcc, 0, v185, vcc
	global_load_dwordx4 v[142:145], v[184:185], off
	s_nop 0
	global_load_dwordx4 v[154:157], v[154:155], off
	ds_write_b128 v216, v[134:137] offset:18432
	v_lshl_add_u64 v[134:135], v[180:181], 0, s[96:97]
	ds_write_b128 v216, v[146:149] offset:27648
	v_lshl_add_u64 v[146:147], v[182:183], 0, s[96:97]
	global_load_dwordx4 v[134:137], v[134:135], off
	s_nop 0
	global_load_dwordx4 v[146:149], v[146:147], off
	ds_read_b128 v[184:187], v215 offset:46112
	ds_read_b128 v[194:197], v215 offset:50720
	ds_read_b128 v[202:205], v214 offset:64
	ds_read_b128 v[226:229], v214 offset:4672
	s_waitcnt lgkmcnt(9)
	v_mfma_f32_32x32x16_bf16 v[114:129], v[166:169], v[230:233], v[114:129]
	v_mfma_f32_32x32x16_bf16 v[66:81], v[166:169], v[234:237], v[66:81]
	s_waitcnt lgkmcnt(8)
	v_mfma_f32_32x32x16_bf16 v[98:113], v[188:191], v[230:233], v[98:113]
	v_mfma_f32_32x32x16_bf16 v[50:65], v[188:191], v[234:237], v[50:65]
	s_waitcnt lgkmcnt(3)
	v_mfma_f32_32x32x16_bf16 v[82:97], v[184:187], v[230:233], v[82:97]
	v_mfma_f32_32x32x16_bf16 v[18:33], v[184:187], v[234:237], v[18:33]
	ds_read_b128 v[166:169], v215 offset:36928
	ds_read_b128 v[184:187], v215 offset:41536
	s_waitcnt lgkmcnt(4)
	v_mfma_f32_32x32x16_bf16 v[34:49], v[194:197], v[230:233], v[34:49]
	v_mfma_f32_32x32x16_bf16 v[2:17], v[194:197], v[234:237], v[2:17]
	v_lshl_add_u64 v[238:239], v[164:165], 0, s[96:97]
	ds_write_b128 v217, v[150:153] offset:9216
	v_add_co_u32_e32 v150, vcc, s93, v238
	ds_write_b128 v217, v[138:141]
	s_nop 0
	v_addc_co_u32_e32 v151, vcc, 0, v239, vcc
	global_load_dwordx4 v[138:141], v[238:239], off
	s_nop 0
	global_load_dwordx4 v[150:153], v[150:151], off
	ds_read_b128 v[188:191], v215 offset:46144
	ds_read_b128 v[194:197], v215 offset:50752
	ds_read_b128 v[230:233], v214 offset:96
	ds_read_b128 v[234:237], v214 offset:4704
	s_waitcnt lgkmcnt(7)
	v_mfma_f32_32x32x16_bf16 v[114:129], v[166:169], v[202:205], v[114:129]
	v_mfma_f32_32x32x16_bf16 v[66:81], v[166:169], v[226:229], v[66:81]
	s_waitcnt lgkmcnt(6)
	v_mfma_f32_32x32x16_bf16 v[98:113], v[184:187], v[202:205], v[98:113]
	v_mfma_f32_32x32x16_bf16 v[50:65], v[184:187], v[226:229], v[50:65]
	s_waitcnt lgkmcnt(3)
	v_mfma_f32_32x32x16_bf16 v[82:97], v[188:191], v[202:205], v[82:97]
	ds_read_b128 v[166:169], v215 offset:36960
	ds_read_b128 v[184:187], v215 offset:41568
	v_mfma_f32_32x32x16_bf16 v[18:33], v[188:191], v[226:229], v[18:33]
	s_waitcnt lgkmcnt(4)
	v_mfma_f32_32x32x16_bf16 v[34:49], v[194:197], v[202:205], v[34:49]
	v_mfma_f32_32x32x16_bf16 v[2:17], v[194:197], v[226:229], v[2:17]
	ds_write_b128 v217, v[130:133] offset:18432
	v_add_co_u32_e32 v130, vcc, s49, v238
	ds_write_b128 v217, v[158:161] offset:27648
	s_nop 0
	v_addc_co_u32_e32 v131, vcc, 0, v239, vcc
	v_add_co_u32_e32 v158, vcc, s70, v238
	global_load_dwordx4 v[130:133], v[130:131], off
	s_nop 0
	v_addc_co_u32_e32 v159, vcc, 0, v239, vcc
	global_load_dwordx4 v[158:161], v[158:159], off
	ds_read_b128 v[188:191], v215 offset:46176
	ds_read_b128 v[194:197], v215 offset:50784
	s_waitcnt lgkmcnt(5)
	v_mfma_f32_32x32x16_bf16 v[114:129], v[166:169], v[230:233], v[114:129]
	v_mfma_f32_32x32x16_bf16 v[66:81], v[166:169], v[234:237], v[66:81]
	s_waitcnt lgkmcnt(4)
	v_mfma_f32_32x32x16_bf16 v[98:113], v[184:187], v[230:233], v[98:113]
	v_mfma_f32_32x32x16_bf16 v[50:65], v[184:187], v[234:237], v[50:65]
	s_waitcnt lgkmcnt(0)
	s_barrier
	ds_read_b128 v[202:205], v218
	ds_read_b128 v[226:229], v218 offset:4608
	ds_read_b128 v[166:169], v219
	ds_read_b128 v[184:187], v219 offset:4608
	v_mfma_f32_32x32x16_bf16 v[82:97], v[188:191], v[230:233], v[82:97]
	v_mfma_f32_32x32x16_bf16 v[18:33], v[188:191], v[234:237], v[18:33]
	ds_read_b128 v[188:191], v219 offset:9216
	v_mfma_f32_32x32x16_bf16 v[34:49], v[194:197], v[230:233], v[34:49]
	v_mfma_f32_32x32x16_bf16 v[2:17], v[194:197], v[234:237], v[2:17]
	ds_read_b128 v[194:197], v219 offset:13824
	v_add_u32_e32 v0, v212, v208
	ds_read_b128 v[230:233], v0 offset:32
	ds_read_b128 v[234:237], v220 offset:32
	s_waitcnt lgkmcnt(5)
	v_mfma_f32_32x32x16_bf16 v[114:129], v[166:169], v[202:205], v[114:129]
	v_mfma_f32_32x32x16_bf16 v[66:81], v[166:169], v[226:229], v[66:81]
	s_waitcnt lgkmcnt(4)
	v_mfma_f32_32x32x16_bf16 v[98:113], v[184:187], v[202:205], v[98:113]
	v_mfma_f32_32x32x16_bf16 v[50:65], v[184:187], v[226:229], v[50:65]
	s_waitcnt lgkmcnt(3)
	v_mfma_f32_32x32x16_bf16 v[82:97], v[188:191], v[202:205], v[82:97]
	v_add_u32_e32 v225, v213, v208
	v_mfma_f32_32x32x16_bf16 v[18:33], v[188:191], v[226:229], v[18:33]
	s_waitcnt lgkmcnt(2)
	v_mfma_f32_32x32x16_bf16 v[34:49], v[194:197], v[202:205], v[34:49]
	ds_read_b128 v[166:169], v225 offset:32
	ds_read_b128 v[188:191], v221 offset:32
	v_mfma_f32_32x32x16_bf16 v[2:17], v[194:197], v[226:229], v[2:17]
	s_mov_b32 s5, s97
	v_lshl_add_u64 v[184:185], v[178:179], 0, s[4:5]
	s_waitcnt vmcnt(6)
	ds_write_b128 v224, v[154:157] offset:9216
	v_add_co_u32_e32 v154, vcc, s93, v184
	ds_write_b128 v224, v[142:145]
	s_nop 0
	v_addc_co_u32_e32 v155, vcc, 0, v185, vcc
	global_load_dwordx4 v[142:145], v[184:185], off offset:384
	s_nop 0
	global_load_dwordx4 v[154:157], v[154:155], off offset:384
	s_waitcnt vmcnt(7)
	ds_write_b128 v224, v[134:137] offset:18432
	v_add_co_u32_e32 v134, vcc, s49, v184
	s_waitcnt vmcnt(6)
	ds_write_b128 v224, v[146:149] offset:27648
	v_addc_co_u32_e32 v135, vcc, 0, v185, vcc
	v_lshl_add_u64 v[146:147], v[182:183], 0, s[4:5]
	global_load_dwordx4 v[134:137], v[134:135], off offset:384
	s_nop 0
	global_load_dwordx4 v[146:149], v[146:147], off offset:384
	ds_read_b128 v[184:187], v222 offset:32
	ds_read_b128 v[194:197], v223 offset:32
	ds_read_b128 v[202:205], v0 offset:64
	ds_read_b128 v[226:229], v220 offset:64
	s_waitcnt lgkmcnt(9)
	v_mfma_f32_32x32x16_bf16 v[114:129], v[166:169], v[230:233], v[114:129]
	v_mfma_f32_32x32x16_bf16 v[66:81], v[166:169], v[234:237], v[66:81]
	s_waitcnt lgkmcnt(8)
	v_mfma_f32_32x32x16_bf16 v[98:113], v[188:191], v[230:233], v[98:113]
	v_mfma_f32_32x32x16_bf16 v[50:65], v[188:191], v[234:237], v[50:65]
	s_waitcnt lgkmcnt(3)
	v_mfma_f32_32x32x16_bf16 v[82:97], v[184:187], v[230:233], v[82:97]
	v_mfma_f32_32x32x16_bf16 v[18:33], v[184:187], v[234:237], v[18:33]
	ds_read_b128 v[166:169], v225 offset:64
	ds_read_b128 v[184:187], v221 offset:64
	s_waitcnt lgkmcnt(4)
	v_mfma_f32_32x32x16_bf16 v[34:49], v[194:197], v[230:233], v[34:49]
	v_mfma_f32_32x32x16_bf16 v[2:17], v[194:197], v[234:237], v[2:17]
	v_lshl_add_u64 v[238:239], v[164:165], 0, s[4:5]
	s_waitcnt vmcnt(6)
	ds_write_b128 v224, v[150:153] offset:46080
	v_add_co_u32_e32 v150, vcc, s93, v238
	ds_write_b128 v224, v[138:141] offset:36864
	s_nop 0
	v_addc_co_u32_e32 v151, vcc, 0, v239, vcc
	global_load_dwordx4 v[138:141], v[238:239], off offset:384
	s_nop 0
	global_load_dwordx4 v[150:153], v[150:151], off offset:384
	ds_read_b128 v[188:191], v222 offset:64
	ds_read_b128 v[194:197], v223 offset:64
	ds_read_b128 v[230:233], v0 offset:96
	ds_read_b128 v[234:237], v220 offset:96
	s_waitcnt lgkmcnt(7)
	v_mfma_f32_32x32x16_bf16 v[114:129], v[166:169], v[202:205], v[114:129]
	v_mfma_f32_32x32x16_bf16 v[66:81], v[166:169], v[226:229], v[66:81]
	s_waitcnt lgkmcnt(6)
	v_mfma_f32_32x32x16_bf16 v[98:113], v[184:187], v[202:205], v[98:113]
	v_mfma_f32_32x32x16_bf16 v[50:65], v[184:187], v[226:229], v[50:65]
	s_waitcnt lgkmcnt(3)
	v_mfma_f32_32x32x16_bf16 v[82:97], v[188:191], v[202:205], v[82:97]
	ds_read_b128 v[166:169], v225 offset:96
	ds_read_b128 v[184:187], v221 offset:96
	v_mfma_f32_32x32x16_bf16 v[18:33], v[188:191], v[226:229], v[18:33]
	s_waitcnt lgkmcnt(4)
	v_mfma_f32_32x32x16_bf16 v[34:49], v[194:197], v[202:205], v[34:49]
	v_mfma_f32_32x32x16_bf16 v[2:17], v[194:197], v[226:229], v[2:17]
	s_waitcnt vmcnt(7)
	ds_write_b128 v224, v[130:133] offset:55296
	v_add_co_u32_e32 v130, vcc, s49, v238
	s_waitcnt vmcnt(6)
	ds_write_b128 v224, v[158:161] offset:64512
	v_addc_co_u32_e32 v131, vcc, 0, v239, vcc
	v_add_co_u32_e32 v158, vcc, s70, v238
	global_load_dwordx4 v[130:133], v[130:131], off offset:384
	s_nop 0
	v_addc_co_u32_e32 v159, vcc, 0, v239, vcc
	global_load_dwordx4 v[158:161], v[158:159], off offset:384
	ds_read_b128 v[188:191], v222 offset:96
	ds_read_b128 v[194:197], v223 offset:96
	s_waitcnt lgkmcnt(5)
	v_mfma_f32_32x32x16_bf16 v[114:129], v[166:169], v[230:233], v[114:129]
	v_mfma_f32_32x32x16_bf16 v[66:81], v[166:169], v[234:237], v[66:81]
	s_waitcnt lgkmcnt(4)
	v_mfma_f32_32x32x16_bf16 v[98:113], v[184:187], v[230:233], v[98:113]
	v_mfma_f32_32x32x16_bf16 v[50:65], v[184:187], v[234:237], v[50:65]
	s_waitcnt lgkmcnt(0)
	s_barrier
	v_add_u32_e32 v0, v209, v210
	ds_read_b128 v[202:205], v0
	ds_read_b128 v[226:229], v0 offset:4608
	v_add_u32_e32 v0, v209, v211
	ds_read_b128 v[166:169], v0 offset:36864
	ds_read_b128 v[184:187], v0 offset:41472
	v_mfma_f32_32x32x16_bf16 v[82:97], v[188:191], v[230:233], v[82:97]
	v_mfma_f32_32x32x16_bf16 v[18:33], v[188:191], v[234:237], v[18:33]
	ds_read_b128 v[188:191], v0 offset:46080
	v_mfma_f32_32x32x16_bf16 v[34:49], v[194:197], v[230:233], v[34:49]
	v_mfma_f32_32x32x16_bf16 v[2:17], v[194:197], v[234:237], v[2:17]
	ds_read_b128 v[194:197], v0 offset:50688
	ds_read_b128 v[230:233], v214 offset:32
	ds_read_b128 v[234:237], v214 offset:4640
	s_mov_b32 s5, s18
	s_cbranch_scc0 .Lkloop_top_5
; #define RL_LOAD(XV, G) { constexpr int mt__ = (G) >> 2, half__ = ((G) >> 1) & 1, nt__ = (G) & 1; \
;     _Pragma("unroll") for (int gq = 0; gq < 4; ++gq) XV[gq] = *(const f32x4*)(xin + rbase + (size_t)mt__ * 32 * 1024 + half__ * 64 + nt__ * 32 + 4 * gq); }
; #define RL_FOLD(XV, G, SM, SQ) { constexpr int mt__ = (G) >> 2, half__ = ((G) >> 1) & 1, nt__ = (G) & 1; \
;     _Pragma("unroll") for (int gq = 0; gq < 4; ++gq) _Pragma("unroll") for (int jj = 0; jj < 4; ++jj) { \
;       const float y = ALPHA * XV[gq][jj] + acc[half__][nt__][mt__][4 * gq + jj]; acc[half__][nt__][mt__][4 * gq + jj] = y; SM += y; SQ += y * y; } }
; #define SB __builtin_amdgcn_sched_barrier(0)
;   DI void full(const int mt_, const int nt_, f32x16 (&acc)[2][2][2], const int tw, const int fw, const int r, const int hh, char* lds, const int tid) const {
;     ...
;     float sm0 = 0.f, sq0 = 0.f, sm1 = 0.f, sq1 = 0.f;
;     RL_LOAD(xa, 0); RL_LOAD(xc, 1); RL_LOAD(xe, 2); SB;
;     RL_FOLD(xa, 0, sm0, sq0); SB; RL_LOAD(xa, 3); SB;
;     RL_FOLD(xc, 1, sm0, sq0); SB; RL_LOAD(xc, 4); SB;
;     RL_FOLD(xe, 2, sm0, sq0); SB; RL_LOAD(xe, 5); SB;
;     RL_FOLD(xa, 3, sm0, sq0); SB; RL_LOAD(xa, 6); SB;
;     RL_FOLD(xc, 4, sm1, sq1); SB; RL_LOAD(xc, 7); SB;
;     RL_FOLD(xe, 5, sm1, sq1); SB;
;     RL_FOLD(xa, 6, sm1, sq1); SB;
;     RL_FOLD(xc, 7, sm1, sq1);
	s_waitcnt lgkmcnt(0)
	v_mov_b32_e32 v186, v192
	s_waitcnt vmcnt(1)
	v_ashrrev_i32_e32 v130, 1, v186
	v_and_b32_e32 v225, 0xdf, v186
	v_and_b32_e32 v184, 0xffffff80, v130
	v_or_b32_e32 v0, s2, v225
	v_ashrrev_i32_e32 v185, 31, v184
	v_bfe_u32 v226, v186, 5, 1
	v_lshl_add_u64 v[130:131], v[184:185], 2, s[16:17]
	v_lshlrev_b64 v[132:133], 12, v[0:1]
	v_lshl_add_u64 v[130:131], v[130:131], 0, v[132:133]
	v_lshlrev_b32_e32 v132, 6, v226
	v_mov_b32_e32 v133, v1
	v_lshl_add_u64 v[188:189], v[130:131], 0, v[132:133]
	global_load_dwordx4 v[130:133], v[188:189], off offset:48
	global_load_dwordx4 v[134:137], v[188:189], off offset:32
	global_load_dwordx4 v[138:141], v[188:189], off offset:16
	global_load_dwordx4 v[142:145], v[188:189], off
	global_load_dwordx4 v[194:197], v[188:189], off offset:176
	global_load_dwordx4 v[202:205], v[188:189], off offset:160
	global_load_dwordx4 v[228:231], v[188:189], off offset:144
	global_load_dwordx4 v[146:149], v[188:189], off offset:128
	global_load_dwordx4 v[232:235], v[188:189], off offset:304
	global_load_dwordx4 v[236:239], v[188:189], off offset:288
	global_load_dwordx4 v[240:243], v[188:189], off offset:272
	global_load_dwordx4 v[244:247], v[188:189], off offset:256
	s_waitcnt vmcnt(8)
	v_pk_fma_f32 v[180:181], v[142:143], s[0:1], v[114:115] op_sel_hi:[1,0,1]
	v_pk_fma_f32 v[182:183], v[144:145], s[0:1], v[116:117] op_sel_hi:[1,0,1]
	v_add_f32_e32 v114, 0, v180
	v_add_f32_e32 v142, v181, v114
	v_mul_f32_e32 v114, v181, v181
	v_pk_fma_f32 v[114:115], v[180:181], v[180:181], v[114:115] op_sel_hi:[1,1,0]
	v_add_f32_e32 v116, v182, v142
	v_pk_fma_f32 v[114:115], v[182:183], v[182:183], v[114:115]
	v_add_f32_e32 v117, v183, v116
	v_mul_f32_e32 v116, v183, v183
	v_pk_fma_f32 v[160:161], v[138:139], s[0:1], v[118:119] op_sel_hi:[1,0,1]
	v_pk_add_f32 v[114:115], v[116:117], v[114:115] op_sel_hi:[0,1]
	v_add_f32_e32 v116, v160, v117
	v_pk_fma_f32 v[114:115], v[160:161], v[160:161], v[114:115]
	v_add_f32_e32 v117, v161, v116
	v_mul_f32_e32 v116, v161, v161
	v_pk_fma_f32 v[178:179], v[140:141], s[0:1], v[120:121] op_sel_hi:[1,0,1]
	v_pk_add_f32 v[114:115], v[116:117], v[114:115] op_sel_hi:[0,1]
	v_add_f32_e32 v116, v178, v117
	v_pk_fma_f32 v[114:115], v[178:179], v[178:179], v[114:115]
	v_add_f32_e32 v117, v179, v116
	v_mul_f32_e32 v116, v179, v179
	v_pk_fma_f32 v[156:157], v[134:135], s[0:1], v[122:123] op_sel_hi:[1,0,1]
	v_pk_add_f32 v[114:115], v[116:117], v[114:115] op_sel_hi:[0,1]
	v_add_f32_e32 v116, v156, v117
	v_pk_fma_f32 v[114:115], v[156:157], v[156:157], v[114:115]
	v_add_f32_e32 v117, v157, v116
	v_mul_f32_e32 v116, v157, v157
	v_pk_fma_f32 v[158:159], v[136:137], s[0:1], v[124:125] op_sel_hi:[1,0,1]
	v_pk_add_f32 v[114:115], v[116:117], v[114:115] op_sel_hi:[0,1]
	v_add_f32_e32 v116, v158, v117
	v_pk_fma_f32 v[114:115], v[158:159], v[158:159], v[114:115]
	v_add_f32_e32 v120, v159, v116
	v_mul_f32_e32 v116, v159, v159
	v_pk_add_f32 v[114:115], v[116:117], v[114:115] op_sel_hi:[0,1]
	v_pk_fma_f32 v[154:155], v[130:131], s[0:1], v[126:127] op_sel_hi:[1,0,1]
	v_pk_fma_f32 v[152:153], v[132:133], s[0:1], v[128:129] op_sel_hi:[1,0,1]
	v_pk_fma_f32 v[114:115], v[154:155], v[154:155], v[114:115]
	v_mul_f32_e32 v116, v155, v155
	v_pk_add_f32 v[114:115], v[116:117], v[114:115] op_sel_hi:[0,1]
	v_pk_fma_f32 v[114:115], v[152:153], v[152:153], v[114:115]
	v_mul_f32_e32 v116, v153, v153
	v_pk_add_f32 v[118:119], v[116:117], v[114:115] op_sel_hi:[0,1]
	global_load_dwordx4 v[114:117], v[188:189], off offset:432
	global_load_dwordx4 v[248:251], v[188:189], off offset:416
	global_load_dwordx4 v[166:169], v[188:189], off offset:400
	global_load_dwordx4 v[122:125], v[188:189], off offset:384
	v_add_f32_e32 v120, v154, v120
	v_add_f32_e32 v120, v155, v120
	v_add_f32_e32 v120, v152, v120
	v_add_f32_e32 v120, v153, v120
	s_waitcnt vmcnt(8)
	v_pk_fma_f32 v[146:147], v[146:147], s[0:1], v[98:99] op_sel_hi:[1,0,1]
	v_pk_fma_f32 v[150:151], v[148:149], s[0:1], v[100:101] op_sel_hi:[1,0,1]
	v_add_f32_e32 v120, v146, v120
	v_pk_fma_f32 v[98:99], v[146:147], v[146:147], v[118:119]
	v_add_f32_e32 v119, v147, v120
	v_mul_f32_e32 v118, v147, v147
	v_pk_add_f32 v[98:99], v[118:119], v[98:99] op_sel_hi:[0,1]
	v_add_f32_e32 v100, v150, v119
	v_pk_fma_f32 v[98:99], v[150:151], v[150:151], v[98:99]
	v_add_f32_e32 v101, v151, v100
	v_mul_f32_e32 v100, v151, v151
	v_pk_fma_f32 v[140:141], v[228:229], s[0:1], v[102:103] op_sel_hi:[1,0,1]
	v_pk_add_f32 v[98:99], v[100:101], v[98:99] op_sel_hi:[0,1]
	v_add_f32_e32 v100, v140, v101
	v_pk_fma_f32 v[98:99], v[140:141], v[140:141], v[98:99]
	v_add_f32_e32 v101, v141, v100
	v_mul_f32_e32 v100, v141, v141
	v_pk_fma_f32 v[148:149], v[230:231], s[0:1], v[104:105] op_sel_hi:[1,0,1]
	v_pk_add_f32 v[98:99], v[100:101], v[98:99] op_sel_hi:[0,1]
	v_add_f32_e32 v100, v148, v101
	v_pk_fma_f32 v[98:99], v[148:149], v[148:149], v[98:99]
	v_add_f32_e32 v101, v149, v100
	v_mul_f32_e32 v100, v149, v149
	v_pk_fma_f32 v[132:133], v[202:203], s[0:1], v[106:107] op_sel_hi:[1,0,1]
	v_pk_add_f32 v[98:99], v[100:101], v[98:99] op_sel_hi:[0,1]
	v_add_f32_e32 v100, v132, v101
	v_pk_fma_f32 v[98:99], v[132:133], v[132:133], v[98:99]
	v_add_f32_e32 v101, v133, v100
	v_mul_f32_e32 v100, v133, v133
	v_pk_fma_f32 v[142:143], v[204:205], s[0:1], v[108:109] op_sel_hi:[1,0,1]
	v_pk_add_f32 v[98:99], v[100:101], v[98:99] op_sel_hi:[0,1]
	v_add_f32_e32 v100, v142, v101
	v_pk_fma_f32 v[98:99], v[142:143], v[142:143], v[98:99]
	v_add_f32_e32 v106, v143, v100
	v_mul_f32_e32 v100, v143, v143
	v_pk_add_f32 v[102:103], v[100:101], v[98:99] op_sel_hi:[0,1]
	v_pk_fma_f32 v[126:127], v[194:195], s[0:1], v[110:111] op_sel_hi:[1,0,1]
	v_pk_fma_f32 v[136:137], v[196:197], s[0:1], v[112:113] op_sel_hi:[1,0,1]
	v_add_co_u32_e32 v190, vcc, s91, v188
	s_mov_b64 s[4:5], 0x20000
	s_nop 0
	v_addc_co_u32_e32 v191, vcc, 0, v189, vcc
	v_lshl_add_u64 v[104:105], v[188:189], 0, s[4:5]
	global_load_dwordx4 v[194:197], v[190:191], off
	global_load_dwordx4 v[98:101], v[104:105], off offset:48
	global_load_dwordx4 v[202:205], v[104:105], off offset:32
	global_load_dwordx4 v[228:231], v[104:105], off offset:16
	v_add_f32_e32 v104, v126, v106
	v_pk_fma_f32 v[102:103], v[126:127], v[126:127], v[102:103]
	v_add_f32_e32 v105, v127, v104
	v_mul_f32_e32 v104, v127, v127
	v_pk_add_f32 v[102:103], v[104:105], v[102:103] op_sel_hi:[0,1]
	v_add_f32_e32 v104, v136, v105
	v_pk_fma_f32 v[102:103], v[136:137], v[136:137], v[102:103]
	v_add_f32_e32 v105, v137, v104
	v_mul_f32_e32 v104, v137, v137
	v_pk_add_f32 v[102:103], v[104:105], v[102:103] op_sel_hi:[0,1]
	s_waitcnt vmcnt(8)
; #define RL_LOAD(XV, G) { constexpr int mt__ = (G) >> 2, half__ = ((G) >> 1) & 1, nt__ = (G) & 1; \
;     _Pragma("unroll") for (int gq = 0; gq < 4; ++gq) XV[gq] = *(const f32x4*)(xin + rbase + (size_t)mt__ * 32 * 1024 + half__ * 64 + nt__ * 32 + 4 * gq); }
; #define RL_FOLD(XV, G, SM, SQ) { constexpr int mt__ = (G) >> 2, half__ = ((G) >> 1) & 1, nt__ = (G) & 1; \
;     _Pragma("unroll") for (int gq = 0; gq < 4; ++gq) _Pragma("unroll") for (int jj = 0; jj < 4; ++jj) { \
;       const float y = ALPHA * XV[gq][jj] + acc[half__][nt__][mt__][4 * gq + jj]; acc[half__][nt__][mt__][4 * gq + jj] = y; SM += y; SQ += y * y; } }
; #define SB __builtin_amdgcn_sched_barrier(0)
;   DI void full(const int mt_, const int nt_, f32x16 (&acc)[2][2][2], const int tw, const int fw, const int r, const int hh, char* lds, const int tid) const {
;     ...
;     float sm0 = 0.f, sq0 = 0.f, sm1 = 0.f, sq1 = 0.f;
;     RL_LOAD(xa, 0); RL_LOAD(xc, 1); RL_LOAD(xe, 2); SB;
;     RL_FOLD(xa, 0, sm0, sq0); SB; RL_LOAD(xa, 3); SB;
;     RL_FOLD(xc, 1, sm0, sq0); SB; RL_LOAD(xc, 4); SB;
;     RL_FOLD(xe, 2, sm0, sq0); SB; RL_LOAD(xe, 5); SB;
;     RL_FOLD(xa, 3, sm0, sq0); SB; RL_LOAD(xa, 6); SB;
;     RL_FOLD(xc, 4, sm1, sq1); SB; RL_LOAD(xc, 7); SB;
;     RL_FOLD(xe, 5, sm1, sq1); SB;
;     RL_FOLD(xa, 6, sm1, sq1); SB;
;     RL_FOLD(xc, 7, sm1, sq1);
	v_pk_fma_f32 v[134:135], v[244:245], s[0:1], v[82:83] op_sel_hi:[1,0,1]
	v_pk_fma_f32 v[144:145], v[246:247], s[0:1], v[84:85] op_sel_hi:[1,0,1]
	v_add_f32_e32 v104, v134, v105
	v_pk_fma_f32 v[82:83], v[134:135], v[134:135], v[102:103]
	v_add_f32_e32 v103, v135, v104
	v_mul_f32_e32 v102, v135, v135
	v_pk_add_f32 v[82:83], v[102:103], v[82:83] op_sel_hi:[0,1]
	v_add_f32_e32 v84, v144, v103
	v_pk_fma_f32 v[82:83], v[144:145], v[144:145], v[82:83]
	v_add_f32_e32 v85, v145, v84
	v_mul_f32_e32 v84, v145, v145
	v_pk_fma_f32 v[128:129], v[240:241], s[0:1], v[86:87] op_sel_hi:[1,0,1]
	v_pk_add_f32 v[82:83], v[84:85], v[82:83] op_sel_hi:[0,1]
	v_add_f32_e32 v84, v128, v85
	v_pk_fma_f32 v[82:83], v[128:129], v[128:129], v[82:83]
	v_add_f32_e32 v85, v129, v84
	v_mul_f32_e32 v84, v129, v129
	v_pk_fma_f32 v[138:139], v[242:243], s[0:1], v[88:89] op_sel_hi:[1,0,1]
	v_pk_add_f32 v[82:83], v[84:85], v[82:83] op_sel_hi:[0,1]
	v_add_f32_e32 v84, v138, v85
	v_pk_fma_f32 v[82:83], v[138:139], v[138:139], v[82:83]
	v_add_f32_e32 v85, v139, v84
	v_mul_f32_e32 v84, v139, v139
	v_pk_fma_f32 v[118:119], v[236:237], s[0:1], v[90:91] op_sel_hi:[1,0,1]
	v_pk_add_f32 v[82:83], v[84:85], v[82:83] op_sel_hi:[0,1]
	v_add_f32_e32 v84, v118, v85
	v_pk_fma_f32 v[82:83], v[118:119], v[118:119], v[82:83]
	v_add_f32_e32 v85, v119, v84
	v_mul_f32_e32 v84, v119, v119
	v_pk_fma_f32 v[130:131], v[238:239], s[0:1], v[92:93] op_sel_hi:[1,0,1]
	v_pk_add_f32 v[82:83], v[84:85], v[82:83] op_sel_hi:[0,1]
	v_add_f32_e32 v84, v130, v85
	v_pk_fma_f32 v[82:83], v[130:131], v[130:131], v[82:83]
	v_add_f32_e32 v90, v131, v84
	v_mul_f32_e32 v84, v131, v131
	v_pk_add_f32 v[86:87], v[84:85], v[82:83] op_sel_hi:[0,1]
	v_pk_fma_f32 v[108:109], v[232:233], s[0:1], v[94:95] op_sel_hi:[1,0,1]
	v_pk_fma_f32 v[120:121], v[234:235], s[0:1], v[96:97] op_sel_hi:[1,0,1]
	s_mov_b64 s[4:5], 0x20080
	v_lshl_add_u64 v[88:89], v[188:189], 0, s[4:5]
	global_load_dwordx4 v[82:85], v[88:89], off offset:48
	global_load_dwordx4 v[232:235], v[88:89], off offset:32
	global_load_dwordx4 v[236:239], v[190:191], off offset:128
	global_load_dwordx4 v[240:243], v[88:89], off offset:16
	v_add_f32_e32 v88, v108, v90
	v_pk_fma_f32 v[86:87], v[108:109], v[108:109], v[86:87]
	v_add_f32_e32 v89, v109, v88
	v_mul_f32_e32 v88, v109, v109
	v_pk_add_f32 v[86:87], v[88:89], v[86:87] op_sel_hi:[0,1]
	v_add_f32_e32 v88, v120, v89
	v_pk_fma_f32 v[86:87], v[120:121], v[120:121], v[86:87]
	v_add_f32_e32 v89, v121, v88
	v_mul_f32_e32 v88, v121, v121
	v_pk_add_f32 v[86:87], v[88:89], v[86:87] op_sel_hi:[0,1]
	s_waitcnt vmcnt(8)
	v_pk_fma_f32 v[106:107], v[122:123], s[0:1], v[34:35] op_sel_hi:[1,0,1]
	v_pk_fma_f32 v[124:125], v[124:125], s[0:1], v[36:37] op_sel_hi:[1,0,1]
	v_add_f32_e32 v88, v106, v89
	v_pk_fma_f32 v[34:35], v[106:107], v[106:107], v[86:87]
	v_add_f32_e32 v87, v107, v88
	v_mul_f32_e32 v86, v107, v107
	v_add_f32_e32 v36, v124, v87
	v_pk_add_f32 v[34:35], v[86:87], v[34:35] op_sel_hi:[0,1]
	v_add_f32_e32 v36, v125, v36
	v_pk_fma_f32 v[104:105], v[166:167], s[0:1], v[38:39] op_sel_hi:[1,0,1]
	v_pk_fma_f32 v[34:35], v[124:125], v[124:125], v[34:35]
	v_add_f32_e32 v39, v104, v36
	v_mul_f32_e32 v38, v125, v125
	v_mov_b32_e32 v36, v104
	v_mov_b32_e32 v37, v125
	v_pk_add_f32 v[34:35], v[38:39], v[34:35] op_sel_hi:[0,1]
	v_pk_fma_f32 v[34:35], v[36:37], v[36:37], v[34:35]
	v_add_f32_e32 v36, v105, v39
	v_pk_fma_f32 v[122:123], v[168:169], s[0:1], v[40:41] op_sel_hi:[1,0,1]
	v_mul_f32_e32 v38, v105, v105
	v_add_f32_e32 v39, v122, v36
	v_mov_b32_e32 v36, v122
	v_mov_b32_e32 v37, v105
	v_pk_add_f32 v[34:35], v[38:39], v[34:35] op_sel_hi:[0,1]
	v_pk_fma_f32 v[34:35], v[36:37], v[36:37], v[34:35]
	v_add_f32_e32 v36, v123, v39
	v_pk_fma_f32 v[96:97], v[248:249], s[0:1], v[42:43] op_sel_hi:[1,0,1]
	v_mul_f32_e32 v38, v123, v123
	v_add_f32_e32 v39, v96, v36
	v_mov_b32_e32 v36, v96
	v_mov_b32_e32 v37, v123
	v_pk_add_f32 v[34:35], v[38:39], v[34:35] op_sel_hi:[0,1]
	v_pk_fma_f32 v[34:35], v[36:37], v[36:37], v[34:35]
	v_add_f32_e32 v36, v97, v39
	v_pk_fma_f32 v[110:111], v[250:251], s[0:1], v[44:45] op_sel_hi:[1,0,1]
	v_mul_f32_e32 v38, v97, v97
	v_add_f32_e32 v39, v110, v36
	v_mov_b32_e32 v36, v110
	v_mov_b32_e32 v37, v97
	v_pk_add_f32 v[34:35], v[38:39], v[34:35] op_sel_hi:[0,1]
	v_pk_fma_f32 v[102:103], v[114:115], s[0:1], v[46:47] op_sel_hi:[1,0,1]
	v_pk_fma_f32 v[112:113], v[116:117], s[0:1], v[48:49] op_sel_hi:[1,0,1]
	v_pk_fma_f32 v[34:35], v[36:37], v[36:37], v[34:35]
	v_add_f32_e32 v86, v111, v39
	v_mul_f32_e32 v38, v111, v111
	v_mov_b32_e32 v42, v112
	v_mov_b32_e32 v43, v103
	v_mov_b32_e32 v36, v102
	v_mov_b32_e32 v37, v111
	v_pk_add_f32 v[34:35], v[38:39], v[34:35] op_sel_hi:[0,1]
	v_pk_mul_f32 v[114:115], v[112:113], v[112:113]
	s_mov_b64 s[4:5], 0x20100
	v_lshl_add_u64 v[44:45], v[188:189], 0, s[4:5]
	global_load_dwordx4 v[166:169], v[44:45], off offset:48
	global_load_dwordx4 v[244:247], v[44:45], off offset:32
	global_load_dwordx4 v[38:41], v[190:191], off offset:256
	global_load_dwordx4 v[248:251], v[44:45], off offset:16
	v_add_f32_e32 v44, v102, v86
	v_add_f32_e32 v44, v103, v44
	v_add_f32_e32 v114, v112, v44
	s_waitcnt vmcnt(11)
	v_pk_fma_f32 v[92:93], v[194:195], s[0:1], v[66:67] op_sel_hi:[1,0,1]
	v_pk_fma_f32 v[94:95], v[196:197], s[0:1], v[68:69] op_sel_hi:[1,0,1]
	v_add_f32_e32 v44, 0, v92
	v_add_f32_e32 v46, v93, v44
	v_mul_f32_e32 v44, v93, v93
	v_pk_fma_f32 v[44:45], v[92:93], v[92:93], v[44:45] op_sel_hi:[1,1,0]
	v_add_f32_e32 v46, v94, v46
	v_pk_fma_f32 v[44:45], v[94:95], v[94:95], v[44:45]
	v_add_f32_e32 v47, v95, v46
	v_mul_f32_e32 v46, v95, v95
	s_waitcnt vmcnt(8)
; #define RL_LOAD(XV, G) { constexpr int mt__ = (G) >> 2, half__ = ((G) >> 1) & 1, nt__ = (G) & 1; \
;     _Pragma("unroll") for (int gq = 0; gq < 4; ++gq) XV[gq] = *(const f32x4*)(xin + rbase + (size_t)mt__ * 32 * 1024 + half__ * 64 + nt__ * 32 + 4 * gq); }
; #define RL_FOLD(XV, G, SM, SQ) { constexpr int mt__ = (G) >> 2, half__ = ((G) >> 1) & 1, nt__ = (G) & 1; \
;     _Pragma("unroll") for (int gq = 0; gq < 4; ++gq) _Pragma("unroll") for (int jj = 0; jj < 4; ++jj) { \
;       const float y = ALPHA * XV[gq][jj] + acc[half__][nt__][mt__][4 * gq + jj]; acc[half__][nt__][mt__][4 * gq + jj] = y; SM += y; SQ += y * y; } }
; #define SB __builtin_amdgcn_sched_barrier(0)
;   DI void full(const int mt_, const int nt_, f32x16 (&acc)[2][2][2], const int tw, const int fw, const int r, const int hh, char* lds, const int tid) const {
;     ...
;     float sm0 = 0.f, sq0 = 0.f, sm1 = 0.f, sq1 = 0.f;
;     RL_LOAD(xa, 0); RL_LOAD(xc, 1); RL_LOAD(xe, 2); SB;
;     RL_FOLD(xa, 0, sm0, sq0); SB; RL_LOAD(xa, 3); SB;
;     RL_FOLD(xc, 1, sm0, sq0); SB; RL_LOAD(xc, 4); SB;
;     RL_FOLD(xe, 2, sm0, sq0); SB; RL_LOAD(xe, 5); SB;
;     RL_FOLD(xa, 3, sm0, sq0); SB; RL_LOAD(xa, 6); SB;
;     RL_FOLD(xc, 4, sm1, sq1); SB; RL_LOAD(xc, 7); SB;
;     RL_FOLD(xe, 5, sm1, sq1); SB;
;     RL_FOLD(xa, 6, sm1, sq1); SB;
;     RL_FOLD(xc, 7, sm1, sq1);
	v_pk_fma_f32 v[88:89], v[228:229], s[0:1], v[70:71] op_sel_hi:[1,0,1]
	v_pk_add_f32 v[44:45], v[46:47], v[44:45] op_sel_hi:[0,1]
	v_add_f32_e32 v46, v88, v47
	v_pk_fma_f32 v[44:45], v[88:89], v[88:89], v[44:45]
	v_add_f32_e32 v47, v89, v46
	v_mul_f32_e32 v46, v89, v89
	v_pk_fma_f32 v[90:91], v[230:231], s[0:1], v[72:73] op_sel_hi:[1,0,1]
	v_pk_add_f32 v[44:45], v[46:47], v[44:45] op_sel_hi:[0,1]
	v_add_f32_e32 v46, v90, v47
	v_pk_fma_f32 v[44:45], v[90:91], v[90:91], v[44:45]
	v_add_f32_e32 v47, v91, v46
	v_mul_f32_e32 v46, v91, v91
	v_pk_fma_f32 v[86:87], v[202:203], s[0:1], v[74:75] op_sel_hi:[1,0,1]
	v_pk_add_f32 v[44:45], v[46:47], v[44:45] op_sel_hi:[0,1]
	v_add_f32_e32 v46, v86, v47
	v_pk_fma_f32 v[44:45], v[86:87], v[86:87], v[44:45]
	v_add_f32_e32 v47, v87, v46
	v_mul_f32_e32 v46, v87, v87
	v_pk_fma_f32 v[76:77], v[204:205], s[0:1], v[76:77] op_sel_hi:[1,0,1]
	v_pk_add_f32 v[44:45], v[46:47], v[44:45] op_sel_hi:[0,1]
	v_add_f32_e32 v46, v76, v47
	v_pk_fma_f32 v[44:45], v[76:77], v[76:77], v[44:45]
	v_add_f32_e32 v47, v77, v46
	v_mul_f32_e32 v46, v77, v77
	v_pk_fma_f32 v[34:35], v[36:37], v[36:37], v[34:35]
	v_mul_f32_e32 v36, v103, v103
	v_pk_add_f32 v[44:45], v[46:47], v[44:45] op_sel_hi:[0,1]
	v_pk_fma_f32 v[74:75], v[98:99], s[0:1], v[78:79] op_sel_hi:[1,0,1]
	v_pk_fma_f32 v[72:73], v[100:101], s[0:1], v[80:81] op_sel_hi:[1,0,1]
	v_pk_add_f32 v[34:35], v[36:37], v[34:35] op_sel_hi:[0,1]
	v_pk_fma_f32 v[78:79], v[42:43], v[42:43], v[34:35]
	s_mov_b64 s[4:5], 0x20180
	v_lshl_add_u64 v[42:43], v[188:189], 0, s[4:5]
	global_load_dwordx4 v[34:37], v[42:43], off offset:48
	global_load_dwordx4 v[98:101], v[42:43], off offset:32
	s_nop 0
	global_load_dwordx4 v[188:191], v[190:191], off offset:384
	s_nop 0
	global_load_dwordx4 v[194:197], v[42:43], off offset:16
	v_add_f32_e32 v46, v74, v47
	v_pk_fma_f32 v[42:43], v[74:75], v[74:75], v[44:45]
	v_add_f32_e32 v45, v75, v46
	v_mul_f32_e32 v44, v75, v75
	v_pk_add_f32 v[42:43], v[44:45], v[42:43] op_sel_hi:[0,1]
	v_add_f32_e32 v44, v72, v45
	v_pk_fma_f32 v[42:43], v[72:73], v[72:73], v[42:43]
	v_add_f32_e32 v45, v73, v44
	v_mul_f32_e32 v44, v73, v73
	v_pk_add_f32 v[42:43], v[44:45], v[42:43] op_sel_hi:[0,1]
	s_waitcnt vmcnt(9)
	v_pk_fma_f32 v[66:67], v[236:237], s[0:1], v[50:51] op_sel_hi:[1,0,1]
	v_pk_fma_f32 v[70:71], v[238:239], s[0:1], v[52:53] op_sel_hi:[1,0,1]
	v_add_f32_e32 v44, v66, v45
	v_pk_fma_f32 v[42:43], v[66:67], v[66:67], v[42:43]
	v_add_f32_e32 v45, v67, v44
	v_mul_f32_e32 v44, v67, v67
	v_pk_add_f32 v[42:43], v[44:45], v[42:43] op_sel_hi:[0,1]
	v_add_f32_e32 v44, v70, v45
	v_pk_fma_f32 v[42:43], v[70:71], v[70:71], v[42:43]
	v_add_f32_e32 v45, v71, v44
	v_mul_f32_e32 v44, v71, v71
	s_waitcnt vmcnt(8)
	v_pk_fma_f32 v[54:55], v[240:241], s[0:1], v[54:55] op_sel_hi:[1,0,1]
	v_pk_add_f32 v[42:43], v[44:45], v[42:43] op_sel_hi:[0,1]
	v_add_f32_e32 v44, v54, v45
	v_pk_fma_f32 v[42:43], v[54:55], v[54:55], v[42:43]
	v_add_f32_e32 v45, v55, v44
	v_mul_f32_e32 v44, v55, v55
	v_pk_fma_f32 v[68:69], v[242:243], s[0:1], v[56:57] op_sel_hi:[1,0,1]
	v_pk_add_f32 v[42:43], v[44:45], v[42:43] op_sel_hi:[0,1]
	v_add_f32_e32 v44, v68, v45
	v_pk_fma_f32 v[42:43], v[68:69], v[68:69], v[42:43]
	v_add_f32_e32 v45, v69, v44
	v_mul_f32_e32 v44, v69, v69
	v_pk_fma_f32 v[50:51], v[232:233], s[0:1], v[58:59] op_sel_hi:[1,0,1]
	v_pk_add_f32 v[42:43], v[44:45], v[42:43] op_sel_hi:[0,1]
	v_add_f32_e32 v44, v50, v45
	v_pk_fma_f32 v[42:43], v[50:51], v[50:51], v[42:43]
	v_add_f32_e32 v45, v51, v44
	v_mul_f32_e32 v44, v51, v51
	v_pk_fma_f32 v[56:57], v[234:235], s[0:1], v[60:61] op_sel_hi:[1,0,1]
	v_pk_add_f32 v[42:43], v[44:45], v[42:43] op_sel_hi:[0,1]
	v_add_f32_e32 v44, v56, v45
	v_pk_fma_f32 v[42:43], v[56:57], v[56:57], v[42:43]
	v_add_f32_e32 v45, v57, v44
	v_mul_f32_e32 v44, v57, v57
	v_pk_fma_f32 v[48:49], v[82:83], s[0:1], v[62:63] op_sel_hi:[1,0,1]
	v_pk_add_f32 v[42:43], v[44:45], v[42:43] op_sel_hi:[0,1]
	v_add_f32_e32 v44, v48, v45
	v_pk_fma_f32 v[42:43], v[48:49], v[48:49], v[42:43]
	v_add_f32_e32 v45, v49, v44
	v_mul_f32_e32 v44, v49, v49
	v_pk_fma_f32 v[52:53], v[84:85], s[0:1], v[64:65] op_sel_hi:[1,0,1]
	v_pk_add_f32 v[42:43], v[44:45], v[42:43] op_sel_hi:[0,1]
	v_add_f32_e32 v44, v52, v45
	v_pk_fma_f32 v[42:43], v[52:53], v[52:53], v[42:43]
	v_add_f32_e32 v46, v53, v44
	v_mul_f32_e32 v44, v53, v53
	v_pk_add_f32 v[44:45], v[44:45], v[42:43] op_sel_hi:[0,1]
	s_waitcnt vmcnt(5)
	v_pk_fma_f32 v[42:43], v[38:39], s[0:1], v[18:19] op_sel_hi:[1,0,1]
	v_pk_fma_f32 v[26:27], v[244:245], s[0:1], v[26:27] op_sel_hi:[1,0,1]
	v_add_f32_e32 v38, v42, v46
	v_pk_fma_f32 v[18:19], v[42:43], v[42:43], v[44:45]
	v_add_f32_e32 v39, v43, v38
	v_mul_f32_e32 v38, v43, v43
	v_pk_fma_f32 v[46:47], v[40:41], s[0:1], v[20:21] op_sel_hi:[1,0,1]
	v_pk_add_f32 v[18:19], v[38:39], v[18:19] op_sel_hi:[0,1]
	v_add_f32_e32 v20, v46, v39
	v_pk_fma_f32 v[18:19], v[46:47], v[46:47], v[18:19]
	v_add_f32_e32 v21, v47, v20
	v_mul_f32_e32 v20, v47, v47
	s_waitcnt vmcnt(4)
; #define RL_LOAD(XV, G) { constexpr int mt__ = (G) >> 2, half__ = ((G) >> 1) & 1, nt__ = (G) & 1; \
;     _Pragma("unroll") for (int gq = 0; gq < 4; ++gq) XV[gq] = *(const f32x4*)(xin + rbase + (size_t)mt__ * 32 * 1024 + half__ * 64 + nt__ * 32 + 4 * gq); }
; #define RL_FOLD(XV, G, SM, SQ) { constexpr int mt__ = (G) >> 2, half__ = ((G) >> 1) & 1, nt__ = (G) & 1; \
;     _Pragma("unroll") for (int gq = 0; gq < 4; ++gq) _Pragma("unroll") for (int jj = 0; jj < 4; ++jj) { \
;       const float y = ALPHA * XV[gq][jj] + acc[half__][nt__][mt__][4 * gq + jj]; acc[half__][nt__][mt__][4 * gq + jj] = y; SM += y; SQ += y * y; } }
; #define SB __builtin_amdgcn_sched_barrier(0)
;   DI void full(const int mt_, const int nt_, f32x16 (&acc)[2][2][2], const int tw, const int fw, const int r, const int hh, char* lds, const int tid) const {
;     ...
;     float sm0 = 0.f, sq0 = 0.f, sm1 = 0.f, sq1 = 0.f;
;     RL_LOAD(xa, 0); RL_LOAD(xc, 1); RL_LOAD(xe, 2); SB;
;     RL_FOLD(xa, 0, sm0, sq0); SB; RL_LOAD(xa, 3); SB;
;     RL_FOLD(xc, 1, sm0, sq0); SB; RL_LOAD(xc, 4); SB;
;     RL_FOLD(xe, 2, sm0, sq0); SB; RL_LOAD(xe, 5); SB;
;     RL_FOLD(xa, 3, sm0, sq0); SB; RL_LOAD(xa, 6); SB;
;     RL_FOLD(xc, 4, sm1, sq1); SB; RL_LOAD(xc, 7); SB;
;     RL_FOLD(xe, 5, sm1, sq1); SB;
;     RL_FOLD(xa, 6, sm1, sq1); SB;
;     RL_FOLD(xc, 7, sm1, sq1);
;     ...
;     sm0 += __shfl_xor(sm0, 32, 64); sq0 += __shfl_xor(sq0, 32, 64); sm1 += __shfl_xor(sm1, 32, 64); sq1 += __shfl_xor(sq1, 32, 64);
;     if (hh == 0) {
;       float* pp = part + ((fw * 256) + tw * 64 + r) * 2; pp[0] = sm0; pp[1] = sq0;
;       pp[64] = sm1; pp[65] = sq1;
	v_pk_fma_f32 v[38:39], v[248:249], s[0:1], v[22:23] op_sel_hi:[1,0,1]
	v_pk_add_f32 v[18:19], v[20:21], v[18:19] op_sel_hi:[0,1]
	v_add_f32_e32 v20, v38, v21
	v_pk_fma_f32 v[18:19], v[38:39], v[38:39], v[18:19]
	v_add_f32_e32 v21, v39, v20
	v_mul_f32_e32 v20, v39, v39
	v_pk_fma_f32 v[44:45], v[250:251], s[0:1], v[24:25] op_sel_hi:[1,0,1]
	v_pk_add_f32 v[18:19], v[20:21], v[18:19] op_sel_hi:[0,1]
	v_add_f32_e32 v20, v44, v21
	v_pk_fma_f32 v[18:19], v[44:45], v[44:45], v[18:19]
	v_add_f32_e32 v21, v45, v20
	v_mul_f32_e32 v20, v45, v45
	v_pk_add_f32 v[18:19], v[20:21], v[18:19] op_sel_hi:[0,1]
	v_add_f32_e32 v20, v26, v21
	v_pk_fma_f32 v[18:19], v[26:27], v[26:27], v[18:19]
	v_add_f32_e32 v21, v27, v20
	v_mul_f32_e32 v20, v27, v27
	v_pk_fma_f32 v[40:41], v[246:247], s[0:1], v[28:29] op_sel_hi:[1,0,1]
	v_pk_add_f32 v[18:19], v[20:21], v[18:19] op_sel_hi:[0,1]
	v_add_f32_e32 v20, v40, v21
	v_pk_fma_f32 v[18:19], v[40:41], v[40:41], v[18:19]
	v_add_f32_e32 v21, v41, v20
	v_mul_f32_e32 v20, v41, v41
	v_pk_fma_f32 v[24:25], v[166:167], s[0:1], v[30:31] op_sel_hi:[1,0,1]
	v_pk_add_f32 v[18:19], v[20:21], v[18:19] op_sel_hi:[0,1]
	v_add_f32_e32 v20, v24, v21
	v_pk_fma_f32 v[18:19], v[24:25], v[24:25], v[18:19]
	v_add_f32_e32 v21, v25, v20
	v_mul_f32_e32 v20, v25, v25
	v_pk_fma_f32 v[28:29], v[168:169], s[0:1], v[32:33] op_sel_hi:[1,0,1]
	v_pk_add_f32 v[18:19], v[20:21], v[18:19] op_sel_hi:[0,1]
	v_add_f32_e32 v20, v28, v21
	v_pk_fma_f32 v[18:19], v[28:29], v[28:29], v[18:19]
	v_add_f32_e32 v22, v29, v20
	v_mul_f32_e32 v20, v29, v29
	v_pk_add_f32 v[20:21], v[20:21], v[18:19] op_sel_hi:[0,1]
	s_waitcnt vmcnt(1)
	v_pk_fma_f32 v[18:19], v[188:189], s[0:1], v[2:3] op_sel_hi:[1,0,1]
	s_waitcnt vmcnt(0)
	v_pk_fma_f32 v[6:7], v[194:195], s[0:1], v[6:7] op_sel_hi:[1,0,1]
	v_add_f32_e32 v22, v18, v22
	v_pk_fma_f32 v[2:3], v[18:19], v[18:19], v[20:21]
	v_add_f32_e32 v21, v19, v22
	v_pk_fma_f32 v[22:23], v[190:191], s[0:1], v[4:5] op_sel_hi:[1,0,1]
	v_mul_f32_e32 v20, v19, v19
	v_add_f32_e32 v4, v22, v21
	v_pk_add_f32 v[2:3], v[20:21], v[2:3] op_sel_hi:[0,1]
	v_add_f32_e32 v4, v23, v4
	v_pk_fma_f32 v[2:3], v[22:23], v[22:23], v[2:3]
	v_add_f32_e32 v21, v6, v4
	v_mul_f32_e32 v20, v23, v23
	v_mov_b32_e32 v4, v6
	v_mov_b32_e32 v5, v23
	v_pk_add_f32 v[2:3], v[20:21], v[2:3] op_sel_hi:[0,1]
	v_pk_fma_f32 v[2:3], v[4:5], v[4:5], v[2:3]
	v_add_f32_e32 v4, v7, v21
	v_pk_fma_f32 v[20:21], v[196:197], s[0:1], v[8:9] op_sel_hi:[1,0,1]
	v_mul_f32_e32 v8, v7, v7
	v_add_f32_e32 v9, v20, v4
	v_mov_b32_e32 v4, v20
	v_mov_b32_e32 v5, v7
	v_pk_add_f32 v[2:3], v[8:9], v[2:3] op_sel_hi:[0,1]
	v_pk_fma_f32 v[4:5], v[4:5], v[4:5], v[2:3]
	v_add_f32_e32 v8, v21, v9
	v_pk_fma_f32 v[2:3], v[98:99], s[0:1], v[10:11] op_sel_hi:[1,0,1]
	v_mul_f32_e32 v10, v21, v21
	v_add_f32_e32 v11, v2, v8
	v_mov_b32_e32 v8, v2
	v_mov_b32_e32 v9, v21
	v_pk_add_f32 v[4:5], v[10:11], v[4:5] op_sel_hi:[0,1]
	v_pk_fma_f32 v[4:5], v[8:9], v[8:9], v[4:5]
	v_add_f32_e32 v10, v3, v11
	v_pk_fma_f32 v[8:9], v[100:101], s[0:1], v[12:13] op_sel_hi:[1,0,1]
	v_mul_f32_e32 v12, v3, v3
	v_add_f32_e32 v13, v8, v10
	v_mov_b32_e32 v10, v8
	v_mov_b32_e32 v11, v3
	v_pk_add_f32 v[4:5], v[12:13], v[4:5] op_sel_hi:[0,1]
	v_pk_fma_f32 v[10:11], v[10:11], v[10:11], v[4:5]
	v_add_f32_e32 v12, v9, v13
	v_pk_fma_f32 v[4:5], v[34:35], s[0:1], v[14:15] op_sel_hi:[1,0,1]
	v_mul_f32_e32 v14, v9, v9
	v_add_f32_e32 v15, v4, v12
	v_mov_b32_e32 v12, v4
	v_mov_b32_e32 v13, v9
	v_pk_add_f32 v[10:11], v[14:15], v[10:11] op_sel_hi:[0,1]
	v_pk_fma_f32 v[12:13], v[12:13], v[12:13], v[10:11]
	v_pk_fma_f32 v[10:11], v[36:37], s[0:1], v[16:17] op_sel_hi:[1,0,1]
	v_mul_f32_e32 v30, v5, v5
	v_mov_b32_e32 v16, v10
	v_mov_b32_e32 v17, v5
	v_pk_add_f32 v[12:13], v[30:31], v[12:13] op_sel_hi:[0,1]
	v_pk_fma_f32 v[12:13], v[16:17], v[16:17], v[12:13]
	v_pk_mul_f32 v[16:17], v[10:11], v[10:11]
	v_add_f32_e32 v14, v5, v15
	v_mov_b32_e32 v15, v17
	v_and_b32_e32 v17, 64, v201
	v_xor_b32_e32 v16, 32, v201
	v_add_u32_e32 v17, 64, v17
	v_add_f32_e32 v14, v10, v14
	v_pk_mov_b32 v[12:13], v[10:11], v[12:13] op_sel:[1,0]
	v_cmp_lt_i32_e32 vcc, v16, v17
	v_pk_add_f32 v[12:13], v[12:13], v[14:15]
	v_pk_mov_b32 v[14:15], v[112:113], v[78:79] op_sel:[1,0]
	v_cndmask_b32_e32 v16, v201, v16, vcc
	v_pk_add_f32 v[14:15], v[14:15], v[114:115]
	v_lshlrev_b32_e32 v31, 2, v16
	ds_bpermute_b32 v16, v31, v14
	ds_bpermute_b32 v17, v31, v15
	ds_bpermute_b32 v30, v31, v12
	ds_bpermute_b32 v31, v31, v13
	v_cmp_eq_u32_e32 vcc, 0, v226
	s_and_saveexec_b64 s[4:5], vcc
	s_cbranch_execz .LBB0_772
	v_lshlrev_b32_e32 v32, 3, v186
	v_and_b32_e32 v32, 0xfffffef8, v32
	v_add_u32_e32 v32, 0, v32
	v_add_u32_e32 v32, 0x12000, v32
	s_waitcnt lgkmcnt(2)
	v_pk_add_f32 v[14:15], v[14:15], v[16:17]
	s_waitcnt lgkmcnt(0)
	v_pk_add_f32 v[12:13], v[12:13], v[30:31]
	ds_write2_b64 v32, v[14:15], v[12:13] offset1:32
